# GEMM K-loops second pass: the remaining strided loads use a scalar-computed base; no 64-bit VALU adds left in the K-loops
# speedup vs baseline: 1.0329x; 1.0040x over previous
.LBB0_359:
	ds_read_b128 v[130:133], v185
	ds_read_b128 v[134:137], v185 offset:1024
	ds_read_b128 v[138:141], v185 offset:2048
	ds_read_b128 v[142:145], v185 offset:3072
	ds_read_b128 v[146:149], v187
	ds_read_b128 v[150:153], v187 offset:1024
	ds_read_b128 v[154:157], v187 offset:2048
	ds_read_b128 v[192:195], v187 offset:3072
	s_add_u32 s30, s28, 0xfff80080
	s_addc_u32 s31, s29, -1
	s_cmp_eq_u32 s76, 28
	s_cselect_b32 s35, s6, s31
	s_cselect_b32 s34, s21, s30
	s_cselect_b32 s31, s19, s75
	s_cselect_b32 s30, s73, s74
	s_add_i32 m0, s27, 0xc000
	ds_read_b128 v[196:199], v189
	ds_read_b128 v[200:203], v189 offset:1024
	ds_read_b128 v[204:207], v189 offset:2048
	ds_read_b128 v[208:211], v189 offset:3072
	ds_read_b128 v[212:215], v189 offset:4096
	ds_read_b128 v[216:219], v189 offset:5120
	ds_read_b128 v[220:223], v189 offset:6144
	ds_read_b128 v[224:227], v189 offset:7168
	global_load_lds_dwordx4 v174, s[28:29]
	s_add_i32 m0, s27, 0xe000
	s_nop 0
	global_load_lds_dwordx4 v172, s[28:29]
	s_waitcnt vmcnt(8)
	s_waitcnt lgkmcnt(0)
	s_barrier
	s_setprio 1
	s_waitcnt lgkmcnt(0)
	v_mfma_f32_16x16x32_bf16 v[124:127], v[130:133], v[196:199], v[124:127]
	v_mfma_f32_16x16x32_bf16 v[120:123], v[138:141], v[196:199], v[120:123]
	v_mfma_f32_16x16x32_bf16 v[112:115], v[130:133], v[204:207], v[112:115]
	v_mfma_f32_16x16x32_bf16 v[104:107], v[138:141], v[204:207], v[104:107]
	v_mfma_f32_16x16x32_bf16 v[96:99], v[130:133], v[212:215], v[96:99]
	v_mfma_f32_16x16x32_bf16 v[88:91], v[138:141], v[212:215], v[88:91]
	v_mfma_f32_16x16x32_bf16 v[80:83], v[130:133], v[220:223], v[80:83]
	v_mfma_f32_16x16x32_bf16 v[72:75], v[138:141], v[220:223], v[72:75]
	v_mfma_f32_16x16x32_bf16 v[124:127], v[134:137], v[200:203], v[124:127]
	v_mfma_f32_16x16x32_bf16 v[120:123], v[142:145], v[200:203], v[120:123]
	v_mfma_f32_16x16x32_bf16 v[112:115], v[134:137], v[208:211], v[112:115]
	v_mfma_f32_16x16x32_bf16 v[104:107], v[142:145], v[208:211], v[104:107]
	v_mfma_f32_16x16x32_bf16 v[96:99], v[134:137], v[216:219], v[96:99]
	v_mfma_f32_16x16x32_bf16 v[88:91], v[142:145], v[216:219], v[88:91]
	v_mfma_f32_16x16x32_bf16 v[80:83], v[134:137], v[224:227], v[80:83]
	v_mfma_f32_16x16x32_bf16 v[72:75], v[142:145], v[224:227], v[72:75]
	s_setprio 0
	s_setprio 1
	v_mfma_f32_16x16x32_bf16 v[116:119], v[146:149], v[196:199], v[116:119]
	v_mfma_f32_16x16x32_bf16 v[108:111], v[154:157], v[196:199], v[108:111]
	v_mfma_f32_16x16x32_bf16 v[100:103], v[146:149], v[204:207], v[100:103]
	v_mfma_f32_16x16x32_bf16 v[92:95], v[154:157], v[204:207], v[92:95]
	v_mfma_f32_16x16x32_bf16 v[84:87], v[146:149], v[212:215], v[84:87]
	v_mfma_f32_16x16x32_bf16 v[76:79], v[154:157], v[212:215], v[76:79]
	v_mfma_f32_16x16x32_bf16 v[68:71], v[146:149], v[220:223], v[68:71]
	v_mfma_f32_16x16x32_bf16 v[64:67], v[154:157], v[220:223], v[64:67]
	v_mfma_f32_16x16x32_bf16 v[116:119], v[150:153], v[200:203], v[116:119]
	v_mfma_f32_16x16x32_bf16 v[108:111], v[192:195], v[200:203], v[108:111]
	v_mfma_f32_16x16x32_bf16 v[100:103], v[150:153], v[208:211], v[100:103]
	v_mfma_f32_16x16x32_bf16 v[92:95], v[192:195], v[208:211], v[92:95]
	s_barrier
	s_setprio 2
	v_mfma_f32_16x16x32_bf16 v[84:87], v[150:153], v[216:219], v[84:87]
	v_mfma_f32_16x16x32_bf16 v[76:79], v[192:195], v[216:219], v[76:79]
	v_mfma_f32_16x16x32_bf16 v[68:71], v[150:153], v[224:227], v[68:71]
	v_mfma_f32_16x16x32_bf16 v[64:67], v[192:195], v[224:227], v[64:67]
	s_setprio 0
	s_add_i32 s77, s57, s67
	s_add_u32 s82, s30, s12
	s_addc_u32 s83, s31, s13
	s_mov_b32 m0, s77
	ds_read_b128 v[196:199], v189 offset:16384
	ds_read_b128 v[200:203], v189 offset:17408
	ds_read_b128 v[204:207], v189 offset:18432
	ds_read_b128 v[208:211], v189 offset:19456
	ds_read_b128 v[212:215], v189 offset:20480
	ds_read_b128 v[216:219], v189 offset:21504
	ds_read_b128 v[220:223], v189 offset:22528
	ds_read_b128 v[224:227], v189 offset:23552
	global_load_lds_dwordx4 v162, s[30:31]
	s_add_i32 m0, s77, 0x2000
	s_add_u32 s78, s30, 0x80000
	s_addc_u32 s79, s31, 0
	s_add_i32 s77, s58, s67
	global_load_lds_dwordx4 v166, s[30:31]
	s_mov_b32 m0, s77
	s_add_u32 s84, s34, s12
	s_addc_u32 s85, s35, s13
	global_load_lds_dwordx4 v162, s[78:79]
	s_add_i32 m0, s77, 0x2000
	s_nop 0
	global_load_lds_dwordx4 v166, s[78:79]
	s_mov_b32 m0, s27
	s_nop 0
	global_load_lds_dwordx4 v160, s[34:35]
	s_mov_b32 m0, s41
	s_nop 0
	global_load_lds_dwordx4 v164, s[34:35]
	s_waitcnt vmcnt(8)
	s_waitcnt lgkmcnt(0)
	s_barrier
	s_setprio 1
	s_waitcnt lgkmcnt(0)
	v_mfma_f32_16x16x32_bf16 v[60:63], v[130:133], v[196:199], v[60:63]
	v_mfma_f32_16x16x32_bf16 v[56:59], v[138:141], v[196:199], v[56:59]
	v_mfma_f32_16x16x32_bf16 v[48:51], v[130:133], v[204:207], v[48:51]
	v_mfma_f32_16x16x32_bf16 v[40:43], v[138:141], v[204:207], v[40:43]
	v_mfma_f32_16x16x32_bf16 v[32:35], v[130:133], v[212:215], v[32:35]
	v_mfma_f32_16x16x32_bf16 v[24:27], v[138:141], v[212:215], v[24:27]
	v_mfma_f32_16x16x32_bf16 v[16:19], v[130:133], v[220:223], v[16:19]
	v_mfma_f32_16x16x32_bf16 v[8:11], v[138:141], v[220:223], v[8:11]
	v_mfma_f32_16x16x32_bf16 v[60:63], v[134:137], v[200:203], v[60:63]
	v_mfma_f32_16x16x32_bf16 v[56:59], v[142:145], v[200:203], v[56:59]
	v_mfma_f32_16x16x32_bf16 v[48:51], v[134:137], v[208:211], v[48:51]
	v_mfma_f32_16x16x32_bf16 v[40:43], v[142:145], v[208:211], v[40:43]
	v_mfma_f32_16x16x32_bf16 v[32:35], v[134:137], v[216:219], v[32:35]
	v_mfma_f32_16x16x32_bf16 v[24:27], v[142:145], v[216:219], v[24:27]
	v_mfma_f32_16x16x32_bf16 v[16:19], v[134:137], v[224:227], v[16:19]
	v_mfma_f32_16x16x32_bf16 v[8:11], v[142:145], v[224:227], v[8:11]
	s_setprio 0
	s_setprio 1
	v_mfma_f32_16x16x32_bf16 v[52:55], v[146:149], v[196:199], v[52:55]
	v_mfma_f32_16x16x32_bf16 v[44:47], v[154:157], v[196:199], v[44:47]
	v_mfma_f32_16x16x32_bf16 v[36:39], v[146:149], v[204:207], v[36:39]
	v_mfma_f32_16x16x32_bf16 v[28:31], v[154:157], v[204:207], v[28:31]
	v_mfma_f32_16x16x32_bf16 v[20:23], v[146:149], v[212:215], v[20:23]
	v_mfma_f32_16x16x32_bf16 v[12:15], v[154:157], v[212:215], v[12:15]
	v_mfma_f32_16x16x32_bf16 v[4:7], v[146:149], v[220:223], v[4:7]
	v_mfma_f32_16x16x32_bf16 v[0:3], v[154:157], v[220:223], v[0:3]
	v_mfma_f32_16x16x32_bf16 v[52:55], v[150:153], v[200:203], v[52:55]
	v_mfma_f32_16x16x32_bf16 v[44:47], v[192:195], v[200:203], v[44:47]
	v_mfma_f32_16x16x32_bf16 v[36:39], v[150:153], v[208:211], v[36:39]
	v_mfma_f32_16x16x32_bf16 v[28:31], v[192:195], v[208:211], v[28:31]
	s_barrier
	s_setprio 2
	v_mfma_f32_16x16x32_bf16 v[20:23], v[150:153], v[216:219], v[20:23]
	v_mfma_f32_16x16x32_bf16 v[12:15], v[192:195], v[216:219], v[12:15]
	v_mfma_f32_16x16x32_bf16 v[4:7], v[150:153], v[224:227], v[4:7]
	v_mfma_f32_16x16x32_bf16 v[0:3], v[192:195], v[224:227], v[0:3]
	s_setprio 0
	s_add_i32 s77, 0, 0x18000
	v_add_u32_e32 v129, s77, v181
	s_add_i32 s78, 0, 0x1c000
	ds_read_b128 v[130:133], v129
	ds_read_b128 v[134:137], v129 offset:1024
	ds_read_b128 v[138:141], v129 offset:2048
	ds_read_b128 v[142:145], v129 offset:3072
	v_add_u32_e32 v129, s78, v181
	ds_read_b128 v[146:149], v129
	ds_read_b128 v[150:153], v129 offset:1024
	ds_read_b128 v[154:157], v129 offset:2048
	ds_read_b128 v[192:195], v129 offset:3072
	s_add_u32 s34, s34, 0x80000
	s_addc_u32 s35, s35, 0
	s_mov_b32 m0, s42
	ds_read_b128 v[196:199], v189 offset:32768
	ds_read_b128 v[200:203], v189 offset:33792
	ds_read_b128 v[204:207], v189 offset:34816
	ds_read_b128 v[208:211], v189 offset:35840
	ds_read_b128 v[212:215], v189 offset:36864
	ds_read_b128 v[216:219], v189 offset:37888
	ds_read_b128 v[220:223], v189 offset:38912
	ds_read_b128 v[224:227], v189 offset:39936
	global_load_lds_dwordx4 v160, s[34:35]
	s_mov_b32 m0, s43
	s_nop 0
	global_load_lds_dwordx4 v164, s[34:35]
	s_waitcnt vmcnt(8)
	s_waitcnt lgkmcnt(0)
	s_barrier
	s_setprio 1
	s_waitcnt lgkmcnt(0)
	v_mfma_f32_16x16x32_bf16 v[124:127], v[130:133], v[196:199], v[124:127]
	v_mfma_f32_16x16x32_bf16 v[120:123], v[138:141], v[196:199], v[120:123]
	v_mfma_f32_16x16x32_bf16 v[112:115], v[130:133], v[204:207], v[112:115]
	v_mfma_f32_16x16x32_bf16 v[104:107], v[138:141], v[204:207], v[104:107]
	v_mfma_f32_16x16x32_bf16 v[96:99], v[130:133], v[212:215], v[96:99]
	v_mfma_f32_16x16x32_bf16 v[88:91], v[138:141], v[212:215], v[88:91]
	v_mfma_f32_16x16x32_bf16 v[80:83], v[130:133], v[220:223], v[80:83]
	v_mfma_f32_16x16x32_bf16 v[72:75], v[138:141], v[220:223], v[72:75]
	v_mfma_f32_16x16x32_bf16 v[124:127], v[134:137], v[200:203], v[124:127]
	v_mfma_f32_16x16x32_bf16 v[120:123], v[142:145], v[200:203], v[120:123]
	v_mfma_f32_16x16x32_bf16 v[112:115], v[134:137], v[208:211], v[112:115]
	v_mfma_f32_16x16x32_bf16 v[104:107], v[142:145], v[208:211], v[104:107]
	v_mfma_f32_16x16x32_bf16 v[96:99], v[134:137], v[216:219], v[96:99]
	v_mfma_f32_16x16x32_bf16 v[88:91], v[142:145], v[216:219], v[88:91]
	v_mfma_f32_16x16x32_bf16 v[80:83], v[134:137], v[224:227], v[80:83]
	v_mfma_f32_16x16x32_bf16 v[72:75], v[142:145], v[224:227], v[72:75]
	s_setprio 0
	s_setprio 1
	v_mfma_f32_16x16x32_bf16 v[116:119], v[146:149], v[196:199], v[116:119]
	v_mfma_f32_16x16x32_bf16 v[108:111], v[154:157], v[196:199], v[108:111]
	v_mfma_f32_16x16x32_bf16 v[100:103], v[146:149], v[204:207], v[100:103]
	v_mfma_f32_16x16x32_bf16 v[92:95], v[154:157], v[204:207], v[92:95]
	v_mfma_f32_16x16x32_bf16 v[84:87], v[146:149], v[212:215], v[84:87]
	v_mfma_f32_16x16x32_bf16 v[76:79], v[154:157], v[212:215], v[76:79]
	v_mfma_f32_16x16x32_bf16 v[68:71], v[146:149], v[220:223], v[68:71]
	v_mfma_f32_16x16x32_bf16 v[64:67], v[154:157], v[220:223], v[64:67]
	v_mfma_f32_16x16x32_bf16 v[116:119], v[150:153], v[200:203], v[116:119]
	v_mfma_f32_16x16x32_bf16 v[108:111], v[192:195], v[200:203], v[108:111]
	v_mfma_f32_16x16x32_bf16 v[100:103], v[150:153], v[208:211], v[100:103]
	v_mfma_f32_16x16x32_bf16 v[92:95], v[192:195], v[208:211], v[92:95]
	s_barrier
	s_setprio 2
	v_mfma_f32_16x16x32_bf16 v[84:87], v[150:153], v[216:219], v[84:87]
	v_mfma_f32_16x16x32_bf16 v[76:79], v[192:195], v[216:219], v[76:79]
	v_mfma_f32_16x16x32_bf16 v[68:71], v[150:153], v[224:227], v[68:71]
	v_mfma_f32_16x16x32_bf16 v[64:67], v[192:195], v[224:227], v[64:67]
	s_setprio 0
	s_add_i32 s34, s77, s67
	s_mov_b32 m0, s34
	ds_read_b128 v[196:199], v189 offset:49152
	ds_read_b128 v[200:203], v189 offset:50176
	ds_read_b128 v[204:207], v189 offset:51200
	ds_read_b128 v[208:211], v189 offset:52224
	ds_read_b128 v[212:215], v189 offset:53248
	ds_read_b128 v[216:219], v189 offset:54272
	ds_read_b128 v[220:223], v189 offset:55296
	ds_read_b128 v[224:227], v189 offset:56320
	global_load_lds_dwordx4 v162, s[82:83]
	s_add_i32 m0, s34, 0x2000
	s_add_u32 s30, s30, 0x80080
	s_addc_u32 s31, s31, 0
	s_add_i32 s34, s78, s67
	global_load_lds_dwordx4 v166, s[82:83]
	s_mov_b32 m0, s34
	s_nop 0
	global_load_lds_dwordx4 v162, s[30:31]
	s_add_i32 m0, s34, 0x2000
	s_nop 0
	global_load_lds_dwordx4 v166, s[30:31]
	s_mov_b32 m0, s45
	s_nop 0
	global_load_lds_dwordx4 v160, s[84:85]
	s_mov_b32 m0, s47
	s_nop 0
	global_load_lds_dwordx4 v164, s[84:85]
	s_waitcnt vmcnt(8)
	s_waitcnt lgkmcnt(0)
	s_barrier
	s_setprio 1
	s_waitcnt lgkmcnt(0)
	v_mfma_f32_16x16x32_bf16 v[60:63], v[130:133], v[196:199], v[60:63]
	v_mfma_f32_16x16x32_bf16 v[56:59], v[138:141], v[196:199], v[56:59]
	v_mfma_f32_16x16x32_bf16 v[48:51], v[130:133], v[204:207], v[48:51]
	v_mfma_f32_16x16x32_bf16 v[40:43], v[138:141], v[204:207], v[40:43]
	v_mfma_f32_16x16x32_bf16 v[32:35], v[130:133], v[212:215], v[32:35]
	v_mfma_f32_16x16x32_bf16 v[24:27], v[138:141], v[212:215], v[24:27]
	v_mfma_f32_16x16x32_bf16 v[16:19], v[130:133], v[220:223], v[16:19]
	v_mfma_f32_16x16x32_bf16 v[8:11], v[138:141], v[220:223], v[8:11]
	v_mfma_f32_16x16x32_bf16 v[60:63], v[134:137], v[200:203], v[60:63]
	v_mfma_f32_16x16x32_bf16 v[56:59], v[142:145], v[200:203], v[56:59]
	v_mfma_f32_16x16x32_bf16 v[48:51], v[134:137], v[208:211], v[48:51]
	v_mfma_f32_16x16x32_bf16 v[40:43], v[142:145], v[208:211], v[40:43]
	v_mfma_f32_16x16x32_bf16 v[32:35], v[134:137], v[216:219], v[32:35]
	v_mfma_f32_16x16x32_bf16 v[24:27], v[142:145], v[216:219], v[24:27]
	v_mfma_f32_16x16x32_bf16 v[16:19], v[134:137], v[224:227], v[16:19]
	v_mfma_f32_16x16x32_bf16 v[8:11], v[142:145], v[224:227], v[8:11]
	s_setprio 0
	s_setprio 1
	v_mfma_f32_16x16x32_bf16 v[52:55], v[146:149], v[196:199], v[52:55]
	v_mfma_f32_16x16x32_bf16 v[44:47], v[154:157], v[196:199], v[44:47]
	v_mfma_f32_16x16x32_bf16 v[36:39], v[146:149], v[204:207], v[36:39]
	v_mfma_f32_16x16x32_bf16 v[28:31], v[154:157], v[204:207], v[28:31]
	v_mfma_f32_16x16x32_bf16 v[20:23], v[146:149], v[212:215], v[20:23]
	v_mfma_f32_16x16x32_bf16 v[12:15], v[154:157], v[212:215], v[12:15]
	v_mfma_f32_16x16x32_bf16 v[4:7], v[146:149], v[220:223], v[4:7]
	v_mfma_f32_16x16x32_bf16 v[0:3], v[154:157], v[220:223], v[0:3]
	v_mfma_f32_16x16x32_bf16 v[52:55], v[150:153], v[200:203], v[52:55]
	v_mfma_f32_16x16x32_bf16 v[44:47], v[192:195], v[200:203], v[44:47]
	v_mfma_f32_16x16x32_bf16 v[36:39], v[150:153], v[208:211], v[36:39]
	v_mfma_f32_16x16x32_bf16 v[28:31], v[192:195], v[208:211], v[28:31]
	s_barrier
	s_setprio 2
	v_mfma_f32_16x16x32_bf16 v[20:23], v[150:153], v[216:219], v[20:23]
	v_mfma_f32_16x16x32_bf16 v[12:15], v[192:195], v[216:219], v[12:15]
	v_mfma_f32_16x16x32_bf16 v[4:7], v[150:153], v[224:227], v[4:7]
	v_mfma_f32_16x16x32_bf16 v[0:3], v[192:195], v[224:227], v[0:3]
	s_setprio 0
	s_add_i32 s76, s76, 2
	s_add_u32 s74, s74, 0x100
	s_addc_u32 s75, s75, 0
	s_add_u32 s28, s28, 0x100
	s_addc_u32 s29, s29, 0
	s_cmp_gt_u32 s76, 29
	s_cbranch_scc0 .LBB0_359
	s_and_b64 vcc, exec, s[14:15]
	s_cbranch_vccz .LBB0_362
	s_barrier

.LBB0_1192:
	ds_read_b128 v[128:131], v215
	ds_read_b128 v[132:135], v215 offset:1024
	ds_read_b128 v[136:139], v215 offset:2048
	ds_read_b128 v[158:161], v215 offset:3072
	ds_read_b128 v[162:165], v216
	ds_read_b128 v[166:169], v216 offset:1024
	ds_read_b128 v[170:173], v216 offset:2048
	ds_read_b128 v[174:177], v216 offset:3072
	s_add_u32 s24, s22, 0xfff80080
	s_addc_u32 s25, s23, -1
	s_cmp_eq_u32 s30, 28
	s_cselect_b32 s27, s3, s25
	s_cselect_b32 s26, s15, s24
	s_cselect_b32 s25, s13, s29
	s_cselect_b32 s24, s21, s28
	s_add_i32 m0, s38, 0xc000
	ds_read_b128 v[178:181], v217
	ds_read_b128 v[182:185], v217 offset:1024
	ds_read_b128 v[186:189], v217 offset:2048
	ds_read_b128 v[190:193], v217 offset:3072
	ds_read_b128 v[194:197], v217 offset:4096
	ds_read_b128 v[198:201], v217 offset:5120
	ds_read_b128 v[202:205], v217 offset:6144
	ds_read_b128 v[206:209], v217 offset:7168
	global_load_lds_dwordx4 v152, s[22:23]
	s_add_i32 m0, s38, 0xe000
	s_nop 0
	global_load_lds_dwordx4 v150, s[22:23]
	s_waitcnt vmcnt(8)
	s_waitcnt lgkmcnt(0)
	s_barrier
	s_setprio 1
	s_waitcnt lgkmcnt(0)
	v_mfma_f32_16x16x32_bf16 v[124:127], v[128:131], v[178:181], v[124:127]
	v_mfma_f32_16x16x32_bf16 v[120:123], v[136:139], v[178:181], v[120:123]
	v_mfma_f32_16x16x32_bf16 v[116:119], v[128:131], v[186:189], v[116:119]
	v_mfma_f32_16x16x32_bf16 v[112:115], v[136:139], v[186:189], v[112:115]
	v_mfma_f32_16x16x32_bf16 v[108:111], v[128:131], v[194:197], v[108:111]
	v_mfma_f32_16x16x32_bf16 v[104:107], v[136:139], v[194:197], v[104:107]
	v_mfma_f32_16x16x32_bf16 v[100:103], v[128:131], v[202:205], v[100:103]
	v_mfma_f32_16x16x32_bf16 v[96:99], v[136:139], v[202:205], v[96:99]
	v_mfma_f32_16x16x32_bf16 v[124:127], v[132:135], v[182:185], v[124:127]
	v_mfma_f32_16x16x32_bf16 v[120:123], v[158:161], v[182:185], v[120:123]
	v_mfma_f32_16x16x32_bf16 v[116:119], v[132:135], v[190:193], v[116:119]
	v_mfma_f32_16x16x32_bf16 v[112:115], v[158:161], v[190:193], v[112:115]
	v_mfma_f32_16x16x32_bf16 v[108:111], v[132:135], v[198:201], v[108:111]
	v_mfma_f32_16x16x32_bf16 v[104:107], v[158:161], v[198:201], v[104:107]
	v_mfma_f32_16x16x32_bf16 v[100:103], v[132:135], v[206:209], v[100:103]
	v_mfma_f32_16x16x32_bf16 v[96:99], v[158:161], v[206:209], v[96:99]
	s_setprio 0
	s_setprio 1
	v_mfma_f32_16x16x32_bf16 v[60:63], v[162:165], v[178:181], v[60:63]
	v_mfma_f32_16x16x32_bf16 v[56:59], v[170:173], v[178:181], v[56:59]
	v_mfma_f32_16x16x32_bf16 v[52:55], v[162:165], v[186:189], v[52:55]
	v_mfma_f32_16x16x32_bf16 v[48:51], v[170:173], v[186:189], v[48:51]
	v_mfma_f32_16x16x32_bf16 v[44:47], v[162:165], v[194:197], v[44:47]
	v_mfma_f32_16x16x32_bf16 v[40:43], v[170:173], v[194:197], v[40:43]
	v_mfma_f32_16x16x32_bf16 v[36:39], v[162:165], v[202:205], v[36:39]
	v_mfma_f32_16x16x32_bf16 v[32:35], v[170:173], v[202:205], v[32:35]
	v_mfma_f32_16x16x32_bf16 v[60:63], v[166:169], v[182:185], v[60:63]
	v_mfma_f32_16x16x32_bf16 v[56:59], v[174:177], v[182:185], v[56:59]
	v_mfma_f32_16x16x32_bf16 v[52:55], v[166:169], v[190:193], v[52:55]
	v_mfma_f32_16x16x32_bf16 v[48:51], v[174:177], v[190:193], v[48:51]
	s_barrier
	s_setprio 2
	v_mfma_f32_16x16x32_bf16 v[44:47], v[166:169], v[198:201], v[44:47]
	v_mfma_f32_16x16x32_bf16 v[40:43], v[174:177], v[198:201], v[40:43]
	v_mfma_f32_16x16x32_bf16 v[36:39], v[166:169], v[206:209], v[36:39]
	v_mfma_f32_16x16x32_bf16 v[32:35], v[174:177], v[206:209], v[32:35]
	s_setprio 0
	s_add_i32 s31, s60, s67
	s_add_u32 s76, s24, s6
	s_addc_u32 s77, s25, s7
	s_mov_b32 m0, s31
	ds_read_b128 v[178:181], v217 offset:16384
	ds_read_b128 v[182:185], v217 offset:17408
	ds_read_b128 v[186:189], v217 offset:18432
	ds_read_b128 v[190:193], v217 offset:19456
	ds_read_b128 v[194:197], v217 offset:20480
	ds_read_b128 v[198:201], v217 offset:21504
	ds_read_b128 v[202:205], v217 offset:22528
	ds_read_b128 v[206:209], v217 offset:23552
	global_load_lds_dwordx4 v142, s[24:25]
	s_add_i32 m0, s31, 0x2000
	s_add_u32 s74, s24, 0x80000
	s_addc_u32 s75, s25, 0
	s_add_i32 s31, s61, s67
	global_load_lds_dwordx4 v146, s[24:25]
	s_mov_b32 m0, s31
	s_add_u32 s78, s26, s6
	s_addc_u32 s79, s27, s7
	global_load_lds_dwordx4 v142, s[74:75]
	s_add_i32 m0, s31, 0x2000
	s_nop 0
	global_load_lds_dwordx4 v146, s[74:75]
	s_mov_b32 m0, s38
	s_nop 0
	global_load_lds_dwordx4 v140, s[26:27]
	s_mov_b32 m0, s39
	s_nop 0
	global_load_lds_dwordx4 v144, s[26:27]
	s_waitcnt vmcnt(8)
	s_waitcnt lgkmcnt(0)
	s_barrier
	s_setprio 1
	s_waitcnt lgkmcnt(0)
	v_mfma_f32_16x16x32_bf16 v[92:95], v[128:131], v[178:181], v[92:95]
	v_mfma_f32_16x16x32_bf16 v[88:91], v[136:139], v[178:181], v[88:91]
	v_mfma_f32_16x16x32_bf16 v[84:87], v[128:131], v[186:189], v[84:87]
	v_mfma_f32_16x16x32_bf16 v[80:83], v[136:139], v[186:189], v[80:83]
	v_mfma_f32_16x16x32_bf16 v[76:79], v[128:131], v[194:197], v[76:79]
	v_mfma_f32_16x16x32_bf16 v[72:75], v[136:139], v[194:197], v[72:75]
	v_mfma_f32_16x16x32_bf16 v[68:71], v[128:131], v[202:205], v[68:71]
	v_mfma_f32_16x16x32_bf16 v[64:67], v[136:139], v[202:205], v[64:67]
	v_mfma_f32_16x16x32_bf16 v[92:95], v[132:135], v[182:185], v[92:95]
	v_mfma_f32_16x16x32_bf16 v[88:91], v[158:161], v[182:185], v[88:91]
	v_mfma_f32_16x16x32_bf16 v[84:87], v[132:135], v[190:193], v[84:87]
	v_mfma_f32_16x16x32_bf16 v[80:83], v[158:161], v[190:193], v[80:83]
	v_mfma_f32_16x16x32_bf16 v[76:79], v[132:135], v[198:201], v[76:79]
	v_mfma_f32_16x16x32_bf16 v[72:75], v[158:161], v[198:201], v[72:75]
	v_mfma_f32_16x16x32_bf16 v[68:71], v[132:135], v[206:209], v[68:71]
	v_mfma_f32_16x16x32_bf16 v[64:67], v[158:161], v[206:209], v[64:67]
	s_setprio 0
	s_setprio 1
	v_mfma_f32_16x16x32_bf16 v[28:31], v[162:165], v[178:181], v[28:31]
	v_mfma_f32_16x16x32_bf16 v[24:27], v[170:173], v[178:181], v[24:27]
	v_mfma_f32_16x16x32_bf16 v[20:23], v[162:165], v[186:189], v[20:23]
	v_mfma_f32_16x16x32_bf16 v[16:19], v[170:173], v[186:189], v[16:19]
	v_mfma_f32_16x16x32_bf16 v[12:15], v[162:165], v[194:197], v[12:15]
	v_mfma_f32_16x16x32_bf16 v[8:11], v[170:173], v[194:197], v[8:11]
	v_mfma_f32_16x16x32_bf16 v[4:7], v[162:165], v[202:205], v[4:7]
	v_mfma_f32_16x16x32_bf16 v[0:3], v[170:173], v[202:205], v[0:3]
	v_mfma_f32_16x16x32_bf16 v[28:31], v[166:169], v[182:185], v[28:31]
	v_mfma_f32_16x16x32_bf16 v[24:27], v[174:177], v[182:185], v[24:27]
	v_mfma_f32_16x16x32_bf16 v[20:23], v[166:169], v[190:193], v[20:23]
	v_mfma_f32_16x16x32_bf16 v[16:19], v[174:177], v[190:193], v[16:19]
	s_barrier
	s_setprio 2
	v_mfma_f32_16x16x32_bf16 v[12:15], v[166:169], v[198:201], v[12:15]
	v_mfma_f32_16x16x32_bf16 v[8:11], v[174:177], v[198:201], v[8:11]
	v_mfma_f32_16x16x32_bf16 v[4:7], v[166:169], v[206:209], v[4:7]
	v_mfma_f32_16x16x32_bf16 v[0:3], v[174:177], v[206:209], v[0:3]
	s_setprio 0
	s_add_i32 s31, 0, 0x18000
	v_add_u32_e32 v148, s31, v214
	s_add_i32 s74, 0, 0x1c000
	ds_read_b128 v[128:131], v148
	ds_read_b128 v[132:135], v148 offset:1024
	ds_read_b128 v[136:139], v148 offset:2048
	ds_read_b128 v[158:161], v148 offset:3072
	v_add_u32_e32 v148, s74, v214
	ds_read_b128 v[162:165], v148
	ds_read_b128 v[166:169], v148 offset:1024
	ds_read_b128 v[170:173], v148 offset:2048
	ds_read_b128 v[174:177], v148 offset:3072
	s_add_u32 s26, s26, 0x80000
	s_addc_u32 s27, s27, 0
	s_mov_b32 m0, s40
	ds_read_b128 v[178:181], v217 offset:32768
	ds_read_b128 v[182:185], v217 offset:33792
	ds_read_b128 v[186:189], v217 offset:34816
	ds_read_b128 v[190:193], v217 offset:35840
	ds_read_b128 v[194:197], v217 offset:36864
	ds_read_b128 v[198:201], v217 offset:37888
	ds_read_b128 v[202:205], v217 offset:38912
	ds_read_b128 v[206:209], v217 offset:39936
	global_load_lds_dwordx4 v140, s[26:27]
	s_mov_b32 m0, s41
	s_nop 0
	global_load_lds_dwordx4 v144, s[26:27]
	s_waitcnt vmcnt(8)
	s_waitcnt lgkmcnt(0)
	s_barrier
	s_setprio 1
	s_waitcnt lgkmcnt(0)
	v_mfma_f32_16x16x32_bf16 v[124:127], v[128:131], v[178:181], v[124:127]
	v_mfma_f32_16x16x32_bf16 v[120:123], v[136:139], v[178:181], v[120:123]
	v_mfma_f32_16x16x32_bf16 v[116:119], v[128:131], v[186:189], v[116:119]
	v_mfma_f32_16x16x32_bf16 v[112:115], v[136:139], v[186:189], v[112:115]
	v_mfma_f32_16x16x32_bf16 v[108:111], v[128:131], v[194:197], v[108:111]
	v_mfma_f32_16x16x32_bf16 v[104:107], v[136:139], v[194:197], v[104:107]
	v_mfma_f32_16x16x32_bf16 v[100:103], v[128:131], v[202:205], v[100:103]
	v_mfma_f32_16x16x32_bf16 v[96:99], v[136:139], v[202:205], v[96:99]
	v_mfma_f32_16x16x32_bf16 v[124:127], v[132:135], v[182:185], v[124:127]
	v_mfma_f32_16x16x32_bf16 v[120:123], v[158:161], v[182:185], v[120:123]
	v_mfma_f32_16x16x32_bf16 v[116:119], v[132:135], v[190:193], v[116:119]
	v_mfma_f32_16x16x32_bf16 v[112:115], v[158:161], v[190:193], v[112:115]
	v_mfma_f32_16x16x32_bf16 v[108:111], v[132:135], v[198:201], v[108:111]
	v_mfma_f32_16x16x32_bf16 v[104:107], v[158:161], v[198:201], v[104:107]
	v_mfma_f32_16x16x32_bf16 v[100:103], v[132:135], v[206:209], v[100:103]
	v_mfma_f32_16x16x32_bf16 v[96:99], v[158:161], v[206:209], v[96:99]
	s_setprio 0
	s_setprio 1
	v_mfma_f32_16x16x32_bf16 v[60:63], v[162:165], v[178:181], v[60:63]
	v_mfma_f32_16x16x32_bf16 v[56:59], v[170:173], v[178:181], v[56:59]
	v_mfma_f32_16x16x32_bf16 v[52:55], v[162:165], v[186:189], v[52:55]
	v_mfma_f32_16x16x32_bf16 v[48:51], v[170:173], v[186:189], v[48:51]
	v_mfma_f32_16x16x32_bf16 v[44:47], v[162:165], v[194:197], v[44:47]
	v_mfma_f32_16x16x32_bf16 v[40:43], v[170:173], v[194:197], v[40:43]
	v_mfma_f32_16x16x32_bf16 v[36:39], v[162:165], v[202:205], v[36:39]
	v_mfma_f32_16x16x32_bf16 v[32:35], v[170:173], v[202:205], v[32:35]
	v_mfma_f32_16x16x32_bf16 v[60:63], v[166:169], v[182:185], v[60:63]
	v_mfma_f32_16x16x32_bf16 v[56:59], v[174:177], v[182:185], v[56:59]
	v_mfma_f32_16x16x32_bf16 v[52:55], v[166:169], v[190:193], v[52:55]
	v_mfma_f32_16x16x32_bf16 v[48:51], v[174:177], v[190:193], v[48:51]
	s_barrier
	s_setprio 2
	v_mfma_f32_16x16x32_bf16 v[44:47], v[166:169], v[198:201], v[44:47]
	v_mfma_f32_16x16x32_bf16 v[40:43], v[174:177], v[198:201], v[40:43]
	v_mfma_f32_16x16x32_bf16 v[36:39], v[166:169], v[206:209], v[36:39]
	v_mfma_f32_16x16x32_bf16 v[32:35], v[174:177], v[206:209], v[32:35]
	s_setprio 0
	s_add_i32 s26, s31, s67
	s_mov_b32 m0, s26
	ds_read_b128 v[178:181], v217 offset:49152
	ds_read_b128 v[182:185], v217 offset:50176
	ds_read_b128 v[186:189], v217 offset:51200
	ds_read_b128 v[190:193], v217 offset:52224
	ds_read_b128 v[194:197], v217 offset:53248
	ds_read_b128 v[198:201], v217 offset:54272
	ds_read_b128 v[202:205], v217 offset:55296
	ds_read_b128 v[206:209], v217 offset:56320
	global_load_lds_dwordx4 v142, s[76:77]
	s_add_i32 m0, s26, 0x2000
	s_add_u32 s24, s24, 0x80080
	s_addc_u32 s25, s25, 0
	s_add_i32 s26, s74, s67
	global_load_lds_dwordx4 v146, s[76:77]
	s_mov_b32 m0, s26
	s_nop 0
	global_load_lds_dwordx4 v142, s[24:25]
	s_add_i32 m0, s26, 0x2000
	s_nop 0
	global_load_lds_dwordx4 v146, s[24:25]
	s_mov_b32 m0, s55
	s_nop 0
	global_load_lds_dwordx4 v140, s[78:79]
	s_mov_b32 m0, s56
	s_nop 0
	global_load_lds_dwordx4 v144, s[78:79]
	s_waitcnt vmcnt(8)
	s_waitcnt lgkmcnt(0)
	s_barrier
	s_setprio 1
	s_waitcnt lgkmcnt(0)
	v_mfma_f32_16x16x32_bf16 v[92:95], v[128:131], v[178:181], v[92:95]
	v_mfma_f32_16x16x32_bf16 v[88:91], v[136:139], v[178:181], v[88:91]
	v_mfma_f32_16x16x32_bf16 v[84:87], v[128:131], v[186:189], v[84:87]
	v_mfma_f32_16x16x32_bf16 v[80:83], v[136:139], v[186:189], v[80:83]
	v_mfma_f32_16x16x32_bf16 v[76:79], v[128:131], v[194:197], v[76:79]
	v_mfma_f32_16x16x32_bf16 v[72:75], v[136:139], v[194:197], v[72:75]
	v_mfma_f32_16x16x32_bf16 v[68:71], v[128:131], v[202:205], v[68:71]
	v_mfma_f32_16x16x32_bf16 v[64:67], v[136:139], v[202:205], v[64:67]
	v_mfma_f32_16x16x32_bf16 v[92:95], v[132:135], v[182:185], v[92:95]
	v_mfma_f32_16x16x32_bf16 v[88:91], v[158:161], v[182:185], v[88:91]
	v_mfma_f32_16x16x32_bf16 v[84:87], v[132:135], v[190:193], v[84:87]
	v_mfma_f32_16x16x32_bf16 v[80:83], v[158:161], v[190:193], v[80:83]
	v_mfma_f32_16x16x32_bf16 v[76:79], v[132:135], v[198:201], v[76:79]
	v_mfma_f32_16x16x32_bf16 v[72:75], v[158:161], v[198:201], v[72:75]
	v_mfma_f32_16x16x32_bf16 v[68:71], v[132:135], v[206:209], v[68:71]
	v_mfma_f32_16x16x32_bf16 v[64:67], v[158:161], v[206:209], v[64:67]
	s_setprio 0
	s_setprio 1
	v_mfma_f32_16x16x32_bf16 v[28:31], v[162:165], v[178:181], v[28:31]
	v_mfma_f32_16x16x32_bf16 v[24:27], v[170:173], v[178:181], v[24:27]
	v_mfma_f32_16x16x32_bf16 v[20:23], v[162:165], v[186:189], v[20:23]
	v_mfma_f32_16x16x32_bf16 v[16:19], v[170:173], v[186:189], v[16:19]
	v_mfma_f32_16x16x32_bf16 v[12:15], v[162:165], v[194:197], v[12:15]
	v_mfma_f32_16x16x32_bf16 v[8:11], v[170:173], v[194:197], v[8:11]
	v_mfma_f32_16x16x32_bf16 v[4:7], v[162:165], v[202:205], v[4:7]
	v_mfma_f32_16x16x32_bf16 v[0:3], v[170:173], v[202:205], v[0:3]
	v_mfma_f32_16x16x32_bf16 v[28:31], v[166:169], v[182:185], v[28:31]
	v_mfma_f32_16x16x32_bf16 v[24:27], v[174:177], v[182:185], v[24:27]
	v_mfma_f32_16x16x32_bf16 v[20:23], v[166:169], v[190:193], v[20:23]
	v_mfma_f32_16x16x32_bf16 v[16:19], v[174:177], v[190:193], v[16:19]
	s_barrier
	s_setprio 2
	v_mfma_f32_16x16x32_bf16 v[12:15], v[166:169], v[198:201], v[12:15]
	v_mfma_f32_16x16x32_bf16 v[8:11], v[174:177], v[198:201], v[8:11]
	v_mfma_f32_16x16x32_bf16 v[4:7], v[166:169], v[206:209], v[4:7]
	v_mfma_f32_16x16x32_bf16 v[0:3], v[174:177], v[206:209], v[0:3]
	s_setprio 0
	s_add_i32 s30, s30, 2
	s_add_u32 s28, s28, 0x100
	s_addc_u32 s29, s29, 0
	s_add_u32 s22, s22, 0x100
	s_addc_u32 s23, s23, 0
	s_cmp_gt_u32 s30, 29
	s_cbranch_scc0 .LBB0_1192
	s_and_b64 vcc, exec, s[8:9]
	s_cbranch_vccz .LBB0_1195
	s_barrier

.LBB0_1304:
	ds_read_b128 v[124:127], v163
	ds_read_b128 v[156:159], v163 offset:1024
	ds_read_b128 v[170:173], v163 offset:2048
	ds_read_b128 v[174:177], v163 offset:3072
	ds_read_b128 v[178:181], v165
	ds_read_b128 v[182:185], v165 offset:1024
	ds_read_b128 v[186:189], v165 offset:2048
	ds_read_b128 v[190:193], v165 offset:3072
	s_add_u32 s26, s24, 0xfff80080
	s_addc_u32 s27, s25, -1
	s_cmp_eq_u32 s55, 28
	s_cselect_b32 s29, s17, s27
	s_cselect_b32 s28, s51, s26
	s_cselect_b32 s27, s15, s54
	s_cselect_b32 s26, s52, s53
	s_add_i32 m0, s23, 0xc000
	ds_read_b128 v[194:197], v167
	ds_read_b128 v[198:201], v167 offset:1024
	ds_read_b128 v[202:205], v167 offset:2048
	ds_read_b128 v[206:209], v167 offset:3072
	ds_read_b128 v[210:213], v167 offset:4096
	ds_read_b128 v[214:217], v167 offset:5120
	ds_read_b128 v[218:221], v167 offset:6144
	ds_read_b128 v[222:225], v167 offset:7168
	global_load_lds_dwordx4 v148, s[24:25]
	s_add_i32 m0, s23, 0xe000
	s_nop 0
	global_load_lds_dwordx4 v146, s[24:25]
	s_waitcnt vmcnt(8)
	s_waitcnt lgkmcnt(0)
	s_barrier
	s_setprio 1
	s_waitcnt lgkmcnt(0)
	v_mfma_f32_16x16x32_bf16 v[132:135], v[124:127], v[194:197], v[132:135]
	v_mfma_f32_16x16x32_bf16 v[120:123], v[170:173], v[194:197], v[120:123]
	v_mfma_f32_16x16x32_bf16 v[108:111], v[124:127], v[202:205], v[108:111]
	v_mfma_f32_16x16x32_bf16 v[100:103], v[170:173], v[202:205], v[100:103]
	v_mfma_f32_16x16x32_bf16 v[92:95], v[124:127], v[210:213], v[92:95]
	v_mfma_f32_16x16x32_bf16 v[84:87], v[170:173], v[210:213], v[84:87]
	v_mfma_f32_16x16x32_bf16 v[76:79], v[124:127], v[218:221], v[76:79]
	v_mfma_f32_16x16x32_bf16 v[68:71], v[170:173], v[218:221], v[68:71]
	v_mfma_f32_16x16x32_bf16 v[132:135], v[156:159], v[198:201], v[132:135]
	v_mfma_f32_16x16x32_bf16 v[120:123], v[174:177], v[198:201], v[120:123]
	v_mfma_f32_16x16x32_bf16 v[108:111], v[156:159], v[206:209], v[108:111]
	v_mfma_f32_16x16x32_bf16 v[100:103], v[174:177], v[206:209], v[100:103]
	v_mfma_f32_16x16x32_bf16 v[92:95], v[156:159], v[214:217], v[92:95]
	v_mfma_f32_16x16x32_bf16 v[84:87], v[174:177], v[214:217], v[84:87]
	v_mfma_f32_16x16x32_bf16 v[76:79], v[156:159], v[222:225], v[76:79]
	v_mfma_f32_16x16x32_bf16 v[68:71], v[174:177], v[222:225], v[68:71]
	s_setprio 0
	s_setprio 1
	v_mfma_f32_16x16x32_bf16 v[128:131], v[178:181], v[194:197], v[128:131]
	v_mfma_f32_16x16x32_bf16 v[114:117], v[186:189], v[194:197], v[116:119]
	v_mfma_f32_16x16x32_bf16 v[104:107], v[178:181], v[202:205], v[104:107]
	v_mfma_f32_16x16x32_bf16 v[96:99], v[186:189], v[202:205], v[96:99]
	v_mfma_f32_16x16x32_bf16 v[88:91], v[178:181], v[210:213], v[88:91]
	v_mfma_f32_16x16x32_bf16 v[80:83], v[186:189], v[210:213], v[80:83]
	v_mfma_f32_16x16x32_bf16 v[72:75], v[178:181], v[218:221], v[72:75]
	v_mfma_f32_16x16x32_bf16 v[64:67], v[186:189], v[218:221], v[64:67]
	v_mfma_f32_16x16x32_bf16 v[128:131], v[182:185], v[198:201], v[128:131]
	v_mfma_f32_16x16x32_bf16 v[114:117], v[190:193], v[198:201], v[114:117]
	v_mfma_f32_16x16x32_bf16 v[104:107], v[182:185], v[206:209], v[104:107]
	v_mfma_f32_16x16x32_bf16 v[96:99], v[190:193], v[206:209], v[96:99]
	s_barrier
	s_setprio 2
	v_mfma_f32_16x16x32_bf16 v[88:91], v[182:185], v[214:217], v[88:91]
	v_mfma_f32_16x16x32_bf16 v[80:83], v[190:193], v[214:217], v[80:83]
	v_mfma_f32_16x16x32_bf16 v[72:75], v[182:185], v[222:225], v[72:75]
	v_mfma_f32_16x16x32_bf16 v[64:67], v[190:193], v[222:225], v[64:67]
	s_setprio 0
	s_add_i32 s56, s47, s67
	s_add_u32 s60, s26, s10
	s_addc_u32 s61, s27, s11
	s_mov_b32 m0, s56
	ds_read_b128 v[194:197], v167 offset:16384
	ds_read_b128 v[198:201], v167 offset:17408
	ds_read_b128 v[202:205], v167 offset:18432
	ds_read_b128 v[206:209], v167 offset:19456
	ds_read_b128 v[210:213], v167 offset:20480
	ds_read_b128 v[214:217], v167 offset:21504
	ds_read_b128 v[218:221], v167 offset:22528
	ds_read_b128 v[222:225], v167 offset:23552
	global_load_lds_dwordx4 v138, s[26:27]
	s_add_i32 m0, s56, 0x2000
	s_add_u32 s56, s26, 0x80000
	s_addc_u32 s57, s27, 0
	s_add_i32 s58, s48, s67
	global_load_lds_dwordx4 v142, s[26:27]
	s_mov_b32 m0, s58
	s_add_u32 s62, s28, s10
	s_addc_u32 s63, s29, s11
	global_load_lds_dwordx4 v138, s[56:57]
	s_add_i32 m0, s58, 0x2000
	s_nop 0
	global_load_lds_dwordx4 v142, s[56:57]
	s_mov_b32 m0, s23
	s_nop 0
	global_load_lds_dwordx4 v136, s[28:29]
	s_mov_b32 m0, s37
	s_nop 0
	global_load_lds_dwordx4 v140, s[28:29]
	s_waitcnt vmcnt(8)
	s_waitcnt lgkmcnt(0)
	s_barrier
	s_setprio 1
	s_waitcnt lgkmcnt(0)
	v_mfma_f32_16x16x32_bf16 v[60:63], v[124:127], v[194:197], v[60:63]
	v_mfma_f32_16x16x32_bf16 v[52:55], v[170:173], v[194:197], v[52:55]
	v_mfma_f32_16x16x32_bf16 v[44:47], v[124:127], v[202:205], v[44:47]
	v_mfma_f32_16x16x32_bf16 v[36:39], v[170:173], v[202:205], v[36:39]
	v_mfma_f32_16x16x32_bf16 v[28:31], v[124:127], v[210:213], v[28:31]
	v_mfma_f32_16x16x32_bf16 v[20:23], v[170:173], v[210:213], v[20:23]
	v_mfma_f32_16x16x32_bf16 v[12:15], v[124:127], v[218:221], v[12:15]
	v_mfma_f32_16x16x32_bf16 v[4:7], v[170:173], v[218:221], v[4:7]
	v_mfma_f32_16x16x32_bf16 v[60:63], v[156:159], v[198:201], v[60:63]
	v_mfma_f32_16x16x32_bf16 v[52:55], v[174:177], v[198:201], v[52:55]
	v_mfma_f32_16x16x32_bf16 v[44:47], v[156:159], v[206:209], v[44:47]
	v_mfma_f32_16x16x32_bf16 v[36:39], v[174:177], v[206:209], v[36:39]
	v_mfma_f32_16x16x32_bf16 v[28:31], v[156:159], v[214:217], v[28:31]
	v_mfma_f32_16x16x32_bf16 v[20:23], v[174:177], v[214:217], v[20:23]
	v_mfma_f32_16x16x32_bf16 v[12:15], v[156:159], v[222:225], v[12:15]
	v_mfma_f32_16x16x32_bf16 v[4:7], v[174:177], v[222:225], v[4:7]
	s_setprio 0
	s_setprio 1
	v_mfma_f32_16x16x32_bf16 v[56:59], v[178:181], v[194:197], v[56:59]
	v_mfma_f32_16x16x32_bf16 v[48:51], v[186:189], v[194:197], v[48:51]
	v_mfma_f32_16x16x32_bf16 v[40:43], v[178:181], v[202:205], v[40:43]
	v_mfma_f32_16x16x32_bf16 v[32:35], v[186:189], v[202:205], v[32:35]
	v_mfma_f32_16x16x32_bf16 v[24:27], v[178:181], v[210:213], v[24:27]
	v_mfma_f32_16x16x32_bf16 v[16:19], v[186:189], v[210:213], v[16:19]
	v_mfma_f32_16x16x32_bf16 v[8:11], v[178:181], v[218:221], v[8:11]
	v_mfma_f32_16x16x32_bf16 v[0:3], v[186:189], v[218:221], v[0:3]
	v_mfma_f32_16x16x32_bf16 v[56:59], v[182:185], v[198:201], v[56:59]
	v_mfma_f32_16x16x32_bf16 v[48:51], v[190:193], v[198:201], v[48:51]
	v_mfma_f32_16x16x32_bf16 v[40:43], v[182:185], v[206:209], v[40:43]
	v_mfma_f32_16x16x32_bf16 v[32:35], v[190:193], v[206:209], v[32:35]
	s_barrier
	s_setprio 2
	v_mfma_f32_16x16x32_bf16 v[24:27], v[182:185], v[214:217], v[24:27]
	v_mfma_f32_16x16x32_bf16 v[16:19], v[190:193], v[214:217], v[16:19]
	v_mfma_f32_16x16x32_bf16 v[8:11], v[182:185], v[222:225], v[8:11]
	v_mfma_f32_16x16x32_bf16 v[0:3], v[190:193], v[222:225], v[0:3]
	s_setprio 0
	s_add_i32 s56, 0, 0x18000
	v_add_u32_e32 v113, s56, v155
	s_add_i32 s57, 0, 0x1c000
	ds_read_b128 v[124:127], v113
	ds_read_b128 v[156:159], v113 offset:1024
	ds_read_b128 v[170:173], v113 offset:2048
	ds_read_b128 v[174:177], v113 offset:3072
	v_add_u32_e32 v113, s57, v155
	ds_read_b128 v[178:181], v113
	ds_read_b128 v[182:185], v113 offset:1024
	ds_read_b128 v[186:189], v113 offset:2048
	ds_read_b128 v[190:193], v113 offset:3072
	s_add_u32 s28, s28, 0x80000
	s_addc_u32 s29, s29, 0
	s_mov_b32 m0, s38
	ds_read_b128 v[194:197], v167 offset:32768
	ds_read_b128 v[198:201], v167 offset:33792
	ds_read_b128 v[202:205], v167 offset:34816
	ds_read_b128 v[206:209], v167 offset:35840
	ds_read_b128 v[210:213], v167 offset:36864
	ds_read_b128 v[214:217], v167 offset:37888
	ds_read_b128 v[218:221], v167 offset:38912
	ds_read_b128 v[222:225], v167 offset:39936
	global_load_lds_dwordx4 v136, s[28:29]
	s_mov_b32 m0, s39
	s_nop 0
	global_load_lds_dwordx4 v140, s[28:29]
	s_waitcnt vmcnt(8)
	s_waitcnt lgkmcnt(0)
	s_barrier
	s_setprio 1
	s_waitcnt lgkmcnt(0)
	v_mfma_f32_16x16x32_bf16 v[132:135], v[124:127], v[194:197], v[132:135]
	v_mfma_f32_16x16x32_bf16 v[118:121], v[170:173], v[194:197], v[120:123]
	v_mfma_f32_16x16x32_bf16 v[108:111], v[124:127], v[202:205], v[108:111]
	v_mfma_f32_16x16x32_bf16 v[100:103], v[170:173], v[202:205], v[100:103]
	v_mfma_f32_16x16x32_bf16 v[92:95], v[124:127], v[210:213], v[92:95]
	v_mfma_f32_16x16x32_bf16 v[84:87], v[170:173], v[210:213], v[84:87]
	v_mfma_f32_16x16x32_bf16 v[76:79], v[124:127], v[218:221], v[76:79]
	v_mfma_f32_16x16x32_bf16 v[68:71], v[170:173], v[218:221], v[68:71]
	v_mfma_f32_16x16x32_bf16 v[132:135], v[156:159], v[198:201], v[132:135]
	v_mfma_f32_16x16x32_bf16 v[120:123], v[174:177], v[198:201], v[118:121]
	v_mfma_f32_16x16x32_bf16 v[108:111], v[156:159], v[206:209], v[108:111]
	v_mfma_f32_16x16x32_bf16 v[100:103], v[174:177], v[206:209], v[100:103]
	v_mfma_f32_16x16x32_bf16 v[92:95], v[156:159], v[214:217], v[92:95]
	v_mfma_f32_16x16x32_bf16 v[84:87], v[174:177], v[214:217], v[84:87]
	v_mfma_f32_16x16x32_bf16 v[76:79], v[156:159], v[222:225], v[76:79]
	v_mfma_f32_16x16x32_bf16 v[68:71], v[174:177], v[222:225], v[68:71]
	s_setprio 0
	s_setprio 1
	v_mfma_f32_16x16x32_bf16 v[128:131], v[178:181], v[194:197], v[128:131]
	v_mfma_f32_16x16x32_bf16 v[114:117], v[186:189], v[194:197], v[114:117]
	v_mfma_f32_16x16x32_bf16 v[104:107], v[178:181], v[202:205], v[104:107]
	v_mfma_f32_16x16x32_bf16 v[96:99], v[186:189], v[202:205], v[96:99]
	v_mfma_f32_16x16x32_bf16 v[88:91], v[178:181], v[210:213], v[88:91]
	v_mfma_f32_16x16x32_bf16 v[80:83], v[186:189], v[210:213], v[80:83]
	v_mfma_f32_16x16x32_bf16 v[72:75], v[178:181], v[218:221], v[72:75]
	v_mfma_f32_16x16x32_bf16 v[64:67], v[186:189], v[218:221], v[64:67]
	v_mfma_f32_16x16x32_bf16 v[128:131], v[182:185], v[198:201], v[128:131]
	v_mfma_f32_16x16x32_bf16 v[116:119], v[190:193], v[198:201], v[114:117]
	v_mfma_f32_16x16x32_bf16 v[104:107], v[182:185], v[206:209], v[104:107]
	v_mfma_f32_16x16x32_bf16 v[96:99], v[190:193], v[206:209], v[96:99]
	s_barrier
	s_setprio 2
	v_mfma_f32_16x16x32_bf16 v[88:91], v[182:185], v[214:217], v[88:91]
	v_mfma_f32_16x16x32_bf16 v[80:83], v[190:193], v[214:217], v[80:83]
	v_mfma_f32_16x16x32_bf16 v[72:75], v[182:185], v[222:225], v[72:75]
	v_mfma_f32_16x16x32_bf16 v[64:67], v[190:193], v[222:225], v[64:67]
	s_setprio 0
	s_add_i32 s28, s56, s67
	s_mov_b32 m0, s28
	ds_read_b128 v[194:197], v167 offset:49152
	ds_read_b128 v[198:201], v167 offset:50176
	ds_read_b128 v[202:205], v167 offset:51200
	ds_read_b128 v[206:209], v167 offset:52224
	ds_read_b128 v[210:213], v167 offset:53248
	ds_read_b128 v[214:217], v167 offset:54272
	ds_read_b128 v[218:221], v167 offset:55296
	ds_read_b128 v[222:225], v167 offset:56320
	global_load_lds_dwordx4 v138, s[60:61]
	s_add_i32 m0, s28, 0x2000
	s_add_u32 s26, s26, 0x80080
	s_addc_u32 s27, s27, 0
	s_add_i32 s28, s57, s67
	global_load_lds_dwordx4 v142, s[60:61]
	s_mov_b32 m0, s28
	s_nop 0
	global_load_lds_dwordx4 v138, s[26:27]
	s_add_i32 m0, s28, 0x2000
	s_nop 0
	global_load_lds_dwordx4 v142, s[26:27]
	s_mov_b32 m0, s41
	s_nop 0
	global_load_lds_dwordx4 v136, s[62:63]
	s_mov_b32 m0, s42
	s_nop 0
	global_load_lds_dwordx4 v140, s[62:63]
	s_waitcnt vmcnt(8)
	s_waitcnt lgkmcnt(0)
	s_barrier
	s_setprio 1
	s_waitcnt lgkmcnt(0)
	v_mfma_f32_16x16x32_bf16 v[60:63], v[124:127], v[194:197], v[60:63]
	v_mfma_f32_16x16x32_bf16 v[52:55], v[170:173], v[194:197], v[52:55]
	v_mfma_f32_16x16x32_bf16 v[44:47], v[124:127], v[202:205], v[44:47]
	v_mfma_f32_16x16x32_bf16 v[36:39], v[170:173], v[202:205], v[36:39]
	v_mfma_f32_16x16x32_bf16 v[28:31], v[124:127], v[210:213], v[28:31]
	v_mfma_f32_16x16x32_bf16 v[20:23], v[170:173], v[210:213], v[20:23]
	v_mfma_f32_16x16x32_bf16 v[12:15], v[124:127], v[218:221], v[12:15]
	v_mfma_f32_16x16x32_bf16 v[4:7], v[170:173], v[218:221], v[4:7]
	v_mfma_f32_16x16x32_bf16 v[60:63], v[156:159], v[198:201], v[60:63]
	v_mfma_f32_16x16x32_bf16 v[52:55], v[174:177], v[198:201], v[52:55]
	v_mfma_f32_16x16x32_bf16 v[44:47], v[156:159], v[206:209], v[44:47]
	v_mfma_f32_16x16x32_bf16 v[36:39], v[174:177], v[206:209], v[36:39]
	v_mfma_f32_16x16x32_bf16 v[28:31], v[156:159], v[214:217], v[28:31]
	v_mfma_f32_16x16x32_bf16 v[20:23], v[174:177], v[214:217], v[20:23]
	v_mfma_f32_16x16x32_bf16 v[12:15], v[156:159], v[222:225], v[12:15]
	v_mfma_f32_16x16x32_bf16 v[4:7], v[174:177], v[222:225], v[4:7]
	s_setprio 0
	s_setprio 1
	v_mfma_f32_16x16x32_bf16 v[56:59], v[178:181], v[194:197], v[56:59]
	v_mfma_f32_16x16x32_bf16 v[48:51], v[186:189], v[194:197], v[48:51]
	v_mfma_f32_16x16x32_bf16 v[40:43], v[178:181], v[202:205], v[40:43]
	v_mfma_f32_16x16x32_bf16 v[32:35], v[186:189], v[202:205], v[32:35]
	v_mfma_f32_16x16x32_bf16 v[24:27], v[178:181], v[210:213], v[24:27]
	v_mfma_f32_16x16x32_bf16 v[16:19], v[186:189], v[210:213], v[16:19]
	v_mfma_f32_16x16x32_bf16 v[8:11], v[178:181], v[218:221], v[8:11]
	v_mfma_f32_16x16x32_bf16 v[0:3], v[186:189], v[218:221], v[0:3]
	v_mfma_f32_16x16x32_bf16 v[56:59], v[182:185], v[198:201], v[56:59]
	v_mfma_f32_16x16x32_bf16 v[48:51], v[190:193], v[198:201], v[48:51]
	v_mfma_f32_16x16x32_bf16 v[40:43], v[182:185], v[206:209], v[40:43]
	v_mfma_f32_16x16x32_bf16 v[32:35], v[190:193], v[206:209], v[32:35]
	s_barrier
	s_setprio 2
	v_mfma_f32_16x16x32_bf16 v[24:27], v[182:185], v[214:217], v[24:27]
	v_mfma_f32_16x16x32_bf16 v[16:19], v[190:193], v[214:217], v[16:19]
	v_mfma_f32_16x16x32_bf16 v[8:11], v[182:185], v[222:225], v[8:11]
	v_mfma_f32_16x16x32_bf16 v[0:3], v[190:193], v[222:225], v[0:3]
	s_setprio 0
	s_add_i32 s55, s55, 2
	s_add_u32 s53, s53, 0x100
	s_addc_u32 s54, s54, 0
	s_add_u32 s24, s24, 0x100
	s_addc_u32 s25, s25, 0
	s_cmp_gt_u32 s55, 29
	s_cbranch_scc0 .LBB0_1304
	s_and_b64 vcc, exec, s[12:13]
	s_cbranch_vccz .LBB0_1307
	s_barrier

.LBB0_1412:
	ds_read_b128 v[128:131], v215
	ds_read_b128 v[132:135], v215 offset:1024
	ds_read_b128 v[136:139], v215 offset:2048
	ds_read_b128 v[158:161], v215 offset:3072
	ds_read_b128 v[162:165], v216
	ds_read_b128 v[166:169], v216 offset:1024
	ds_read_b128 v[170:173], v216 offset:2048
	ds_read_b128 v[174:177], v216 offset:3072
	s_add_u32 s18, s16, 0x100
	s_addc_u32 s19, s17, 0
	s_cmpk_eq_i32 s26, 0x54
	s_cselect_b32 s23, s3, s19
	s_cselect_b32 s22, s2, s18
	s_cselect_b32 s21, s15, s25
	s_cselect_b32 s20, s14, s24
	v_lshl_add_u64 v[210:211], s[16:17], 0, v[152:153]
	s_add_i32 m0, s34, 0xc000
	ds_read_b128 v[178:181], v217
	ds_read_b128 v[182:185], v217 offset:1024
	ds_read_b128 v[186:189], v217 offset:2048
	ds_read_b128 v[190:193], v217 offset:3072
	ds_read_b128 v[194:197], v217 offset:4096
	ds_read_b128 v[198:201], v217 offset:5120
	ds_read_b128 v[202:205], v217 offset:6144
	ds_read_b128 v[206:209], v217 offset:7168
	global_load_lds_dwordx4 v[210:211], off
	v_lshl_add_u64 v[210:211], s[16:17], 0, v[150:151]
	s_add_i32 m0, s34, 0xe000
	s_nop 0
	global_load_lds_dwordx4 v[210:211], off
	s_waitcnt vmcnt(8)
	s_waitcnt lgkmcnt(0)
	s_barrier
	s_setprio 1
	s_waitcnt lgkmcnt(0)
	v_mfma_f32_16x16x32_bf16 v[124:127], v[128:131], v[178:181], v[124:127]
	v_mfma_f32_16x16x32_bf16 v[120:123], v[136:139], v[178:181], v[120:123]
	v_mfma_f32_16x16x32_bf16 v[116:119], v[128:131], v[186:189], v[116:119]
	v_mfma_f32_16x16x32_bf16 v[112:115], v[136:139], v[186:189], v[112:115]
	v_mfma_f32_16x16x32_bf16 v[108:111], v[128:131], v[194:197], v[108:111]
	v_mfma_f32_16x16x32_bf16 v[104:107], v[136:139], v[194:197], v[104:107]
	v_mfma_f32_16x16x32_bf16 v[100:103], v[128:131], v[202:205], v[100:103]
	v_mfma_f32_16x16x32_bf16 v[96:99], v[136:139], v[202:205], v[96:99]
	v_mfma_f32_16x16x32_bf16 v[124:127], v[132:135], v[182:185], v[124:127]
	v_mfma_f32_16x16x32_bf16 v[120:123], v[158:161], v[182:185], v[120:123]
	v_mfma_f32_16x16x32_bf16 v[116:119], v[132:135], v[190:193], v[116:119]
	v_mfma_f32_16x16x32_bf16 v[112:115], v[158:161], v[190:193], v[112:115]
	v_mfma_f32_16x16x32_bf16 v[108:111], v[132:135], v[198:201], v[108:111]
	v_mfma_f32_16x16x32_bf16 v[104:107], v[158:161], v[198:201], v[104:107]
	v_mfma_f32_16x16x32_bf16 v[100:103], v[132:135], v[206:209], v[100:103]
	v_mfma_f32_16x16x32_bf16 v[96:99], v[158:161], v[206:209], v[96:99]
	s_setprio 0
	s_setprio 1
	v_mfma_f32_16x16x32_bf16 v[60:63], v[162:165], v[178:181], v[60:63]
	v_mfma_f32_16x16x32_bf16 v[56:59], v[170:173], v[178:181], v[56:59]
	v_mfma_f32_16x16x32_bf16 v[52:55], v[162:165], v[186:189], v[52:55]
	v_mfma_f32_16x16x32_bf16 v[48:51], v[170:173], v[186:189], v[48:51]
	v_mfma_f32_16x16x32_bf16 v[44:47], v[162:165], v[194:197], v[44:47]
	v_mfma_f32_16x16x32_bf16 v[40:43], v[170:173], v[194:197], v[40:43]
	v_mfma_f32_16x16x32_bf16 v[36:39], v[162:165], v[202:205], v[36:39]
	v_mfma_f32_16x16x32_bf16 v[32:35], v[170:173], v[202:205], v[32:35]
	v_mfma_f32_16x16x32_bf16 v[60:63], v[166:169], v[182:185], v[60:63]
	v_mfma_f32_16x16x32_bf16 v[56:59], v[174:177], v[182:185], v[56:59]
	v_mfma_f32_16x16x32_bf16 v[52:55], v[166:169], v[190:193], v[52:55]
	v_mfma_f32_16x16x32_bf16 v[48:51], v[174:177], v[190:193], v[48:51]
	s_barrier
	s_setprio 2
	v_mfma_f32_16x16x32_bf16 v[44:47], v[166:169], v[198:201], v[44:47]
	v_mfma_f32_16x16x32_bf16 v[40:43], v[174:177], v[198:201], v[40:43]
	v_mfma_f32_16x16x32_bf16 v[36:39], v[166:169], v[206:209], v[36:39]
	v_mfma_f32_16x16x32_bf16 v[32:35], v[174:177], v[206:209], v[32:35]
	s_setprio 0
	s_add_i32 s16, s56, s67
	s_add_u32 s74, s20, s8
	s_addc_u32 s75, s21, s9
	s_mov_b32 m0, s16
	ds_read_b128 v[178:181], v217 offset:16384
	ds_read_b128 v[182:185], v217 offset:17408
	ds_read_b128 v[186:189], v217 offset:18432
	ds_read_b128 v[190:193], v217 offset:19456
	ds_read_b128 v[194:197], v217 offset:20480
	ds_read_b128 v[198:201], v217 offset:21504
	ds_read_b128 v[202:205], v217 offset:22528
	ds_read_b128 v[206:209], v217 offset:23552
	global_load_lds_dwordx4 v142, s[20:21]
	s_add_i32 m0, s16, 0x2000
	s_add_u32 s16, s20, 0x160000
	s_addc_u32 s17, s21, 0
	s_add_i32 s27, s57, s67
	global_load_lds_dwordx4 v146, s[20:21]
	s_mov_b32 m0, s27
	s_add_u32 s76, s22, s8
	s_addc_u32 s77, s23, s9
	global_load_lds_dwordx4 v142, s[16:17]
	s_add_i32 m0, s27, 0x2000
	s_nop 0
	global_load_lds_dwordx4 v146, s[16:17]
	s_mov_b32 m0, s34
	s_nop 0
	global_load_lds_dwordx4 v140, s[22:23]
	s_mov_b32 m0, s35
	s_nop 0
	global_load_lds_dwordx4 v144, s[22:23]
	s_waitcnt vmcnt(8)
	s_waitcnt lgkmcnt(0)
	s_barrier
	s_setprio 1
	s_waitcnt lgkmcnt(0)
	v_mfma_f32_16x16x32_bf16 v[92:95], v[128:131], v[178:181], v[92:95]
	v_mfma_f32_16x16x32_bf16 v[88:91], v[136:139], v[178:181], v[88:91]
	v_mfma_f32_16x16x32_bf16 v[84:87], v[128:131], v[186:189], v[84:87]
	v_mfma_f32_16x16x32_bf16 v[80:83], v[136:139], v[186:189], v[80:83]
	v_mfma_f32_16x16x32_bf16 v[76:79], v[128:131], v[194:197], v[76:79]
	v_mfma_f32_16x16x32_bf16 v[72:75], v[136:139], v[194:197], v[72:75]
	v_mfma_f32_16x16x32_bf16 v[68:71], v[128:131], v[202:205], v[68:71]
	v_mfma_f32_16x16x32_bf16 v[64:67], v[136:139], v[202:205], v[64:67]
	v_mfma_f32_16x16x32_bf16 v[92:95], v[132:135], v[182:185], v[92:95]
	v_mfma_f32_16x16x32_bf16 v[88:91], v[158:161], v[182:185], v[88:91]
	v_mfma_f32_16x16x32_bf16 v[84:87], v[132:135], v[190:193], v[84:87]
	v_mfma_f32_16x16x32_bf16 v[80:83], v[158:161], v[190:193], v[80:83]
	v_mfma_f32_16x16x32_bf16 v[76:79], v[132:135], v[198:201], v[76:79]
	v_mfma_f32_16x16x32_bf16 v[72:75], v[158:161], v[198:201], v[72:75]
	v_mfma_f32_16x16x32_bf16 v[68:71], v[132:135], v[206:209], v[68:71]
	v_mfma_f32_16x16x32_bf16 v[64:67], v[158:161], v[206:209], v[64:67]
	s_setprio 0
	s_setprio 1
	v_mfma_f32_16x16x32_bf16 v[28:31], v[162:165], v[178:181], v[28:31]
	v_mfma_f32_16x16x32_bf16 v[24:27], v[170:173], v[178:181], v[24:27]
	v_mfma_f32_16x16x32_bf16 v[20:23], v[162:165], v[186:189], v[20:23]
	v_mfma_f32_16x16x32_bf16 v[16:19], v[170:173], v[186:189], v[16:19]
	v_mfma_f32_16x16x32_bf16 v[12:15], v[162:165], v[194:197], v[12:15]
	v_mfma_f32_16x16x32_bf16 v[8:11], v[170:173], v[194:197], v[8:11]
	v_mfma_f32_16x16x32_bf16 v[4:7], v[162:165], v[202:205], v[4:7]
	v_mfma_f32_16x16x32_bf16 v[0:3], v[170:173], v[202:205], v[0:3]
	v_mfma_f32_16x16x32_bf16 v[28:31], v[166:169], v[182:185], v[28:31]
	v_mfma_f32_16x16x32_bf16 v[24:27], v[174:177], v[182:185], v[24:27]
	v_mfma_f32_16x16x32_bf16 v[20:23], v[166:169], v[190:193], v[20:23]
	v_mfma_f32_16x16x32_bf16 v[16:19], v[174:177], v[190:193], v[16:19]
	s_barrier
	s_setprio 2
	v_mfma_f32_16x16x32_bf16 v[12:15], v[166:169], v[198:201], v[12:15]
	v_mfma_f32_16x16x32_bf16 v[8:11], v[174:177], v[198:201], v[8:11]
	v_mfma_f32_16x16x32_bf16 v[4:7], v[166:169], v[206:209], v[4:7]
	v_mfma_f32_16x16x32_bf16 v[0:3], v[174:177], v[206:209], v[0:3]
	s_setprio 0
	s_add_i32 s27, 0, 0x18000
	v_add_u32_e32 v148, s27, v214
	s_add_i32 s72, 0, 0x1c000
	ds_read_b128 v[128:131], v148
	ds_read_b128 v[132:135], v148 offset:1024
	ds_read_b128 v[136:139], v148 offset:2048
	ds_read_b128 v[158:161], v148 offset:3072
	v_add_u32_e32 v148, s72, v214
	ds_read_b128 v[162:165], v148
	ds_read_b128 v[166:169], v148 offset:1024
	ds_read_b128 v[170:173], v148 offset:2048
	ds_read_b128 v[174:177], v148 offset:3072
	s_add_u32 s16, s22, 0x160000
	s_addc_u32 s17, s23, 0
	s_mov_b32 m0, s36
	ds_read_b128 v[178:181], v217 offset:32768
	ds_read_b128 v[182:185], v217 offset:33792
	ds_read_b128 v[186:189], v217 offset:34816
	ds_read_b128 v[190:193], v217 offset:35840
	ds_read_b128 v[194:197], v217 offset:36864
	ds_read_b128 v[198:201], v217 offset:37888
	ds_read_b128 v[202:205], v217 offset:38912
	ds_read_b128 v[206:209], v217 offset:39936
	global_load_lds_dwordx4 v140, s[16:17]
	s_mov_b32 m0, s37
	s_nop 0
	global_load_lds_dwordx4 v144, s[16:17]
	s_waitcnt vmcnt(8)
	s_waitcnt lgkmcnt(0)
	s_barrier
	s_setprio 1
	s_waitcnt lgkmcnt(0)
	v_mfma_f32_16x16x32_bf16 v[124:127], v[128:131], v[178:181], v[124:127]
	v_mfma_f32_16x16x32_bf16 v[120:123], v[136:139], v[178:181], v[120:123]
	v_mfma_f32_16x16x32_bf16 v[116:119], v[128:131], v[186:189], v[116:119]
	v_mfma_f32_16x16x32_bf16 v[112:115], v[136:139], v[186:189], v[112:115]
	v_mfma_f32_16x16x32_bf16 v[108:111], v[128:131], v[194:197], v[108:111]
	v_mfma_f32_16x16x32_bf16 v[104:107], v[136:139], v[194:197], v[104:107]
	v_mfma_f32_16x16x32_bf16 v[100:103], v[128:131], v[202:205], v[100:103]
	v_mfma_f32_16x16x32_bf16 v[96:99], v[136:139], v[202:205], v[96:99]
	v_mfma_f32_16x16x32_bf16 v[124:127], v[132:135], v[182:185], v[124:127]
	v_mfma_f32_16x16x32_bf16 v[120:123], v[158:161], v[182:185], v[120:123]
	v_mfma_f32_16x16x32_bf16 v[116:119], v[132:135], v[190:193], v[116:119]
	v_mfma_f32_16x16x32_bf16 v[112:115], v[158:161], v[190:193], v[112:115]
	v_mfma_f32_16x16x32_bf16 v[108:111], v[132:135], v[198:201], v[108:111]
	v_mfma_f32_16x16x32_bf16 v[104:107], v[158:161], v[198:201], v[104:107]
	v_mfma_f32_16x16x32_bf16 v[100:103], v[132:135], v[206:209], v[100:103]
	v_mfma_f32_16x16x32_bf16 v[96:99], v[158:161], v[206:209], v[96:99]
	s_setprio 0
	s_setprio 1
	v_mfma_f32_16x16x32_bf16 v[60:63], v[162:165], v[178:181], v[60:63]
	v_mfma_f32_16x16x32_bf16 v[56:59], v[170:173], v[178:181], v[56:59]
	v_mfma_f32_16x16x32_bf16 v[52:55], v[162:165], v[186:189], v[52:55]
	v_mfma_f32_16x16x32_bf16 v[48:51], v[170:173], v[186:189], v[48:51]
	v_mfma_f32_16x16x32_bf16 v[44:47], v[162:165], v[194:197], v[44:47]
	v_mfma_f32_16x16x32_bf16 v[40:43], v[170:173], v[194:197], v[40:43]
	v_mfma_f32_16x16x32_bf16 v[36:39], v[162:165], v[202:205], v[36:39]
	v_mfma_f32_16x16x32_bf16 v[32:35], v[170:173], v[202:205], v[32:35]
	v_mfma_f32_16x16x32_bf16 v[60:63], v[166:169], v[182:185], v[60:63]
	v_mfma_f32_16x16x32_bf16 v[56:59], v[174:177], v[182:185], v[56:59]
	v_mfma_f32_16x16x32_bf16 v[52:55], v[166:169], v[190:193], v[52:55]
	v_mfma_f32_16x16x32_bf16 v[48:51], v[174:177], v[190:193], v[48:51]
	s_barrier
	s_setprio 2
	v_mfma_f32_16x16x32_bf16 v[44:47], v[166:169], v[198:201], v[44:47]
	v_mfma_f32_16x16x32_bf16 v[40:43], v[174:177], v[198:201], v[40:43]
	v_mfma_f32_16x16x32_bf16 v[36:39], v[166:169], v[206:209], v[36:39]
	v_mfma_f32_16x16x32_bf16 v[32:35], v[174:177], v[206:209], v[32:35]
	s_setprio 0
	s_add_i32 s16, s27, s67
	s_mov_b32 m0, s16
	ds_read_b128 v[178:181], v217 offset:49152
	ds_read_b128 v[182:185], v217 offset:50176
	ds_read_b128 v[186:189], v217 offset:51200
	ds_read_b128 v[190:193], v217 offset:52224
	ds_read_b128 v[194:197], v217 offset:53248
	ds_read_b128 v[198:201], v217 offset:54272
	ds_read_b128 v[202:205], v217 offset:55296
	ds_read_b128 v[206:209], v217 offset:56320
	global_load_lds_dwordx4 v142, s[74:75]
	s_add_i32 m0, s16, 0x2000
	s_add_u32 s16, s20, 0x160080
	s_addc_u32 s17, s21, 0
	s_add_i32 s20, s72, s67
	global_load_lds_dwordx4 v146, s[74:75]
	s_mov_b32 m0, s20
	s_nop 0
	global_load_lds_dwordx4 v142, s[16:17]
	s_add_i32 m0, s20, 0x2000
	s_nop 0
	global_load_lds_dwordx4 v146, s[16:17]
	s_mov_b32 m0, s51
	s_nop 0
	global_load_lds_dwordx4 v140, s[76:77]
	s_mov_b32 m0, s52
	s_nop 0
	global_load_lds_dwordx4 v144, s[76:77]
	s_waitcnt vmcnt(8)
	s_waitcnt lgkmcnt(0)
	s_barrier
	s_setprio 1
	s_waitcnt lgkmcnt(0)
	v_mfma_f32_16x16x32_bf16 v[92:95], v[128:131], v[178:181], v[92:95]
	v_mfma_f32_16x16x32_bf16 v[88:91], v[136:139], v[178:181], v[88:91]
	v_mfma_f32_16x16x32_bf16 v[84:87], v[128:131], v[186:189], v[84:87]
	v_mfma_f32_16x16x32_bf16 v[80:83], v[136:139], v[186:189], v[80:83]
	v_mfma_f32_16x16x32_bf16 v[76:79], v[128:131], v[194:197], v[76:79]
	v_mfma_f32_16x16x32_bf16 v[72:75], v[136:139], v[194:197], v[72:75]
	v_mfma_f32_16x16x32_bf16 v[68:71], v[128:131], v[202:205], v[68:71]
	v_mfma_f32_16x16x32_bf16 v[64:67], v[136:139], v[202:205], v[64:67]
	v_mfma_f32_16x16x32_bf16 v[92:95], v[132:135], v[182:185], v[92:95]
	v_mfma_f32_16x16x32_bf16 v[88:91], v[158:161], v[182:185], v[88:91]
	v_mfma_f32_16x16x32_bf16 v[84:87], v[132:135], v[190:193], v[84:87]
	v_mfma_f32_16x16x32_bf16 v[80:83], v[158:161], v[190:193], v[80:83]
	v_mfma_f32_16x16x32_bf16 v[76:79], v[132:135], v[198:201], v[76:79]
	v_mfma_f32_16x16x32_bf16 v[72:75], v[158:161], v[198:201], v[72:75]
	v_mfma_f32_16x16x32_bf16 v[68:71], v[132:135], v[206:209], v[68:71]
	v_mfma_f32_16x16x32_bf16 v[64:67], v[158:161], v[206:209], v[64:67]
	s_setprio 0
	s_setprio 1
	v_mfma_f32_16x16x32_bf16 v[28:31], v[162:165], v[178:181], v[28:31]
	v_mfma_f32_16x16x32_bf16 v[24:27], v[170:173], v[178:181], v[24:27]
	v_mfma_f32_16x16x32_bf16 v[20:23], v[162:165], v[186:189], v[20:23]
	v_mfma_f32_16x16x32_bf16 v[16:19], v[170:173], v[186:189], v[16:19]
	v_mfma_f32_16x16x32_bf16 v[12:15], v[162:165], v[194:197], v[12:15]
	v_mfma_f32_16x16x32_bf16 v[8:11], v[170:173], v[194:197], v[8:11]
	v_mfma_f32_16x16x32_bf16 v[4:7], v[162:165], v[202:205], v[4:7]
	v_mfma_f32_16x16x32_bf16 v[0:3], v[170:173], v[202:205], v[0:3]
	v_mfma_f32_16x16x32_bf16 v[28:31], v[166:169], v[182:185], v[28:31]
	v_mfma_f32_16x16x32_bf16 v[24:27], v[174:177], v[182:185], v[24:27]
	v_mfma_f32_16x16x32_bf16 v[20:23], v[166:169], v[190:193], v[20:23]
	v_mfma_f32_16x16x32_bf16 v[16:19], v[174:177], v[190:193], v[16:19]
	s_barrier
	s_setprio 2
	v_mfma_f32_16x16x32_bf16 v[12:15], v[166:169], v[198:201], v[12:15]
	v_mfma_f32_16x16x32_bf16 v[8:11], v[174:177], v[198:201], v[8:11]
	v_mfma_f32_16x16x32_bf16 v[4:7], v[166:169], v[206:209], v[4:7]
	v_mfma_f32_16x16x32_bf16 v[0:3], v[174:177], v[206:209], v[0:3]
	s_setprio 0
	s_add_i32 s26, s26, 2
	s_add_u32 s24, s24, 0x100
	s_addc_u32 s25, s25, 0
	s_cmpk_gt_u32 s26, 0x55
	s_mov_b64 s[16:17], s[18:19]
	s_cbranch_scc0 .LBB0_1412
	s_and_b64 vcc, exec, s[10:11]
	s_cbranch_vccz .LBB0_1415
	s_barrier

.LBB0_1502:
	ds_read_b128 v[130:133], v177
	ds_read_b128 v[134:137], v177 offset:1024
	ds_read_b128 v[138:141], v177 offset:2048
	ds_read_b128 v[142:145], v177 offset:3072
	ds_read_b128 v[146:149], v179
	ds_read_b128 v[184:187], v179 offset:1024
	ds_read_b128 v[188:191], v179 offset:2048
	ds_read_b128 v[192:195], v179 offset:3072
	s_add_u32 s30, s28, 0xfff80080
	s_addc_u32 s31, s29, -1
	s_cmp_eq_u32 s60, 28
	s_cselect_b32 s35, s6, s31
	s_cselect_b32 s34, s21, s30
	s_cselect_b32 s31, s19, s59
	s_cselect_b32 s30, s27, s58
	s_add_i32 m0, s41, 0xc000
	ds_read_b128 v[196:199], v181
	ds_read_b128 v[200:203], v181 offset:1024
	ds_read_b128 v[204:207], v181 offset:2048
	ds_read_b128 v[208:211], v181 offset:3072
	ds_read_b128 v[212:215], v181 offset:4096
	ds_read_b128 v[216:219], v181 offset:5120
	ds_read_b128 v[220:223], v181 offset:6144
	ds_read_b128 v[224:227], v181 offset:7168
	global_load_lds_dwordx4 v166, s[28:29]
	s_add_i32 m0, s41, 0xe000
	s_nop 0
	global_load_lds_dwordx4 v164, s[28:29]
	s_waitcnt vmcnt(8)
	s_waitcnt lgkmcnt(0)
	s_barrier
	s_setprio 1
	s_waitcnt lgkmcnt(0)
	v_mfma_f32_16x16x32_bf16 v[124:127], v[130:133], v[196:199], v[124:127]
	v_mfma_f32_16x16x32_bf16 v[120:123], v[138:141], v[196:199], v[120:123]
	v_mfma_f32_16x16x32_bf16 v[108:111], v[130:133], v[204:207], v[108:111]
	v_mfma_f32_16x16x32_bf16 v[100:103], v[138:141], v[204:207], v[100:103]
	v_mfma_f32_16x16x32_bf16 v[92:95], v[130:133], v[212:215], v[92:95]
	v_mfma_f32_16x16x32_bf16 v[84:87], v[138:141], v[212:215], v[84:87]
	v_mfma_f32_16x16x32_bf16 v[76:79], v[130:133], v[220:223], v[76:79]
	v_mfma_f32_16x16x32_bf16 v[68:71], v[138:141], v[220:223], v[68:71]
	v_mfma_f32_16x16x32_bf16 v[124:127], v[134:137], v[200:203], v[124:127]
	v_mfma_f32_16x16x32_bf16 v[120:123], v[142:145], v[200:203], v[120:123]
	v_mfma_f32_16x16x32_bf16 v[108:111], v[134:137], v[208:211], v[108:111]
	v_mfma_f32_16x16x32_bf16 v[100:103], v[142:145], v[208:211], v[100:103]
	v_mfma_f32_16x16x32_bf16 v[92:95], v[134:137], v[216:219], v[92:95]
	v_mfma_f32_16x16x32_bf16 v[84:87], v[142:145], v[216:219], v[84:87]
	v_mfma_f32_16x16x32_bf16 v[76:79], v[134:137], v[224:227], v[76:79]
	v_mfma_f32_16x16x32_bf16 v[68:71], v[142:145], v[224:227], v[68:71]
	s_setprio 0
	s_setprio 1
	v_mfma_f32_16x16x32_bf16 v[116:119], v[146:149], v[196:199], v[116:119]
	v_mfma_f32_16x16x32_bf16 v[112:115], v[188:191], v[196:199], v[112:115]
	v_mfma_f32_16x16x32_bf16 v[104:107], v[146:149], v[204:207], v[104:107]
	v_mfma_f32_16x16x32_bf16 v[96:99], v[188:191], v[204:207], v[96:99]
	v_mfma_f32_16x16x32_bf16 v[88:91], v[146:149], v[212:215], v[88:91]
	v_mfma_f32_16x16x32_bf16 v[80:83], v[188:191], v[212:215], v[80:83]
	v_mfma_f32_16x16x32_bf16 v[72:75], v[146:149], v[220:223], v[72:75]
	v_mfma_f32_16x16x32_bf16 v[64:67], v[188:191], v[220:223], v[64:67]
	v_mfma_f32_16x16x32_bf16 v[116:119], v[184:187], v[200:203], v[116:119]
	v_mfma_f32_16x16x32_bf16 v[112:115], v[192:195], v[200:203], v[112:115]
	v_mfma_f32_16x16x32_bf16 v[104:107], v[184:187], v[208:211], v[104:107]
	v_mfma_f32_16x16x32_bf16 v[96:99], v[192:195], v[208:211], v[96:99]
	s_barrier
	s_setprio 2
	v_mfma_f32_16x16x32_bf16 v[88:91], v[184:187], v[216:219], v[88:91]
	v_mfma_f32_16x16x32_bf16 v[80:83], v[192:195], v[216:219], v[80:83]
	v_mfma_f32_16x16x32_bf16 v[72:75], v[184:187], v[224:227], v[72:75]
	v_mfma_f32_16x16x32_bf16 v[64:67], v[192:195], v[224:227], v[64:67]
	s_setprio 0
	s_add_i32 s61, s53, s67
	s_add_u32 s72, s30, s12
	s_addc_u32 s73, s31, s13
	s_mov_b32 m0, s61
	ds_read_b128 v[196:199], v181 offset:16384
	ds_read_b128 v[200:203], v181 offset:17408
	ds_read_b128 v[204:207], v181 offset:18432
	ds_read_b128 v[208:211], v181 offset:19456
	ds_read_b128 v[212:215], v181 offset:20480
	ds_read_b128 v[216:219], v181 offset:21504
	ds_read_b128 v[220:223], v181 offset:22528
	ds_read_b128 v[224:227], v181 offset:23552
	global_load_lds_dwordx4 v154, s[30:31]
	s_add_i32 m0, s61, 0x2000
	s_add_u32 s62, s30, 0x80000
	s_addc_u32 s63, s31, 0
	s_add_i32 s61, s54, s67
	global_load_lds_dwordx4 v158, s[30:31]
	s_mov_b32 m0, s61
	s_add_u32 s74, s34, s12
	s_addc_u32 s75, s35, s13
	global_load_lds_dwordx4 v154, s[62:63]
	s_add_i32 m0, s61, 0x2000
	s_nop 0
	global_load_lds_dwordx4 v158, s[62:63]
	s_mov_b32 m0, s41
	s_nop 0
	global_load_lds_dwordx4 v152, s[34:35]
	s_mov_b32 m0, s42
	s_nop 0
	global_load_lds_dwordx4 v156, s[34:35]
	s_waitcnt vmcnt(8)
	s_waitcnt lgkmcnt(0)
	s_barrier
	s_setprio 1
	s_waitcnt lgkmcnt(0)
	v_mfma_f32_16x16x32_bf16 v[60:63], v[130:133], v[196:199], v[60:63]
	v_mfma_f32_16x16x32_bf16 v[52:55], v[138:141], v[196:199], v[52:55]
	v_mfma_f32_16x16x32_bf16 v[44:47], v[130:133], v[204:207], v[44:47]
	v_mfma_f32_16x16x32_bf16 v[36:39], v[138:141], v[204:207], v[36:39]
	v_mfma_f32_16x16x32_bf16 v[28:31], v[130:133], v[212:215], v[28:31]
	v_mfma_f32_16x16x32_bf16 v[20:23], v[138:141], v[212:215], v[20:23]
	v_mfma_f32_16x16x32_bf16 v[12:15], v[130:133], v[220:223], v[12:15]
	v_mfma_f32_16x16x32_bf16 v[4:7], v[138:141], v[220:223], v[4:7]
	v_mfma_f32_16x16x32_bf16 v[60:63], v[134:137], v[200:203], v[60:63]
	v_mfma_f32_16x16x32_bf16 v[52:55], v[142:145], v[200:203], v[52:55]
	v_mfma_f32_16x16x32_bf16 v[44:47], v[134:137], v[208:211], v[44:47]
	v_mfma_f32_16x16x32_bf16 v[36:39], v[142:145], v[208:211], v[36:39]
	v_mfma_f32_16x16x32_bf16 v[28:31], v[134:137], v[216:219], v[28:31]
	v_mfma_f32_16x16x32_bf16 v[20:23], v[142:145], v[216:219], v[20:23]
	v_mfma_f32_16x16x32_bf16 v[12:15], v[134:137], v[224:227], v[12:15]
	v_mfma_f32_16x16x32_bf16 v[4:7], v[142:145], v[224:227], v[4:7]
	s_setprio 0
	s_setprio 1
	v_mfma_f32_16x16x32_bf16 v[56:59], v[146:149], v[196:199], v[56:59]
	v_mfma_f32_16x16x32_bf16 v[48:51], v[188:191], v[196:199], v[48:51]
	v_mfma_f32_16x16x32_bf16 v[40:43], v[146:149], v[204:207], v[40:43]
	v_mfma_f32_16x16x32_bf16 v[32:35], v[188:191], v[204:207], v[32:35]
	v_mfma_f32_16x16x32_bf16 v[24:27], v[146:149], v[212:215], v[24:27]
	v_mfma_f32_16x16x32_bf16 v[16:19], v[188:191], v[212:215], v[16:19]
	v_mfma_f32_16x16x32_bf16 v[8:11], v[146:149], v[220:223], v[8:11]
	v_mfma_f32_16x16x32_bf16 v[0:3], v[188:191], v[220:223], v[0:3]
	v_mfma_f32_16x16x32_bf16 v[56:59], v[184:187], v[200:203], v[56:59]
	v_mfma_f32_16x16x32_bf16 v[48:51], v[192:195], v[200:203], v[48:51]
	v_mfma_f32_16x16x32_bf16 v[40:43], v[184:187], v[208:211], v[40:43]
	v_mfma_f32_16x16x32_bf16 v[32:35], v[192:195], v[208:211], v[32:35]
	s_barrier
	s_setprio 2
	v_mfma_f32_16x16x32_bf16 v[24:27], v[184:187], v[216:219], v[24:27]
	v_mfma_f32_16x16x32_bf16 v[16:19], v[192:195], v[216:219], v[16:19]
	v_mfma_f32_16x16x32_bf16 v[8:11], v[184:187], v[224:227], v[8:11]
	v_mfma_f32_16x16x32_bf16 v[0:3], v[192:195], v[224:227], v[0:3]
	s_setprio 0
	s_add_i32 s61, 0, 0x18000
	v_add_u32_e32 v129, s61, v173
	s_add_i32 s62, 0, 0x1c000
	ds_read_b128 v[130:133], v129
	ds_read_b128 v[134:137], v129 offset:1024
	ds_read_b128 v[138:141], v129 offset:2048
	ds_read_b128 v[142:145], v129 offset:3072
	v_add_u32_e32 v129, s62, v173
	ds_read_b128 v[146:149], v129
	ds_read_b128 v[184:187], v129 offset:1024
	ds_read_b128 v[188:191], v129 offset:2048
	ds_read_b128 v[192:195], v129 offset:3072
	s_add_u32 s34, s34, 0x80000
	s_addc_u32 s35, s35, 0
	s_mov_b32 m0, s43
	ds_read_b128 v[196:199], v181 offset:32768
	ds_read_b128 v[200:203], v181 offset:33792
	ds_read_b128 v[204:207], v181 offset:34816
	ds_read_b128 v[208:211], v181 offset:35840
	ds_read_b128 v[212:215], v181 offset:36864
	ds_read_b128 v[216:219], v181 offset:37888
	ds_read_b128 v[220:223], v181 offset:38912
	ds_read_b128 v[224:227], v181 offset:39936
	global_load_lds_dwordx4 v152, s[34:35]
	s_mov_b32 m0, s44
	s_nop 0
	global_load_lds_dwordx4 v156, s[34:35]
	s_waitcnt vmcnt(8)
	s_waitcnt lgkmcnt(0)
	s_barrier
	s_setprio 1
	s_waitcnt lgkmcnt(0)
	v_mfma_f32_16x16x32_bf16 v[124:127], v[130:133], v[196:199], v[124:127]
	v_mfma_f32_16x16x32_bf16 v[120:123], v[138:141], v[196:199], v[120:123]
	v_mfma_f32_16x16x32_bf16 v[108:111], v[130:133], v[204:207], v[108:111]
	v_mfma_f32_16x16x32_bf16 v[100:103], v[138:141], v[204:207], v[100:103]
	v_mfma_f32_16x16x32_bf16 v[92:95], v[130:133], v[212:215], v[92:95]
	v_mfma_f32_16x16x32_bf16 v[84:87], v[138:141], v[212:215], v[84:87]
	v_mfma_f32_16x16x32_bf16 v[76:79], v[130:133], v[220:223], v[76:79]
	v_mfma_f32_16x16x32_bf16 v[68:71], v[138:141], v[220:223], v[68:71]
	v_mfma_f32_16x16x32_bf16 v[124:127], v[134:137], v[200:203], v[124:127]
	v_mfma_f32_16x16x32_bf16 v[120:123], v[142:145], v[200:203], v[120:123]
	v_mfma_f32_16x16x32_bf16 v[108:111], v[134:137], v[208:211], v[108:111]
	v_mfma_f32_16x16x32_bf16 v[100:103], v[142:145], v[208:211], v[100:103]
	v_mfma_f32_16x16x32_bf16 v[92:95], v[134:137], v[216:219], v[92:95]
	v_mfma_f32_16x16x32_bf16 v[84:87], v[142:145], v[216:219], v[84:87]
	v_mfma_f32_16x16x32_bf16 v[76:79], v[134:137], v[224:227], v[76:79]
	v_mfma_f32_16x16x32_bf16 v[68:71], v[142:145], v[224:227], v[68:71]
	s_setprio 0
	s_setprio 1
	v_mfma_f32_16x16x32_bf16 v[116:119], v[146:149], v[196:199], v[116:119]
	v_mfma_f32_16x16x32_bf16 v[112:115], v[188:191], v[196:199], v[112:115]
	v_mfma_f32_16x16x32_bf16 v[104:107], v[146:149], v[204:207], v[104:107]
	v_mfma_f32_16x16x32_bf16 v[96:99], v[188:191], v[204:207], v[96:99]
	v_mfma_f32_16x16x32_bf16 v[88:91], v[146:149], v[212:215], v[88:91]
	v_mfma_f32_16x16x32_bf16 v[80:83], v[188:191], v[212:215], v[80:83]
	v_mfma_f32_16x16x32_bf16 v[72:75], v[146:149], v[220:223], v[72:75]
	v_mfma_f32_16x16x32_bf16 v[64:67], v[188:191], v[220:223], v[64:67]
	v_mfma_f32_16x16x32_bf16 v[116:119], v[184:187], v[200:203], v[116:119]
	v_mfma_f32_16x16x32_bf16 v[112:115], v[192:195], v[200:203], v[112:115]
	v_mfma_f32_16x16x32_bf16 v[104:107], v[184:187], v[208:211], v[104:107]
	v_mfma_f32_16x16x32_bf16 v[96:99], v[192:195], v[208:211], v[96:99]
	s_barrier
	s_setprio 2
	v_mfma_f32_16x16x32_bf16 v[88:91], v[184:187], v[216:219], v[88:91]
	v_mfma_f32_16x16x32_bf16 v[80:83], v[192:195], v[216:219], v[80:83]
	v_mfma_f32_16x16x32_bf16 v[72:75], v[184:187], v[224:227], v[72:75]
	v_mfma_f32_16x16x32_bf16 v[64:67], v[192:195], v[224:227], v[64:67]
	s_setprio 0
	s_add_i32 s34, s61, s67
	s_mov_b32 m0, s34
	ds_read_b128 v[196:199], v181 offset:49152
	ds_read_b128 v[200:203], v181 offset:50176
	ds_read_b128 v[204:207], v181 offset:51200
	ds_read_b128 v[208:211], v181 offset:52224
	ds_read_b128 v[212:215], v181 offset:53248
	ds_read_b128 v[216:219], v181 offset:54272
	ds_read_b128 v[220:223], v181 offset:55296
	ds_read_b128 v[224:227], v181 offset:56320
	global_load_lds_dwordx4 v154, s[72:73]
	s_add_i32 m0, s34, 0x2000
	s_add_u32 s30, s30, 0x80080
	s_addc_u32 s31, s31, 0
	s_add_i32 s34, s62, s67
	global_load_lds_dwordx4 v158, s[72:73]
	s_mov_b32 m0, s34
	s_nop 0
	global_load_lds_dwordx4 v154, s[30:31]
	s_add_i32 m0, s34, 0x2000
	s_nop 0
	global_load_lds_dwordx4 v158, s[30:31]
	s_mov_b32 m0, s47
	s_nop 0
	global_load_lds_dwordx4 v152, s[74:75]
	s_mov_b32 m0, s48
	s_nop 0
	global_load_lds_dwordx4 v156, s[74:75]
	s_waitcnt vmcnt(8)
	s_waitcnt lgkmcnt(0)
	s_barrier
	s_setprio 1
	s_waitcnt lgkmcnt(0)
	v_mfma_f32_16x16x32_bf16 v[60:63], v[130:133], v[196:199], v[60:63]
	v_mfma_f32_16x16x32_bf16 v[52:55], v[138:141], v[196:199], v[52:55]
	v_mfma_f32_16x16x32_bf16 v[44:47], v[130:133], v[204:207], v[44:47]
	v_mfma_f32_16x16x32_bf16 v[36:39], v[138:141], v[204:207], v[36:39]
	v_mfma_f32_16x16x32_bf16 v[28:31], v[130:133], v[212:215], v[28:31]
	v_mfma_f32_16x16x32_bf16 v[20:23], v[138:141], v[212:215], v[20:23]
	v_mfma_f32_16x16x32_bf16 v[12:15], v[130:133], v[220:223], v[12:15]
	v_mfma_f32_16x16x32_bf16 v[4:7], v[138:141], v[220:223], v[4:7]
	v_mfma_f32_16x16x32_bf16 v[60:63], v[134:137], v[200:203], v[60:63]
	v_mfma_f32_16x16x32_bf16 v[52:55], v[142:145], v[200:203], v[52:55]
	v_mfma_f32_16x16x32_bf16 v[44:47], v[134:137], v[208:211], v[44:47]
	v_mfma_f32_16x16x32_bf16 v[36:39], v[142:145], v[208:211], v[36:39]
	v_mfma_f32_16x16x32_bf16 v[28:31], v[134:137], v[216:219], v[28:31]
	v_mfma_f32_16x16x32_bf16 v[20:23], v[142:145], v[216:219], v[20:23]
	v_mfma_f32_16x16x32_bf16 v[12:15], v[134:137], v[224:227], v[12:15]
	v_mfma_f32_16x16x32_bf16 v[4:7], v[142:145], v[224:227], v[4:7]
	s_setprio 0
	s_setprio 1
	v_mfma_f32_16x16x32_bf16 v[56:59], v[146:149], v[196:199], v[56:59]
	v_mfma_f32_16x16x32_bf16 v[48:51], v[188:191], v[196:199], v[48:51]
	v_mfma_f32_16x16x32_bf16 v[40:43], v[146:149], v[204:207], v[40:43]
	v_mfma_f32_16x16x32_bf16 v[32:35], v[188:191], v[204:207], v[32:35]
	v_mfma_f32_16x16x32_bf16 v[24:27], v[146:149], v[212:215], v[24:27]
	v_mfma_f32_16x16x32_bf16 v[16:19], v[188:191], v[212:215], v[16:19]
	v_mfma_f32_16x16x32_bf16 v[8:11], v[146:149], v[220:223], v[8:11]
	v_mfma_f32_16x16x32_bf16 v[0:3], v[188:191], v[220:223], v[0:3]
	v_mfma_f32_16x16x32_bf16 v[56:59], v[184:187], v[200:203], v[56:59]
	v_mfma_f32_16x16x32_bf16 v[48:51], v[192:195], v[200:203], v[48:51]
	v_mfma_f32_16x16x32_bf16 v[40:43], v[184:187], v[208:211], v[40:43]
	v_mfma_f32_16x16x32_bf16 v[32:35], v[192:195], v[208:211], v[32:35]
	s_barrier
	s_setprio 2
	v_mfma_f32_16x16x32_bf16 v[24:27], v[184:187], v[216:219], v[24:27]
	v_mfma_f32_16x16x32_bf16 v[16:19], v[192:195], v[216:219], v[16:19]
	v_mfma_f32_16x16x32_bf16 v[8:11], v[184:187], v[224:227], v[8:11]
	v_mfma_f32_16x16x32_bf16 v[0:3], v[192:195], v[224:227], v[0:3]
	s_setprio 0
	s_add_i32 s60, s60, 2
	s_add_u32 s58, s58, 0x100
	s_addc_u32 s59, s59, 0
	s_add_u32 s28, s28, 0x100
	s_addc_u32 s29, s29, 0
	s_cmp_gt_u32 s60, 29
	s_cbranch_scc0 .LBB0_1502
	s_and_b64 vcc, exec, s[14:15]
	s_cbranch_vccz .LBB0_1505
	s_barrier

.LBB0_1661:
	ds_read_b128 v[128:131], v243
	ds_read_b128 v[132:135], v243 offset:1024
	ds_read_b128 v[136:139], v243 offset:2048
	ds_read_b128 v[140:143], v243 offset:3072
	ds_read_b128 v[144:147], v244
	ds_read_b128 v[148:151], v244 offset:1024
	ds_read_b128 v[152:155], v244 offset:2048
	ds_read_b128 v[156:159], v244 offset:3072
	s_add_u32 s26, s24, 0xfff80080
	s_addc_u32 s27, s25, -1
	s_cmp_eq_u32 s75, 28
	s_cselect_b32 s29, s3, s27
	s_cselect_b32 s28, s5, s26
	s_cselect_b32 s27, s17, s31
	s_cselect_b32 s26, s19, s30
	s_add_i32 m0, s38, 0xc000
	ds_read_b128 v[160:163], v245
	ds_read_b128 v[164:167], v245 offset:1024
	ds_read_b128 v[186:189], v245 offset:2048
	ds_read_b128 v[190:193], v245 offset:3072
	ds_read_b128 v[194:197], v245 offset:4096
	ds_read_b128 v[198:201], v245 offset:5120
	ds_read_b128 v[202:205], v245 offset:6144
	ds_read_b128 v[206:209], v245 offset:7168
	global_load_lds_dwordx4 v180, s[24:25]
	s_add_i32 m0, s38, 0xe000
	s_nop 0
	global_load_lds_dwordx4 v178, s[24:25]
	s_waitcnt vmcnt(8)
	s_waitcnt lgkmcnt(0)
	s_barrier
	s_setprio 1
	s_waitcnt lgkmcnt(0)
	v_mfma_f32_16x16x32_bf16 v[124:127], v[128:131], v[160:163], v[124:127]
	v_mfma_f32_16x16x32_bf16 v[120:123], v[136:139], v[160:163], v[120:123]
	v_mfma_f32_16x16x32_bf16 v[116:119], v[128:131], v[186:189], v[116:119]
	v_mfma_f32_16x16x32_bf16 v[112:115], v[136:139], v[186:189], v[112:115]
	v_mfma_f32_16x16x32_bf16 v[108:111], v[128:131], v[194:197], v[108:111]
	v_mfma_f32_16x16x32_bf16 v[104:107], v[136:139], v[194:197], v[104:107]
	v_mfma_f32_16x16x32_bf16 v[100:103], v[128:131], v[202:205], v[100:103]
	v_mfma_f32_16x16x32_bf16 v[96:99], v[136:139], v[202:205], v[96:99]
	v_mfma_f32_16x16x32_bf16 v[124:127], v[132:135], v[164:167], v[124:127]
	v_mfma_f32_16x16x32_bf16 v[120:123], v[140:143], v[164:167], v[120:123]
	v_mfma_f32_16x16x32_bf16 v[116:119], v[132:135], v[190:193], v[116:119]
	v_mfma_f32_16x16x32_bf16 v[112:115], v[140:143], v[190:193], v[112:115]
	v_mfma_f32_16x16x32_bf16 v[108:111], v[132:135], v[198:201], v[108:111]
	v_mfma_f32_16x16x32_bf16 v[104:107], v[140:143], v[198:201], v[104:107]
	v_mfma_f32_16x16x32_bf16 v[100:103], v[132:135], v[206:209], v[100:103]
	v_mfma_f32_16x16x32_bf16 v[96:99], v[140:143], v[206:209], v[96:99]
	s_setprio 0
	s_setprio 1
	v_mfma_f32_16x16x32_bf16 v[60:63], v[144:147], v[160:163], v[60:63]
	v_mfma_f32_16x16x32_bf16 v[56:59], v[152:155], v[160:163], v[56:59]
	v_mfma_f32_16x16x32_bf16 v[52:55], v[144:147], v[186:189], v[52:55]
	v_mfma_f32_16x16x32_bf16 v[48:51], v[152:155], v[186:189], v[48:51]
	v_mfma_f32_16x16x32_bf16 v[44:47], v[144:147], v[194:197], v[44:47]
	v_mfma_f32_16x16x32_bf16 v[40:43], v[152:155], v[194:197], v[40:43]
	v_mfma_f32_16x16x32_bf16 v[36:39], v[144:147], v[202:205], v[36:39]
	v_mfma_f32_16x16x32_bf16 v[32:35], v[152:155], v[202:205], v[32:35]
	v_mfma_f32_16x16x32_bf16 v[60:63], v[148:151], v[164:167], v[60:63]
	v_mfma_f32_16x16x32_bf16 v[56:59], v[156:159], v[164:167], v[56:59]
	v_mfma_f32_16x16x32_bf16 v[52:55], v[148:151], v[190:193], v[52:55]
	v_mfma_f32_16x16x32_bf16 v[48:51], v[156:159], v[190:193], v[48:51]
	s_barrier
	s_setprio 2
	v_mfma_f32_16x16x32_bf16 v[44:47], v[148:151], v[198:201], v[44:47]
	v_mfma_f32_16x16x32_bf16 v[40:43], v[156:159], v[198:201], v[40:43]
	v_mfma_f32_16x16x32_bf16 v[36:39], v[148:151], v[206:209], v[36:39]
	v_mfma_f32_16x16x32_bf16 v[32:35], v[156:159], v[206:209], v[32:35]
	s_setprio 0
	s_add_i32 s76, s62, s67
	s_add_u32 s82, s26, s8
	s_addc_u32 s83, s27, s9
	s_mov_b32 m0, s76
	ds_read_b128 v[160:163], v245 offset:16384
	ds_read_b128 v[164:167], v245 offset:17408
	ds_read_b128 v[186:189], v245 offset:18432
	ds_read_b128 v[190:193], v245 offset:19456
	ds_read_b128 v[194:197], v245 offset:20480
	ds_read_b128 v[198:201], v245 offset:21504
	ds_read_b128 v[202:205], v245 offset:22528
	ds_read_b128 v[206:209], v245 offset:23552
	global_load_lds_dwordx4 v170, s[26:27]
	s_add_i32 m0, s76, 0x2000
	s_add_u32 s76, s26, 0x80000
	s_addc_u32 s77, s27, 0
	s_add_i32 s78, s63, s67
	global_load_lds_dwordx4 v174, s[26:27]
	s_mov_b32 m0, s78
	s_add_u32 s84, s28, s8
	s_addc_u32 s85, s29, s9
	global_load_lds_dwordx4 v170, s[76:77]
	s_add_i32 m0, s78, 0x2000
	s_nop 0
	global_load_lds_dwordx4 v174, s[76:77]
	s_mov_b32 m0, s38
	s_nop 0
	global_load_lds_dwordx4 v168, s[28:29]
	s_mov_b32 m0, s39
	s_nop 0
	global_load_lds_dwordx4 v172, s[28:29]
	s_waitcnt vmcnt(8)
	s_waitcnt lgkmcnt(0)
	s_barrier
	s_setprio 1
	s_waitcnt lgkmcnt(0)
	v_mfma_f32_16x16x32_bf16 v[92:95], v[128:131], v[160:163], v[92:95]
	v_mfma_f32_16x16x32_bf16 v[88:91], v[136:139], v[160:163], v[88:91]
	v_mfma_f32_16x16x32_bf16 v[84:87], v[128:131], v[186:189], v[84:87]
	v_mfma_f32_16x16x32_bf16 v[80:83], v[136:139], v[186:189], v[80:83]
	v_mfma_f32_16x16x32_bf16 v[76:79], v[128:131], v[194:197], v[76:79]
	v_mfma_f32_16x16x32_bf16 v[72:75], v[136:139], v[194:197], v[72:75]
	v_mfma_f32_16x16x32_bf16 v[68:71], v[128:131], v[202:205], v[68:71]
	v_mfma_f32_16x16x32_bf16 v[64:67], v[136:139], v[202:205], v[64:67]
	v_mfma_f32_16x16x32_bf16 v[92:95], v[132:135], v[164:167], v[92:95]
	v_mfma_f32_16x16x32_bf16 v[88:91], v[140:143], v[164:167], v[88:91]
	v_mfma_f32_16x16x32_bf16 v[84:87], v[132:135], v[190:193], v[84:87]
	v_mfma_f32_16x16x32_bf16 v[80:83], v[140:143], v[190:193], v[80:83]
	v_mfma_f32_16x16x32_bf16 v[76:79], v[132:135], v[198:201], v[76:79]
	v_mfma_f32_16x16x32_bf16 v[72:75], v[140:143], v[198:201], v[72:75]
	v_mfma_f32_16x16x32_bf16 v[68:71], v[132:135], v[206:209], v[68:71]
	v_mfma_f32_16x16x32_bf16 v[64:67], v[140:143], v[206:209], v[64:67]
	s_setprio 0
	s_setprio 1
	v_mfma_f32_16x16x32_bf16 v[28:31], v[144:147], v[160:163], v[28:31]
	v_mfma_f32_16x16x32_bf16 v[24:27], v[152:155], v[160:163], v[24:27]
	v_mfma_f32_16x16x32_bf16 v[20:23], v[144:147], v[186:189], v[20:23]
	v_mfma_f32_16x16x32_bf16 v[16:19], v[152:155], v[186:189], v[16:19]
	v_mfma_f32_16x16x32_bf16 v[12:15], v[144:147], v[194:197], v[12:15]
	v_mfma_f32_16x16x32_bf16 v[8:11], v[152:155], v[194:197], v[8:11]
	v_mfma_f32_16x16x32_bf16 v[4:7], v[144:147], v[202:205], v[4:7]
	v_mfma_f32_16x16x32_bf16 v[0:3], v[152:155], v[202:205], v[0:3]
	v_mfma_f32_16x16x32_bf16 v[28:31], v[148:151], v[164:167], v[28:31]
	v_mfma_f32_16x16x32_bf16 v[24:27], v[156:159], v[164:167], v[24:27]
	v_mfma_f32_16x16x32_bf16 v[20:23], v[148:151], v[190:193], v[20:23]
	v_mfma_f32_16x16x32_bf16 v[16:19], v[156:159], v[190:193], v[16:19]
	s_barrier
	s_setprio 2
	v_mfma_f32_16x16x32_bf16 v[12:15], v[148:151], v[198:201], v[12:15]
	v_mfma_f32_16x16x32_bf16 v[8:11], v[156:159], v[198:201], v[8:11]
	v_mfma_f32_16x16x32_bf16 v[4:7], v[148:151], v[206:209], v[4:7]
	v_mfma_f32_16x16x32_bf16 v[0:3], v[156:159], v[206:209], v[0:3]
	s_setprio 0
	s_add_i32 s76, 0, 0x18000
	s_add_i32 s77, 0, 0x1c000
	v_add_u32_e32 v140, s76, v242
	v_add_u32_e32 v156, s77, v242
	ds_read_b128 v[128:131], v140
	ds_read_b128 v[132:135], v140 offset:1024
	ds_read_b128 v[136:139], v140 offset:2048
	ds_read_b128 v[140:143], v140 offset:3072
	ds_read_b128 v[144:147], v156
	ds_read_b128 v[148:151], v156 offset:1024
	ds_read_b128 v[152:155], v156 offset:2048
	ds_read_b128 v[156:159], v156 offset:3072
	s_add_u32 s28, s28, 0x80000
	s_addc_u32 s29, s29, 0
	s_mov_b32 m0, s40
	ds_read_b128 v[160:163], v245 offset:32768
	ds_read_b128 v[164:167], v245 offset:33792
	ds_read_b128 v[186:189], v245 offset:34816
	ds_read_b128 v[190:193], v245 offset:35840
	ds_read_b128 v[194:197], v245 offset:36864
	ds_read_b128 v[198:201], v245 offset:37888
	ds_read_b128 v[202:205], v245 offset:38912
	ds_read_b128 v[206:209], v245 offset:39936
	global_load_lds_dwordx4 v168, s[28:29]
	s_mov_b32 m0, s41
	s_nop 0
	global_load_lds_dwordx4 v172, s[28:29]
	s_waitcnt vmcnt(8)
	s_waitcnt lgkmcnt(0)
	s_barrier
	s_setprio 1
	s_waitcnt lgkmcnt(0)
	v_mfma_f32_16x16x32_bf16 v[124:127], v[128:131], v[160:163], v[124:127]
	v_mfma_f32_16x16x32_bf16 v[120:123], v[136:139], v[160:163], v[120:123]
	v_mfma_f32_16x16x32_bf16 v[116:119], v[128:131], v[186:189], v[116:119]
	v_mfma_f32_16x16x32_bf16 v[112:115], v[136:139], v[186:189], v[112:115]
	v_mfma_f32_16x16x32_bf16 v[108:111], v[128:131], v[194:197], v[108:111]
	v_mfma_f32_16x16x32_bf16 v[104:107], v[136:139], v[194:197], v[104:107]
	v_mfma_f32_16x16x32_bf16 v[100:103], v[128:131], v[202:205], v[100:103]
	v_mfma_f32_16x16x32_bf16 v[96:99], v[136:139], v[202:205], v[96:99]
	v_mfma_f32_16x16x32_bf16 v[124:127], v[132:135], v[164:167], v[124:127]
	v_mfma_f32_16x16x32_bf16 v[120:123], v[140:143], v[164:167], v[120:123]
	v_mfma_f32_16x16x32_bf16 v[116:119], v[132:135], v[190:193], v[116:119]
	v_mfma_f32_16x16x32_bf16 v[112:115], v[140:143], v[190:193], v[112:115]
	v_mfma_f32_16x16x32_bf16 v[108:111], v[132:135], v[198:201], v[108:111]
	v_mfma_f32_16x16x32_bf16 v[104:107], v[140:143], v[198:201], v[104:107]
	v_mfma_f32_16x16x32_bf16 v[100:103], v[132:135], v[206:209], v[100:103]
	v_mfma_f32_16x16x32_bf16 v[96:99], v[140:143], v[206:209], v[96:99]
	s_setprio 0
	s_setprio 1
	v_mfma_f32_16x16x32_bf16 v[60:63], v[144:147], v[160:163], v[60:63]
	v_mfma_f32_16x16x32_bf16 v[56:59], v[152:155], v[160:163], v[56:59]
	v_mfma_f32_16x16x32_bf16 v[52:55], v[144:147], v[186:189], v[52:55]
	v_mfma_f32_16x16x32_bf16 v[48:51], v[152:155], v[186:189], v[48:51]
	v_mfma_f32_16x16x32_bf16 v[44:47], v[144:147], v[194:197], v[44:47]
	v_mfma_f32_16x16x32_bf16 v[40:43], v[152:155], v[194:197], v[40:43]
	v_mfma_f32_16x16x32_bf16 v[36:39], v[144:147], v[202:205], v[36:39]
	v_mfma_f32_16x16x32_bf16 v[32:35], v[152:155], v[202:205], v[32:35]
	v_mfma_f32_16x16x32_bf16 v[60:63], v[148:151], v[164:167], v[60:63]
	v_mfma_f32_16x16x32_bf16 v[56:59], v[156:159], v[164:167], v[56:59]
	v_mfma_f32_16x16x32_bf16 v[52:55], v[148:151], v[190:193], v[52:55]
	v_mfma_f32_16x16x32_bf16 v[48:51], v[156:159], v[190:193], v[48:51]
	s_barrier
	s_setprio 2
	v_mfma_f32_16x16x32_bf16 v[44:47], v[148:151], v[198:201], v[44:47]
	v_mfma_f32_16x16x32_bf16 v[40:43], v[156:159], v[198:201], v[40:43]
	v_mfma_f32_16x16x32_bf16 v[36:39], v[148:151], v[206:209], v[36:39]
	v_mfma_f32_16x16x32_bf16 v[32:35], v[156:159], v[206:209], v[32:35]
	s_setprio 0
	s_add_i32 s28, s76, s67
	s_mov_b32 m0, s28
	ds_read_b128 v[160:163], v245 offset:49152
	ds_read_b128 v[164:167], v245 offset:50176
	ds_read_b128 v[186:189], v245 offset:51200
	ds_read_b128 v[190:193], v245 offset:52224
	ds_read_b128 v[194:197], v245 offset:53248
	ds_read_b128 v[198:201], v245 offset:54272
	ds_read_b128 v[202:205], v245 offset:55296
	ds_read_b128 v[206:209], v245 offset:56320
	global_load_lds_dwordx4 v170, s[82:83]
	s_add_i32 m0, s28, 0x2000
	s_add_u32 s26, s26, 0x80080
	s_addc_u32 s27, s27, 0
	s_add_i32 s28, s77, s67
	global_load_lds_dwordx4 v174, s[82:83]
	s_mov_b32 m0, s28
	s_nop 0
	global_load_lds_dwordx4 v170, s[26:27]
	s_add_i32 m0, s28, 0x2000
	s_nop 0
	global_load_lds_dwordx4 v174, s[26:27]
	s_mov_b32 m0, s55
	s_nop 0
	global_load_lds_dwordx4 v168, s[84:85]
	s_mov_b32 m0, s56
	s_nop 0
	global_load_lds_dwordx4 v172, s[84:85]
	s_waitcnt vmcnt(8)
	s_waitcnt lgkmcnt(0)
	s_barrier
	s_setprio 1
	s_waitcnt lgkmcnt(0)
	v_mfma_f32_16x16x32_bf16 v[92:95], v[128:131], v[160:163], v[92:95]
	v_mfma_f32_16x16x32_bf16 v[88:91], v[136:139], v[160:163], v[88:91]
	v_mfma_f32_16x16x32_bf16 v[84:87], v[128:131], v[186:189], v[84:87]
	v_mfma_f32_16x16x32_bf16 v[80:83], v[136:139], v[186:189], v[80:83]
	v_mfma_f32_16x16x32_bf16 v[76:79], v[128:131], v[194:197], v[76:79]
	v_mfma_f32_16x16x32_bf16 v[72:75], v[136:139], v[194:197], v[72:75]
	v_mfma_f32_16x16x32_bf16 v[68:71], v[128:131], v[202:205], v[68:71]
	v_mfma_f32_16x16x32_bf16 v[64:67], v[136:139], v[202:205], v[64:67]
	v_mfma_f32_16x16x32_bf16 v[92:95], v[132:135], v[164:167], v[92:95]
	v_mfma_f32_16x16x32_bf16 v[88:91], v[140:143], v[164:167], v[88:91]
	v_mfma_f32_16x16x32_bf16 v[84:87], v[132:135], v[190:193], v[84:87]
	v_mfma_f32_16x16x32_bf16 v[80:83], v[140:143], v[190:193], v[80:83]
	v_mfma_f32_16x16x32_bf16 v[76:79], v[132:135], v[198:201], v[76:79]
	v_mfma_f32_16x16x32_bf16 v[72:75], v[140:143], v[198:201], v[72:75]
	v_mfma_f32_16x16x32_bf16 v[68:71], v[132:135], v[206:209], v[68:71]
	v_mfma_f32_16x16x32_bf16 v[64:67], v[140:143], v[206:209], v[64:67]
	s_setprio 0
	s_setprio 1
	v_mfma_f32_16x16x32_bf16 v[28:31], v[144:147], v[160:163], v[28:31]
	v_mfma_f32_16x16x32_bf16 v[24:27], v[152:155], v[160:163], v[24:27]
	v_mfma_f32_16x16x32_bf16 v[20:23], v[144:147], v[186:189], v[20:23]
	v_mfma_f32_16x16x32_bf16 v[16:19], v[152:155], v[186:189], v[16:19]
	v_mfma_f32_16x16x32_bf16 v[12:15], v[144:147], v[194:197], v[12:15]
	v_mfma_f32_16x16x32_bf16 v[8:11], v[152:155], v[194:197], v[8:11]
	v_mfma_f32_16x16x32_bf16 v[4:7], v[144:147], v[202:205], v[4:7]
	v_mfma_f32_16x16x32_bf16 v[0:3], v[152:155], v[202:205], v[0:3]
	v_mfma_f32_16x16x32_bf16 v[28:31], v[148:151], v[164:167], v[28:31]
	v_mfma_f32_16x16x32_bf16 v[24:27], v[156:159], v[164:167], v[24:27]
	v_mfma_f32_16x16x32_bf16 v[20:23], v[148:151], v[190:193], v[20:23]
	v_mfma_f32_16x16x32_bf16 v[16:19], v[156:159], v[190:193], v[16:19]
	s_barrier
	s_setprio 2
	v_mfma_f32_16x16x32_bf16 v[12:15], v[148:151], v[198:201], v[12:15]
	v_mfma_f32_16x16x32_bf16 v[8:11], v[156:159], v[198:201], v[8:11]
	v_mfma_f32_16x16x32_bf16 v[4:7], v[148:151], v[206:209], v[4:7]
	v_mfma_f32_16x16x32_bf16 v[0:3], v[156:159], v[206:209], v[0:3]
	s_setprio 0
	s_add_i32 s75, s75, 2
	s_add_u32 s30, s30, 0x100
	s_addc_u32 s31, s31, 0
	s_add_u32 s24, s24, 0x100
	s_addc_u32 s25, s25, 0
	s_cmp_gt_u32 s75, 29
	s_cbranch_scc0 .LBB0_1661
	s_and_b64 vcc, exec, s[10:11]
	s_cbranch_vccz .LBB0_1664
	s_barrier

.LBB0_1979:
	ds_read_b128 v[130:133], v185
	ds_read_b128 v[134:137], v185 offset:1024
	ds_read_b128 v[138:141], v185 offset:2048
	ds_read_b128 v[142:145], v185 offset:3072
	ds_read_b128 v[146:149], v187
	ds_read_b128 v[150:153], v187 offset:1024
	ds_read_b128 v[154:157], v187 offset:2048
	ds_read_b128 v[192:195], v187 offset:3072
	s_add_u32 s30, s28, 0xfff80080
	s_addc_u32 s31, s29, -1
	s_cmp_eq_u32 s61, 28
	s_cselect_b32 s35, s6, s31
	s_cselect_b32 s34, s21, s30
	s_cselect_b32 s31, s19, s60
	s_cselect_b32 s30, s58, s59
	s_add_i32 m0, s27, 0xc000
	ds_read_b128 v[196:199], v189
	ds_read_b128 v[200:203], v189 offset:1024
	ds_read_b128 v[204:207], v189 offset:2048
	ds_read_b128 v[208:211], v189 offset:3072
	ds_read_b128 v[212:215], v189 offset:4096
	ds_read_b128 v[216:219], v189 offset:5120
	ds_read_b128 v[220:223], v189 offset:6144
	ds_read_b128 v[224:227], v189 offset:7168
	global_load_lds_dwordx4 v174, s[28:29]
	s_add_i32 m0, s27, 0xe000
	s_nop 0
	global_load_lds_dwordx4 v172, s[28:29]
	s_waitcnt vmcnt(8)
	s_waitcnt lgkmcnt(0)
	s_barrier
	s_setprio 1
	s_waitcnt lgkmcnt(0)
	v_mfma_f32_16x16x32_bf16 v[124:127], v[130:133], v[196:199], v[124:127]
	v_mfma_f32_16x16x32_bf16 v[120:123], v[138:141], v[196:199], v[120:123]
	v_mfma_f32_16x16x32_bf16 v[112:115], v[130:133], v[204:207], v[112:115]
	v_mfma_f32_16x16x32_bf16 v[104:107], v[138:141], v[204:207], v[104:107]
	v_mfma_f32_16x16x32_bf16 v[96:99], v[130:133], v[212:215], v[96:99]
	v_mfma_f32_16x16x32_bf16 v[88:91], v[138:141], v[212:215], v[88:91]
	v_mfma_f32_16x16x32_bf16 v[80:83], v[130:133], v[220:223], v[80:83]
	v_mfma_f32_16x16x32_bf16 v[72:75], v[138:141], v[220:223], v[72:75]
	v_mfma_f32_16x16x32_bf16 v[124:127], v[134:137], v[200:203], v[124:127]
	v_mfma_f32_16x16x32_bf16 v[120:123], v[142:145], v[200:203], v[120:123]
	v_mfma_f32_16x16x32_bf16 v[112:115], v[134:137], v[208:211], v[112:115]
	v_mfma_f32_16x16x32_bf16 v[104:107], v[142:145], v[208:211], v[104:107]
	v_mfma_f32_16x16x32_bf16 v[96:99], v[134:137], v[216:219], v[96:99]
	v_mfma_f32_16x16x32_bf16 v[88:91], v[142:145], v[216:219], v[88:91]
	v_mfma_f32_16x16x32_bf16 v[80:83], v[134:137], v[224:227], v[80:83]
	v_mfma_f32_16x16x32_bf16 v[72:75], v[142:145], v[224:227], v[72:75]
	s_setprio 0
	s_setprio 1
	v_mfma_f32_16x16x32_bf16 v[116:119], v[146:149], v[196:199], v[116:119]
	v_mfma_f32_16x16x32_bf16 v[108:111], v[154:157], v[196:199], v[108:111]
	v_mfma_f32_16x16x32_bf16 v[100:103], v[146:149], v[204:207], v[100:103]
	v_mfma_f32_16x16x32_bf16 v[92:95], v[154:157], v[204:207], v[92:95]
	v_mfma_f32_16x16x32_bf16 v[84:87], v[146:149], v[212:215], v[84:87]
	v_mfma_f32_16x16x32_bf16 v[76:79], v[154:157], v[212:215], v[76:79]
	v_mfma_f32_16x16x32_bf16 v[68:71], v[146:149], v[220:223], v[68:71]
	v_mfma_f32_16x16x32_bf16 v[64:67], v[154:157], v[220:223], v[64:67]
	v_mfma_f32_16x16x32_bf16 v[116:119], v[150:153], v[200:203], v[116:119]
	v_mfma_f32_16x16x32_bf16 v[108:111], v[192:195], v[200:203], v[108:111]
	v_mfma_f32_16x16x32_bf16 v[100:103], v[150:153], v[208:211], v[100:103]
	v_mfma_f32_16x16x32_bf16 v[92:95], v[192:195], v[208:211], v[92:95]
	s_barrier
	s_setprio 2
	v_mfma_f32_16x16x32_bf16 v[84:87], v[150:153], v[216:219], v[84:87]
	v_mfma_f32_16x16x32_bf16 v[76:79], v[192:195], v[216:219], v[76:79]
	v_mfma_f32_16x16x32_bf16 v[68:71], v[150:153], v[224:227], v[68:71]
	v_mfma_f32_16x16x32_bf16 v[64:67], v[192:195], v[224:227], v[64:67]
	s_setprio 0
	s_add_i32 s62, s52, s67
	s_add_u32 s70, s30, s12
	s_addc_u32 s71, s31, s13
	s_mov_b32 m0, s62
	ds_read_b128 v[196:199], v189 offset:16384
	ds_read_b128 v[200:203], v189 offset:17408
	ds_read_b128 v[204:207], v189 offset:18432
	ds_read_b128 v[208:211], v189 offset:19456
	ds_read_b128 v[212:215], v189 offset:20480
	ds_read_b128 v[216:219], v189 offset:21504
	ds_read_b128 v[220:223], v189 offset:22528
	ds_read_b128 v[224:227], v189 offset:23552
	global_load_lds_dwordx4 v162, s[30:31]
	s_add_i32 m0, s62, 0x2000
	s_add_u32 s62, s30, 0x80000
	s_addc_u32 s63, s31, 0
	s_add_i32 s64, s53, s67
	global_load_lds_dwordx4 v166, s[30:31]
	s_mov_b32 m0, s64
	s_add_u32 s72, s34, s12
	s_addc_u32 s73, s35, s13
	global_load_lds_dwordx4 v162, s[62:63]
	s_add_i32 m0, s64, 0x2000
	s_nop 0
	global_load_lds_dwordx4 v166, s[62:63]
	s_mov_b32 m0, s27
	s_nop 0
	global_load_lds_dwordx4 v160, s[34:35]
	s_mov_b32 m0, s41
	s_nop 0
	global_load_lds_dwordx4 v164, s[34:35]
	s_waitcnt vmcnt(8)
	s_waitcnt lgkmcnt(0)
	s_barrier
	s_setprio 1
	s_waitcnt lgkmcnt(0)
	v_mfma_f32_16x16x32_bf16 v[60:63], v[130:133], v[196:199], v[60:63]
	v_mfma_f32_16x16x32_bf16 v[56:59], v[138:141], v[196:199], v[56:59]
	v_mfma_f32_16x16x32_bf16 v[48:51], v[130:133], v[204:207], v[48:51]
	v_mfma_f32_16x16x32_bf16 v[40:43], v[138:141], v[204:207], v[40:43]
	v_mfma_f32_16x16x32_bf16 v[32:35], v[130:133], v[212:215], v[32:35]
	v_mfma_f32_16x16x32_bf16 v[24:27], v[138:141], v[212:215], v[24:27]
	v_mfma_f32_16x16x32_bf16 v[16:19], v[130:133], v[220:223], v[16:19]
	v_mfma_f32_16x16x32_bf16 v[8:11], v[138:141], v[220:223], v[8:11]
	v_mfma_f32_16x16x32_bf16 v[60:63], v[134:137], v[200:203], v[60:63]
	v_mfma_f32_16x16x32_bf16 v[56:59], v[142:145], v[200:203], v[56:59]
	v_mfma_f32_16x16x32_bf16 v[48:51], v[134:137], v[208:211], v[48:51]
	v_mfma_f32_16x16x32_bf16 v[40:43], v[142:145], v[208:211], v[40:43]
	v_mfma_f32_16x16x32_bf16 v[32:35], v[134:137], v[216:219], v[32:35]
	v_mfma_f32_16x16x32_bf16 v[24:27], v[142:145], v[216:219], v[24:27]
	v_mfma_f32_16x16x32_bf16 v[16:19], v[134:137], v[224:227], v[16:19]
	v_mfma_f32_16x16x32_bf16 v[8:11], v[142:145], v[224:227], v[8:11]
	s_setprio 0
	s_setprio 1
	v_mfma_f32_16x16x32_bf16 v[52:55], v[146:149], v[196:199], v[52:55]
	v_mfma_f32_16x16x32_bf16 v[44:47], v[154:157], v[196:199], v[44:47]
	v_mfma_f32_16x16x32_bf16 v[36:39], v[146:149], v[204:207], v[36:39]
	v_mfma_f32_16x16x32_bf16 v[28:31], v[154:157], v[204:207], v[28:31]
	v_mfma_f32_16x16x32_bf16 v[20:23], v[146:149], v[212:215], v[20:23]
	v_mfma_f32_16x16x32_bf16 v[12:15], v[154:157], v[212:215], v[12:15]
	v_mfma_f32_16x16x32_bf16 v[4:7], v[146:149], v[220:223], v[4:7]
	v_mfma_f32_16x16x32_bf16 v[0:3], v[154:157], v[220:223], v[0:3]
	v_mfma_f32_16x16x32_bf16 v[52:55], v[150:153], v[200:203], v[52:55]
	v_mfma_f32_16x16x32_bf16 v[44:47], v[192:195], v[200:203], v[44:47]
	v_mfma_f32_16x16x32_bf16 v[36:39], v[150:153], v[208:211], v[36:39]
	v_mfma_f32_16x16x32_bf16 v[28:31], v[192:195], v[208:211], v[28:31]
	s_barrier
	s_setprio 2
	v_mfma_f32_16x16x32_bf16 v[20:23], v[150:153], v[216:219], v[20:23]
	v_mfma_f32_16x16x32_bf16 v[12:15], v[192:195], v[216:219], v[12:15]
	v_mfma_f32_16x16x32_bf16 v[4:7], v[150:153], v[224:227], v[4:7]
	v_mfma_f32_16x16x32_bf16 v[0:3], v[192:195], v[224:227], v[0:3]
	s_setprio 0
	s_add_i32 s62, 0, 0x18000
	v_add_u32_e32 v129, s62, v181
	s_add_i32 s63, 0, 0x1c000
	ds_read_b128 v[130:133], v129
	ds_read_b128 v[134:137], v129 offset:1024
	ds_read_b128 v[138:141], v129 offset:2048
	ds_read_b128 v[142:145], v129 offset:3072
	v_add_u32_e32 v129, s63, v181
	ds_read_b128 v[146:149], v129
	ds_read_b128 v[150:153], v129 offset:1024
	ds_read_b128 v[154:157], v129 offset:2048
	ds_read_b128 v[192:195], v129 offset:3072
	s_add_u32 s34, s34, 0x80000
	s_addc_u32 s35, s35, 0
	s_mov_b32 m0, s42
	ds_read_b128 v[196:199], v189 offset:32768
	ds_read_b128 v[200:203], v189 offset:33792
	ds_read_b128 v[204:207], v189 offset:34816
	ds_read_b128 v[208:211], v189 offset:35840
	ds_read_b128 v[212:215], v189 offset:36864
	ds_read_b128 v[216:219], v189 offset:37888
	ds_read_b128 v[220:223], v189 offset:38912
	ds_read_b128 v[224:227], v189 offset:39936
	global_load_lds_dwordx4 v160, s[34:35]
	s_mov_b32 m0, s43
	s_nop 0
	global_load_lds_dwordx4 v164, s[34:35]
	s_waitcnt vmcnt(8)
	s_waitcnt lgkmcnt(0)
	s_barrier
	s_setprio 1
	s_waitcnt lgkmcnt(0)
	v_mfma_f32_16x16x32_bf16 v[124:127], v[130:133], v[196:199], v[124:127]
	v_mfma_f32_16x16x32_bf16 v[120:123], v[138:141], v[196:199], v[120:123]
	v_mfma_f32_16x16x32_bf16 v[112:115], v[130:133], v[204:207], v[112:115]
	v_mfma_f32_16x16x32_bf16 v[104:107], v[138:141], v[204:207], v[104:107]
	v_mfma_f32_16x16x32_bf16 v[96:99], v[130:133], v[212:215], v[96:99]
	v_mfma_f32_16x16x32_bf16 v[88:91], v[138:141], v[212:215], v[88:91]
	v_mfma_f32_16x16x32_bf16 v[80:83], v[130:133], v[220:223], v[80:83]
	v_mfma_f32_16x16x32_bf16 v[72:75], v[138:141], v[220:223], v[72:75]
	v_mfma_f32_16x16x32_bf16 v[124:127], v[134:137], v[200:203], v[124:127]
	v_mfma_f32_16x16x32_bf16 v[120:123], v[142:145], v[200:203], v[120:123]
	v_mfma_f32_16x16x32_bf16 v[112:115], v[134:137], v[208:211], v[112:115]
	v_mfma_f32_16x16x32_bf16 v[104:107], v[142:145], v[208:211], v[104:107]
	v_mfma_f32_16x16x32_bf16 v[96:99], v[134:137], v[216:219], v[96:99]
	v_mfma_f32_16x16x32_bf16 v[88:91], v[142:145], v[216:219], v[88:91]
	v_mfma_f32_16x16x32_bf16 v[80:83], v[134:137], v[224:227], v[80:83]
	v_mfma_f32_16x16x32_bf16 v[72:75], v[142:145], v[224:227], v[72:75]
	s_setprio 0
	s_setprio 1
	v_mfma_f32_16x16x32_bf16 v[116:119], v[146:149], v[196:199], v[116:119]
	v_mfma_f32_16x16x32_bf16 v[108:111], v[154:157], v[196:199], v[108:111]
	v_mfma_f32_16x16x32_bf16 v[100:103], v[146:149], v[204:207], v[100:103]
	v_mfma_f32_16x16x32_bf16 v[92:95], v[154:157], v[204:207], v[92:95]
	v_mfma_f32_16x16x32_bf16 v[84:87], v[146:149], v[212:215], v[84:87]
	v_mfma_f32_16x16x32_bf16 v[76:79], v[154:157], v[212:215], v[76:79]
	v_mfma_f32_16x16x32_bf16 v[68:71], v[146:149], v[220:223], v[68:71]
	v_mfma_f32_16x16x32_bf16 v[64:67], v[154:157], v[220:223], v[64:67]
	v_mfma_f32_16x16x32_bf16 v[116:119], v[150:153], v[200:203], v[116:119]
	v_mfma_f32_16x16x32_bf16 v[108:111], v[192:195], v[200:203], v[108:111]
	v_mfma_f32_16x16x32_bf16 v[100:103], v[150:153], v[208:211], v[100:103]
	v_mfma_f32_16x16x32_bf16 v[92:95], v[192:195], v[208:211], v[92:95]
	s_barrier
	s_setprio 2
	v_mfma_f32_16x16x32_bf16 v[84:87], v[150:153], v[216:219], v[84:87]
	v_mfma_f32_16x16x32_bf16 v[76:79], v[192:195], v[216:219], v[76:79]
	v_mfma_f32_16x16x32_bf16 v[68:71], v[150:153], v[224:227], v[68:71]
	v_mfma_f32_16x16x32_bf16 v[64:67], v[192:195], v[224:227], v[64:67]
	s_setprio 0
	s_add_i32 s34, s62, s67
	s_mov_b32 m0, s34
	ds_read_b128 v[196:199], v189 offset:49152
	ds_read_b128 v[200:203], v189 offset:50176
	ds_read_b128 v[204:207], v189 offset:51200
	ds_read_b128 v[208:211], v189 offset:52224
	ds_read_b128 v[212:215], v189 offset:53248
	ds_read_b128 v[216:219], v189 offset:54272
	ds_read_b128 v[220:223], v189 offset:55296
	ds_read_b128 v[224:227], v189 offset:56320
	global_load_lds_dwordx4 v162, s[70:71]
	s_add_i32 m0, s34, 0x2000
	s_add_u32 s30, s30, 0x80080
	s_addc_u32 s31, s31, 0
	s_add_i32 s34, s63, s67
	global_load_lds_dwordx4 v166, s[70:71]
	s_mov_b32 m0, s34
	s_nop 0
	global_load_lds_dwordx4 v162, s[30:31]
	s_add_i32 m0, s34, 0x2000
	s_nop 0
	global_load_lds_dwordx4 v166, s[30:31]
	s_mov_b32 m0, s44
	s_nop 0
	global_load_lds_dwordx4 v160, s[72:73]
	s_mov_b32 m0, s45
	s_nop 0
	global_load_lds_dwordx4 v164, s[72:73]
	s_waitcnt vmcnt(8)
	s_waitcnt lgkmcnt(0)
	s_barrier
	s_setprio 1
	s_waitcnt lgkmcnt(0)
	v_mfma_f32_16x16x32_bf16 v[60:63], v[130:133], v[196:199], v[60:63]
	v_mfma_f32_16x16x32_bf16 v[56:59], v[138:141], v[196:199], v[56:59]
	v_mfma_f32_16x16x32_bf16 v[48:51], v[130:133], v[204:207], v[48:51]
	v_mfma_f32_16x16x32_bf16 v[40:43], v[138:141], v[204:207], v[40:43]
	v_mfma_f32_16x16x32_bf16 v[32:35], v[130:133], v[212:215], v[32:35]
	v_mfma_f32_16x16x32_bf16 v[24:27], v[138:141], v[212:215], v[24:27]
	v_mfma_f32_16x16x32_bf16 v[16:19], v[130:133], v[220:223], v[16:19]
	v_mfma_f32_16x16x32_bf16 v[8:11], v[138:141], v[220:223], v[8:11]
	v_mfma_f32_16x16x32_bf16 v[60:63], v[134:137], v[200:203], v[60:63]
	v_mfma_f32_16x16x32_bf16 v[56:59], v[142:145], v[200:203], v[56:59]
	v_mfma_f32_16x16x32_bf16 v[48:51], v[134:137], v[208:211], v[48:51]
	v_mfma_f32_16x16x32_bf16 v[40:43], v[142:145], v[208:211], v[40:43]
	v_mfma_f32_16x16x32_bf16 v[32:35], v[134:137], v[216:219], v[32:35]
	v_mfma_f32_16x16x32_bf16 v[24:27], v[142:145], v[216:219], v[24:27]
	v_mfma_f32_16x16x32_bf16 v[16:19], v[134:137], v[224:227], v[16:19]
	v_mfma_f32_16x16x32_bf16 v[8:11], v[142:145], v[224:227], v[8:11]
	s_setprio 0
	s_setprio 1
	v_mfma_f32_16x16x32_bf16 v[52:55], v[146:149], v[196:199], v[52:55]
	v_mfma_f32_16x16x32_bf16 v[44:47], v[154:157], v[196:199], v[44:47]
	v_mfma_f32_16x16x32_bf16 v[36:39], v[146:149], v[204:207], v[36:39]
	v_mfma_f32_16x16x32_bf16 v[28:31], v[154:157], v[204:207], v[28:31]
	v_mfma_f32_16x16x32_bf16 v[20:23], v[146:149], v[212:215], v[20:23]
	v_mfma_f32_16x16x32_bf16 v[12:15], v[154:157], v[212:215], v[12:15]
	v_mfma_f32_16x16x32_bf16 v[4:7], v[146:149], v[220:223], v[4:7]
	v_mfma_f32_16x16x32_bf16 v[0:3], v[154:157], v[220:223], v[0:3]
	v_mfma_f32_16x16x32_bf16 v[52:55], v[150:153], v[200:203], v[52:55]
	v_mfma_f32_16x16x32_bf16 v[44:47], v[192:195], v[200:203], v[44:47]
	v_mfma_f32_16x16x32_bf16 v[36:39], v[150:153], v[208:211], v[36:39]
	v_mfma_f32_16x16x32_bf16 v[28:31], v[192:195], v[208:211], v[28:31]
	s_barrier
	s_setprio 2
	v_mfma_f32_16x16x32_bf16 v[20:23], v[150:153], v[216:219], v[20:23]
	v_mfma_f32_16x16x32_bf16 v[12:15], v[192:195], v[216:219], v[12:15]
	v_mfma_f32_16x16x32_bf16 v[4:7], v[150:153], v[224:227], v[4:7]
	v_mfma_f32_16x16x32_bf16 v[0:3], v[192:195], v[224:227], v[0:3]
	s_setprio 0
	s_add_i32 s61, s61, 2
	s_add_u32 s59, s59, 0x100
	s_addc_u32 s60, s60, 0
	s_add_u32 s28, s28, 0x100
	s_addc_u32 s29, s29, 0
	s_cmp_gt_u32 s61, 29
	s_cbranch_scc0 .LBB0_1979
	s_and_b64 vcc, exec, s[14:15]
	s_cbranch_vccz .LBB0_1982
	s_barrier

.LBB0_2924:
	ds_read_b128 v[124:127], v163
	ds_read_b128 v[156:159], v163 offset:1024
	ds_read_b128 v[170:173], v163 offset:2048
	ds_read_b128 v[174:177], v163 offset:3072
	ds_read_b128 v[178:181], v165
	ds_read_b128 v[182:185], v165 offset:1024
	ds_read_b128 v[186:189], v165 offset:2048
	ds_read_b128 v[190:193], v165 offset:3072
	s_add_u32 s26, s24, 0xfff80080
	s_addc_u32 s27, s25, -1
	s_cmp_eq_u32 s56, 28
	s_cselect_b32 s29, s17, s27
	s_cselect_b32 s28, s52, s26
	s_cselect_b32 s27, s15, s55
	s_cselect_b32 s26, s53, s54
	s_add_i32 m0, s23, 0xc000
	ds_read_b128 v[194:197], v167
	ds_read_b128 v[198:201], v167 offset:1024
	ds_read_b128 v[202:205], v167 offset:2048
	ds_read_b128 v[206:209], v167 offset:3072
	ds_read_b128 v[210:213], v167 offset:4096
	ds_read_b128 v[214:217], v167 offset:5120
	ds_read_b128 v[218:221], v167 offset:6144
	ds_read_b128 v[222:225], v167 offset:7168
	global_load_lds_dwordx4 v148, s[24:25]
	s_add_i32 m0, s23, 0xe000
	s_nop 0
	global_load_lds_dwordx4 v146, s[24:25]
	s_waitcnt vmcnt(8)
	s_waitcnt lgkmcnt(0)
	s_barrier
	s_setprio 1
	s_waitcnt lgkmcnt(0)
	v_mfma_f32_16x16x32_bf16 v[132:135], v[124:127], v[194:197], v[132:135]
	v_mfma_f32_16x16x32_bf16 v[120:123], v[170:173], v[194:197], v[120:123]
	v_mfma_f32_16x16x32_bf16 v[108:111], v[124:127], v[202:205], v[108:111]
	v_mfma_f32_16x16x32_bf16 v[100:103], v[170:173], v[202:205], v[100:103]
	v_mfma_f32_16x16x32_bf16 v[92:95], v[124:127], v[210:213], v[92:95]
	v_mfma_f32_16x16x32_bf16 v[84:87], v[170:173], v[210:213], v[84:87]
	v_mfma_f32_16x16x32_bf16 v[76:79], v[124:127], v[218:221], v[76:79]
	v_mfma_f32_16x16x32_bf16 v[68:71], v[170:173], v[218:221], v[68:71]
	v_mfma_f32_16x16x32_bf16 v[132:135], v[156:159], v[198:201], v[132:135]
	v_mfma_f32_16x16x32_bf16 v[120:123], v[174:177], v[198:201], v[120:123]
	v_mfma_f32_16x16x32_bf16 v[108:111], v[156:159], v[206:209], v[108:111]
	v_mfma_f32_16x16x32_bf16 v[100:103], v[174:177], v[206:209], v[100:103]
	v_mfma_f32_16x16x32_bf16 v[92:95], v[156:159], v[214:217], v[92:95]
	v_mfma_f32_16x16x32_bf16 v[84:87], v[174:177], v[214:217], v[84:87]
	v_mfma_f32_16x16x32_bf16 v[76:79], v[156:159], v[222:225], v[76:79]
	v_mfma_f32_16x16x32_bf16 v[68:71], v[174:177], v[222:225], v[68:71]
	s_setprio 0
	s_setprio 1
	v_mfma_f32_16x16x32_bf16 v[128:131], v[178:181], v[194:197], v[128:131]
	v_mfma_f32_16x16x32_bf16 v[114:117], v[186:189], v[194:197], v[116:119]
	v_mfma_f32_16x16x32_bf16 v[104:107], v[178:181], v[202:205], v[104:107]
	v_mfma_f32_16x16x32_bf16 v[96:99], v[186:189], v[202:205], v[96:99]
	v_mfma_f32_16x16x32_bf16 v[88:91], v[178:181], v[210:213], v[88:91]
	v_mfma_f32_16x16x32_bf16 v[80:83], v[186:189], v[210:213], v[80:83]
	v_mfma_f32_16x16x32_bf16 v[72:75], v[178:181], v[218:221], v[72:75]
	v_mfma_f32_16x16x32_bf16 v[64:67], v[186:189], v[218:221], v[64:67]
	v_mfma_f32_16x16x32_bf16 v[128:131], v[182:185], v[198:201], v[128:131]
	v_mfma_f32_16x16x32_bf16 v[114:117], v[190:193], v[198:201], v[114:117]
	v_mfma_f32_16x16x32_bf16 v[104:107], v[182:185], v[206:209], v[104:107]
	v_mfma_f32_16x16x32_bf16 v[96:99], v[190:193], v[206:209], v[96:99]
	s_barrier
	s_setprio 2
	v_mfma_f32_16x16x32_bf16 v[88:91], v[182:185], v[214:217], v[88:91]
	v_mfma_f32_16x16x32_bf16 v[80:83], v[190:193], v[214:217], v[80:83]
	v_mfma_f32_16x16x32_bf16 v[72:75], v[182:185], v[222:225], v[72:75]
	v_mfma_f32_16x16x32_bf16 v[64:67], v[190:193], v[222:225], v[64:67]
	s_setprio 0
	s_add_i32 s57, s48, s67
	s_add_u32 s60, s26, s10
	s_addc_u32 s61, s27, s11
	s_mov_b32 m0, s57
	ds_read_b128 v[194:197], v167 offset:16384
	ds_read_b128 v[198:201], v167 offset:17408
	ds_read_b128 v[202:205], v167 offset:18432
	ds_read_b128 v[206:209], v167 offset:19456
	ds_read_b128 v[210:213], v167 offset:20480
	ds_read_b128 v[214:217], v167 offset:21504
	ds_read_b128 v[218:221], v167 offset:22528
	ds_read_b128 v[222:225], v167 offset:23552
	global_load_lds_dwordx4 v138, s[26:27]
	s_add_i32 m0, s57, 0x2000
	s_add_u32 s58, s26, 0x80000
	s_addc_u32 s59, s27, 0
	s_add_i32 s57, s49, s67
	global_load_lds_dwordx4 v142, s[26:27]
	s_mov_b32 m0, s57
	s_add_u32 s62, s28, s10
	s_addc_u32 s63, s29, s11
	global_load_lds_dwordx4 v138, s[58:59]
	s_add_i32 m0, s57, 0x2000
	s_nop 0
	global_load_lds_dwordx4 v142, s[58:59]
	s_mov_b32 m0, s23
	s_nop 0
	global_load_lds_dwordx4 v136, s[28:29]
	s_mov_b32 m0, s37
	s_nop 0
	global_load_lds_dwordx4 v140, s[28:29]
	s_waitcnt vmcnt(8)
	s_waitcnt lgkmcnt(0)
	s_barrier
	s_setprio 1
	s_waitcnt lgkmcnt(0)
	v_mfma_f32_16x16x32_bf16 v[60:63], v[124:127], v[194:197], v[60:63]
	v_mfma_f32_16x16x32_bf16 v[52:55], v[170:173], v[194:197], v[52:55]
	v_mfma_f32_16x16x32_bf16 v[44:47], v[124:127], v[202:205], v[44:47]
	v_mfma_f32_16x16x32_bf16 v[36:39], v[170:173], v[202:205], v[36:39]
	v_mfma_f32_16x16x32_bf16 v[28:31], v[124:127], v[210:213], v[28:31]
	v_mfma_f32_16x16x32_bf16 v[20:23], v[170:173], v[210:213], v[20:23]
	v_mfma_f32_16x16x32_bf16 v[12:15], v[124:127], v[218:221], v[12:15]
	v_mfma_f32_16x16x32_bf16 v[4:7], v[170:173], v[218:221], v[4:7]
	v_mfma_f32_16x16x32_bf16 v[60:63], v[156:159], v[198:201], v[60:63]
	v_mfma_f32_16x16x32_bf16 v[52:55], v[174:177], v[198:201], v[52:55]
	v_mfma_f32_16x16x32_bf16 v[44:47], v[156:159], v[206:209], v[44:47]
	v_mfma_f32_16x16x32_bf16 v[36:39], v[174:177], v[206:209], v[36:39]
	v_mfma_f32_16x16x32_bf16 v[28:31], v[156:159], v[214:217], v[28:31]
	v_mfma_f32_16x16x32_bf16 v[20:23], v[174:177], v[214:217], v[20:23]
	v_mfma_f32_16x16x32_bf16 v[12:15], v[156:159], v[222:225], v[12:15]
	v_mfma_f32_16x16x32_bf16 v[4:7], v[174:177], v[222:225], v[4:7]
	s_setprio 0
	s_setprio 1
	v_mfma_f32_16x16x32_bf16 v[56:59], v[178:181], v[194:197], v[56:59]
	v_mfma_f32_16x16x32_bf16 v[48:51], v[186:189], v[194:197], v[48:51]
	v_mfma_f32_16x16x32_bf16 v[40:43], v[178:181], v[202:205], v[40:43]
	v_mfma_f32_16x16x32_bf16 v[32:35], v[186:189], v[202:205], v[32:35]
	v_mfma_f32_16x16x32_bf16 v[24:27], v[178:181], v[210:213], v[24:27]
	v_mfma_f32_16x16x32_bf16 v[16:19], v[186:189], v[210:213], v[16:19]
	v_mfma_f32_16x16x32_bf16 v[8:11], v[178:181], v[218:221], v[8:11]
	v_mfma_f32_16x16x32_bf16 v[0:3], v[186:189], v[218:221], v[0:3]
	v_mfma_f32_16x16x32_bf16 v[56:59], v[182:185], v[198:201], v[56:59]
	v_mfma_f32_16x16x32_bf16 v[48:51], v[190:193], v[198:201], v[48:51]
	v_mfma_f32_16x16x32_bf16 v[40:43], v[182:185], v[206:209], v[40:43]
	v_mfma_f32_16x16x32_bf16 v[32:35], v[190:193], v[206:209], v[32:35]
	s_barrier
	s_setprio 2
	v_mfma_f32_16x16x32_bf16 v[24:27], v[182:185], v[214:217], v[24:27]
	v_mfma_f32_16x16x32_bf16 v[16:19], v[190:193], v[214:217], v[16:19]
	v_mfma_f32_16x16x32_bf16 v[8:11], v[182:185], v[222:225], v[8:11]
	v_mfma_f32_16x16x32_bf16 v[0:3], v[190:193], v[222:225], v[0:3]
	s_setprio 0
	s_add_i32 s57, 0, 0x18000
	v_add_u32_e32 v113, s57, v155
	s_add_i32 s58, 0, 0x1c000
	ds_read_b128 v[124:127], v113
	ds_read_b128 v[156:159], v113 offset:1024
	ds_read_b128 v[170:173], v113 offset:2048
	ds_read_b128 v[174:177], v113 offset:3072
	v_add_u32_e32 v113, s58, v155
	ds_read_b128 v[178:181], v113
	ds_read_b128 v[182:185], v113 offset:1024
	ds_read_b128 v[186:189], v113 offset:2048
	ds_read_b128 v[190:193], v113 offset:3072
	s_add_u32 s28, s28, 0x80000
	s_addc_u32 s29, s29, 0
	s_mov_b32 m0, s38
	ds_read_b128 v[194:197], v167 offset:32768
	ds_read_b128 v[198:201], v167 offset:33792
	ds_read_b128 v[202:205], v167 offset:34816
	ds_read_b128 v[206:209], v167 offset:35840
	ds_read_b128 v[210:213], v167 offset:36864
	ds_read_b128 v[214:217], v167 offset:37888
	ds_read_b128 v[218:221], v167 offset:38912
	ds_read_b128 v[222:225], v167 offset:39936
	global_load_lds_dwordx4 v136, s[28:29]
	s_mov_b32 m0, s39
	s_nop 0
	global_load_lds_dwordx4 v140, s[28:29]
	s_waitcnt vmcnt(8)
	s_waitcnt lgkmcnt(0)
	s_barrier
	s_setprio 1
	s_waitcnt lgkmcnt(0)
	v_mfma_f32_16x16x32_bf16 v[132:135], v[124:127], v[194:197], v[132:135]
	v_mfma_f32_16x16x32_bf16 v[118:121], v[170:173], v[194:197], v[120:123]
	v_mfma_f32_16x16x32_bf16 v[108:111], v[124:127], v[202:205], v[108:111]
	v_mfma_f32_16x16x32_bf16 v[100:103], v[170:173], v[202:205], v[100:103]
	v_mfma_f32_16x16x32_bf16 v[92:95], v[124:127], v[210:213], v[92:95]
	v_mfma_f32_16x16x32_bf16 v[84:87], v[170:173], v[210:213], v[84:87]
	v_mfma_f32_16x16x32_bf16 v[76:79], v[124:127], v[218:221], v[76:79]
	v_mfma_f32_16x16x32_bf16 v[68:71], v[170:173], v[218:221], v[68:71]
	v_mfma_f32_16x16x32_bf16 v[132:135], v[156:159], v[198:201], v[132:135]
	v_mfma_f32_16x16x32_bf16 v[120:123], v[174:177], v[198:201], v[118:121]
	v_mfma_f32_16x16x32_bf16 v[108:111], v[156:159], v[206:209], v[108:111]
	v_mfma_f32_16x16x32_bf16 v[100:103], v[174:177], v[206:209], v[100:103]
	v_mfma_f32_16x16x32_bf16 v[92:95], v[156:159], v[214:217], v[92:95]
	v_mfma_f32_16x16x32_bf16 v[84:87], v[174:177], v[214:217], v[84:87]
	v_mfma_f32_16x16x32_bf16 v[76:79], v[156:159], v[222:225], v[76:79]
	v_mfma_f32_16x16x32_bf16 v[68:71], v[174:177], v[222:225], v[68:71]
	s_setprio 0
	s_setprio 1
	v_mfma_f32_16x16x32_bf16 v[128:131], v[178:181], v[194:197], v[128:131]
	v_mfma_f32_16x16x32_bf16 v[114:117], v[186:189], v[194:197], v[114:117]
	v_mfma_f32_16x16x32_bf16 v[104:107], v[178:181], v[202:205], v[104:107]
	v_mfma_f32_16x16x32_bf16 v[96:99], v[186:189], v[202:205], v[96:99]
	v_mfma_f32_16x16x32_bf16 v[88:91], v[178:181], v[210:213], v[88:91]
	v_mfma_f32_16x16x32_bf16 v[80:83], v[186:189], v[210:213], v[80:83]
	v_mfma_f32_16x16x32_bf16 v[72:75], v[178:181], v[218:221], v[72:75]
	v_mfma_f32_16x16x32_bf16 v[64:67], v[186:189], v[218:221], v[64:67]
	v_mfma_f32_16x16x32_bf16 v[128:131], v[182:185], v[198:201], v[128:131]
	v_mfma_f32_16x16x32_bf16 v[116:119], v[190:193], v[198:201], v[114:117]
	v_mfma_f32_16x16x32_bf16 v[104:107], v[182:185], v[206:209], v[104:107]
	v_mfma_f32_16x16x32_bf16 v[96:99], v[190:193], v[206:209], v[96:99]
	s_barrier
	s_setprio 2
	v_mfma_f32_16x16x32_bf16 v[88:91], v[182:185], v[214:217], v[88:91]
	v_mfma_f32_16x16x32_bf16 v[80:83], v[190:193], v[214:217], v[80:83]
	v_mfma_f32_16x16x32_bf16 v[72:75], v[182:185], v[222:225], v[72:75]
	v_mfma_f32_16x16x32_bf16 v[64:67], v[190:193], v[222:225], v[64:67]
	s_setprio 0
	s_add_i32 s28, s57, s67
	s_mov_b32 m0, s28
	ds_read_b128 v[194:197], v167 offset:49152
	ds_read_b128 v[198:201], v167 offset:50176
	ds_read_b128 v[202:205], v167 offset:51200
	ds_read_b128 v[206:209], v167 offset:52224
	ds_read_b128 v[210:213], v167 offset:53248
	ds_read_b128 v[214:217], v167 offset:54272
	ds_read_b128 v[218:221], v167 offset:55296
	ds_read_b128 v[222:225], v167 offset:56320
	global_load_lds_dwordx4 v138, s[60:61]
	s_add_i32 m0, s28, 0x2000
	s_add_u32 s26, s26, 0x80080
	s_addc_u32 s27, s27, 0
	s_add_i32 s28, s58, s67
	global_load_lds_dwordx4 v142, s[60:61]
	s_mov_b32 m0, s28
	s_nop 0
	global_load_lds_dwordx4 v138, s[26:27]
	s_add_i32 m0, s28, 0x2000
	s_nop 0
	global_load_lds_dwordx4 v142, s[26:27]
	s_mov_b32 m0, s41
	s_nop 0
	global_load_lds_dwordx4 v136, s[62:63]
	s_mov_b32 m0, s42
	s_nop 0
	global_load_lds_dwordx4 v140, s[62:63]
	s_waitcnt vmcnt(8)
	s_waitcnt lgkmcnt(0)
	s_barrier
	s_setprio 1
	s_waitcnt lgkmcnt(0)
	v_mfma_f32_16x16x32_bf16 v[60:63], v[124:127], v[194:197], v[60:63]
	v_mfma_f32_16x16x32_bf16 v[52:55], v[170:173], v[194:197], v[52:55]
	v_mfma_f32_16x16x32_bf16 v[44:47], v[124:127], v[202:205], v[44:47]
	v_mfma_f32_16x16x32_bf16 v[36:39], v[170:173], v[202:205], v[36:39]
	v_mfma_f32_16x16x32_bf16 v[28:31], v[124:127], v[210:213], v[28:31]
	v_mfma_f32_16x16x32_bf16 v[20:23], v[170:173], v[210:213], v[20:23]
	v_mfma_f32_16x16x32_bf16 v[12:15], v[124:127], v[218:221], v[12:15]
	v_mfma_f32_16x16x32_bf16 v[4:7], v[170:173], v[218:221], v[4:7]
	v_mfma_f32_16x16x32_bf16 v[60:63], v[156:159], v[198:201], v[60:63]
	v_mfma_f32_16x16x32_bf16 v[52:55], v[174:177], v[198:201], v[52:55]
	v_mfma_f32_16x16x32_bf16 v[44:47], v[156:159], v[206:209], v[44:47]
	v_mfma_f32_16x16x32_bf16 v[36:39], v[174:177], v[206:209], v[36:39]
	v_mfma_f32_16x16x32_bf16 v[28:31], v[156:159], v[214:217], v[28:31]
	v_mfma_f32_16x16x32_bf16 v[20:23], v[174:177], v[214:217], v[20:23]
	v_mfma_f32_16x16x32_bf16 v[12:15], v[156:159], v[222:225], v[12:15]
	v_mfma_f32_16x16x32_bf16 v[4:7], v[174:177], v[222:225], v[4:7]
	s_setprio 0
	s_setprio 1
	v_mfma_f32_16x16x32_bf16 v[56:59], v[178:181], v[194:197], v[56:59]
	v_mfma_f32_16x16x32_bf16 v[48:51], v[186:189], v[194:197], v[48:51]
	v_mfma_f32_16x16x32_bf16 v[40:43], v[178:181], v[202:205], v[40:43]
	v_mfma_f32_16x16x32_bf16 v[32:35], v[186:189], v[202:205], v[32:35]
	v_mfma_f32_16x16x32_bf16 v[24:27], v[178:181], v[210:213], v[24:27]
	v_mfma_f32_16x16x32_bf16 v[16:19], v[186:189], v[210:213], v[16:19]
	v_mfma_f32_16x16x32_bf16 v[8:11], v[178:181], v[218:221], v[8:11]
	v_mfma_f32_16x16x32_bf16 v[0:3], v[186:189], v[218:221], v[0:3]
	v_mfma_f32_16x16x32_bf16 v[56:59], v[182:185], v[198:201], v[56:59]
	v_mfma_f32_16x16x32_bf16 v[48:51], v[190:193], v[198:201], v[48:51]
	v_mfma_f32_16x16x32_bf16 v[40:43], v[182:185], v[206:209], v[40:43]
	v_mfma_f32_16x16x32_bf16 v[32:35], v[190:193], v[206:209], v[32:35]
	s_barrier
	s_setprio 2
	v_mfma_f32_16x16x32_bf16 v[24:27], v[182:185], v[214:217], v[24:27]
	v_mfma_f32_16x16x32_bf16 v[16:19], v[190:193], v[214:217], v[16:19]
	v_mfma_f32_16x16x32_bf16 v[8:11], v[182:185], v[222:225], v[8:11]
	v_mfma_f32_16x16x32_bf16 v[0:3], v[190:193], v[222:225], v[0:3]
	s_setprio 0
	s_add_i32 s56, s56, 2
	s_add_u32 s54, s54, 0x100
	s_addc_u32 s55, s55, 0
	s_add_u32 s24, s24, 0x100
	s_addc_u32 s25, s25, 0
	s_cmp_gt_u32 s56, 29
	s_cbranch_scc0 .LBB0_2924
	s_and_b64 vcc, exec, s[12:13]
	s_cbranch_vccz .LBB0_2927
	s_barrier

.LBB0_3122:
	ds_read_b128 v[130:133], v177
	ds_read_b128 v[134:137], v177 offset:1024
	ds_read_b128 v[138:141], v177 offset:2048
	ds_read_b128 v[142:145], v177 offset:3072
	ds_read_b128 v[146:149], v179
	ds_read_b128 v[186:189], v179 offset:1024
	ds_read_b128 v[190:193], v179 offset:2048
	ds_read_b128 v[194:197], v179 offset:3072
	s_add_u32 s30, s28, 0xfff80080
	s_addc_u32 s31, s29, -1
	s_cmp_eq_u32 s72, 28
	s_cselect_b32 s35, s6, s31
	s_cselect_b32 s34, s21, s30
	s_cselect_b32 s31, s19, s71
	s_cselect_b32 s30, s27, s70
	s_add_i32 m0, s41, 0xc000
	ds_read_b128 v[198:201], v181
	ds_read_b128 v[202:205], v181 offset:1024
	ds_read_b128 v[206:209], v181 offset:2048
	ds_read_b128 v[210:213], v181 offset:3072
	ds_read_b128 v[214:217], v181 offset:4096
	ds_read_b128 v[218:221], v181 offset:5120
	ds_read_b128 v[222:225], v181 offset:6144
	ds_read_b128 v[226:229], v181 offset:7168
	global_load_lds_dwordx4 v166, s[28:29]
	s_add_i32 m0, s41, 0xe000
	s_nop 0
	global_load_lds_dwordx4 v164, s[28:29]
	s_waitcnt vmcnt(8)
	s_waitcnt lgkmcnt(0)
	s_barrier
	s_setprio 1
	s_waitcnt lgkmcnt(0)
	v_mfma_f32_16x16x32_bf16 v[124:127], v[130:133], v[198:201], v[124:127]
	v_mfma_f32_16x16x32_bf16 v[120:123], v[138:141], v[198:201], v[120:123]
	v_mfma_f32_16x16x32_bf16 v[108:111], v[130:133], v[206:209], v[108:111]
	v_mfma_f32_16x16x32_bf16 v[100:103], v[138:141], v[206:209], v[100:103]
	v_mfma_f32_16x16x32_bf16 v[92:95], v[130:133], v[214:217], v[92:95]
	v_mfma_f32_16x16x32_bf16 v[84:87], v[138:141], v[214:217], v[84:87]
	v_mfma_f32_16x16x32_bf16 v[76:79], v[130:133], v[222:225], v[76:79]
	v_mfma_f32_16x16x32_bf16 v[68:71], v[138:141], v[222:225], v[68:71]
	v_mfma_f32_16x16x32_bf16 v[124:127], v[134:137], v[202:205], v[124:127]
	v_mfma_f32_16x16x32_bf16 v[120:123], v[142:145], v[202:205], v[120:123]
	v_mfma_f32_16x16x32_bf16 v[108:111], v[134:137], v[210:213], v[108:111]
	v_mfma_f32_16x16x32_bf16 v[100:103], v[142:145], v[210:213], v[100:103]
	v_mfma_f32_16x16x32_bf16 v[92:95], v[134:137], v[218:221], v[92:95]
	v_mfma_f32_16x16x32_bf16 v[84:87], v[142:145], v[218:221], v[84:87]
	v_mfma_f32_16x16x32_bf16 v[76:79], v[134:137], v[226:229], v[76:79]
	v_mfma_f32_16x16x32_bf16 v[68:71], v[142:145], v[226:229], v[68:71]
	s_setprio 0
	s_setprio 1
	v_mfma_f32_16x16x32_bf16 v[116:119], v[146:149], v[198:201], v[116:119]
	v_mfma_f32_16x16x32_bf16 v[112:115], v[190:193], v[198:201], v[112:115]
	v_mfma_f32_16x16x32_bf16 v[104:107], v[146:149], v[206:209], v[104:107]
	v_mfma_f32_16x16x32_bf16 v[96:99], v[190:193], v[206:209], v[96:99]
	v_mfma_f32_16x16x32_bf16 v[88:91], v[146:149], v[214:217], v[88:91]
	v_mfma_f32_16x16x32_bf16 v[80:83], v[190:193], v[214:217], v[80:83]
	v_mfma_f32_16x16x32_bf16 v[72:75], v[146:149], v[222:225], v[72:75]
	v_mfma_f32_16x16x32_bf16 v[64:67], v[190:193], v[222:225], v[64:67]
	v_mfma_f32_16x16x32_bf16 v[116:119], v[186:189], v[202:205], v[116:119]
	v_mfma_f32_16x16x32_bf16 v[112:115], v[194:197], v[202:205], v[112:115]
	v_mfma_f32_16x16x32_bf16 v[104:107], v[186:189], v[210:213], v[104:107]
	v_mfma_f32_16x16x32_bf16 v[96:99], v[194:197], v[210:213], v[96:99]
	s_barrier
	s_setprio 2
	v_mfma_f32_16x16x32_bf16 v[88:91], v[186:189], v[218:221], v[88:91]
	v_mfma_f32_16x16x32_bf16 v[80:83], v[194:197], v[218:221], v[80:83]
	v_mfma_f32_16x16x32_bf16 v[72:75], v[186:189], v[226:229], v[72:75]
	v_mfma_f32_16x16x32_bf16 v[64:67], v[194:197], v[226:229], v[64:67]
	s_setprio 0
	s_add_i32 s73, s56, s67
	s_add_u32 s76, s30, s12
	s_addc_u32 s77, s31, s13
	s_mov_b32 m0, s73
	ds_read_b128 v[198:201], v181 offset:16384
	ds_read_b128 v[202:205], v181 offset:17408
	ds_read_b128 v[206:209], v181 offset:18432
	ds_read_b128 v[210:213], v181 offset:19456
	ds_read_b128 v[214:217], v181 offset:20480
	ds_read_b128 v[218:221], v181 offset:21504
	ds_read_b128 v[222:225], v181 offset:22528
	ds_read_b128 v[226:229], v181 offset:23552
	global_load_lds_dwordx4 v154, s[30:31]
	s_add_i32 m0, s73, 0x2000
	s_add_u32 s74, s30, 0x80000
	s_addc_u32 s75, s31, 0
	s_add_i32 s73, s57, s67
	global_load_lds_dwordx4 v158, s[30:31]
	s_mov_b32 m0, s73
	s_add_u32 s78, s34, s12
	s_addc_u32 s79, s35, s13
	global_load_lds_dwordx4 v154, s[74:75]
	s_add_i32 m0, s73, 0x2000
	s_nop 0
	global_load_lds_dwordx4 v158, s[74:75]
	s_mov_b32 m0, s41
	s_nop 0
	global_load_lds_dwordx4 v152, s[34:35]
	s_mov_b32 m0, s42
	s_nop 0
	global_load_lds_dwordx4 v156, s[34:35]
	s_waitcnt vmcnt(8)
	s_waitcnt lgkmcnt(0)
	s_barrier
	s_setprio 1
	s_waitcnt lgkmcnt(0)
	v_mfma_f32_16x16x32_bf16 v[60:63], v[130:133], v[198:201], v[60:63]
	v_mfma_f32_16x16x32_bf16 v[52:55], v[138:141], v[198:201], v[52:55]
	v_mfma_f32_16x16x32_bf16 v[44:47], v[130:133], v[206:209], v[44:47]
	v_mfma_f32_16x16x32_bf16 v[36:39], v[138:141], v[206:209], v[36:39]
	v_mfma_f32_16x16x32_bf16 v[28:31], v[130:133], v[214:217], v[28:31]
	v_mfma_f32_16x16x32_bf16 v[20:23], v[138:141], v[214:217], v[20:23]
	v_mfma_f32_16x16x32_bf16 v[12:15], v[130:133], v[222:225], v[12:15]
	v_mfma_f32_16x16x32_bf16 v[4:7], v[138:141], v[222:225], v[4:7]
	v_mfma_f32_16x16x32_bf16 v[60:63], v[134:137], v[202:205], v[60:63]
	v_mfma_f32_16x16x32_bf16 v[52:55], v[142:145], v[202:205], v[52:55]
	v_mfma_f32_16x16x32_bf16 v[44:47], v[134:137], v[210:213], v[44:47]
	v_mfma_f32_16x16x32_bf16 v[36:39], v[142:145], v[210:213], v[36:39]
	v_mfma_f32_16x16x32_bf16 v[28:31], v[134:137], v[218:221], v[28:31]
	v_mfma_f32_16x16x32_bf16 v[20:23], v[142:145], v[218:221], v[20:23]
	v_mfma_f32_16x16x32_bf16 v[12:15], v[134:137], v[226:229], v[12:15]
	v_mfma_f32_16x16x32_bf16 v[4:7], v[142:145], v[226:229], v[4:7]
	s_setprio 0
	s_setprio 1
	v_mfma_f32_16x16x32_bf16 v[56:59], v[146:149], v[198:201], v[56:59]
	v_mfma_f32_16x16x32_bf16 v[48:51], v[190:193], v[198:201], v[48:51]
	v_mfma_f32_16x16x32_bf16 v[40:43], v[146:149], v[206:209], v[40:43]
	v_mfma_f32_16x16x32_bf16 v[32:35], v[190:193], v[206:209], v[32:35]
	v_mfma_f32_16x16x32_bf16 v[24:27], v[146:149], v[214:217], v[24:27]
	v_mfma_f32_16x16x32_bf16 v[16:19], v[190:193], v[214:217], v[16:19]
	v_mfma_f32_16x16x32_bf16 v[8:11], v[146:149], v[222:225], v[8:11]
	v_mfma_f32_16x16x32_bf16 v[0:3], v[190:193], v[222:225], v[0:3]
	v_mfma_f32_16x16x32_bf16 v[56:59], v[186:189], v[202:205], v[56:59]
	v_mfma_f32_16x16x32_bf16 v[48:51], v[194:197], v[202:205], v[48:51]
	v_mfma_f32_16x16x32_bf16 v[40:43], v[186:189], v[210:213], v[40:43]
	v_mfma_f32_16x16x32_bf16 v[32:35], v[194:197], v[210:213], v[32:35]
	s_barrier
	s_setprio 2
	v_mfma_f32_16x16x32_bf16 v[24:27], v[186:189], v[218:221], v[24:27]
	v_mfma_f32_16x16x32_bf16 v[16:19], v[194:197], v[218:221], v[16:19]
	v_mfma_f32_16x16x32_bf16 v[8:11], v[186:189], v[226:229], v[8:11]
	v_mfma_f32_16x16x32_bf16 v[0:3], v[194:197], v[226:229], v[0:3]
	s_setprio 0
	s_add_i32 s73, 0, 0x18000
	v_add_u32_e32 v129, s73, v173
	s_add_i32 s74, 0, 0x1c000
	ds_read_b128 v[130:133], v129
	ds_read_b128 v[134:137], v129 offset:1024
	ds_read_b128 v[138:141], v129 offset:2048
	ds_read_b128 v[142:145], v129 offset:3072
	v_add_u32_e32 v129, s74, v173
	ds_read_b128 v[146:149], v129
	ds_read_b128 v[186:189], v129 offset:1024
	ds_read_b128 v[190:193], v129 offset:2048
	ds_read_b128 v[194:197], v129 offset:3072
	s_add_u32 s34, s34, 0x80000
	s_addc_u32 s35, s35, 0
	s_mov_b32 m0, s43
	ds_read_b128 v[198:201], v181 offset:32768
	ds_read_b128 v[202:205], v181 offset:33792
	ds_read_b128 v[206:209], v181 offset:34816
	ds_read_b128 v[210:213], v181 offset:35840
	ds_read_b128 v[214:217], v181 offset:36864
	ds_read_b128 v[218:221], v181 offset:37888
	ds_read_b128 v[222:225], v181 offset:38912
	ds_read_b128 v[226:229], v181 offset:39936
	global_load_lds_dwordx4 v152, s[34:35]
	s_mov_b32 m0, s44
	s_nop 0
	global_load_lds_dwordx4 v156, s[34:35]
	s_waitcnt vmcnt(8)
	s_waitcnt lgkmcnt(0)
	s_barrier
	s_setprio 1
	s_waitcnt lgkmcnt(0)
	v_mfma_f32_16x16x32_bf16 v[124:127], v[130:133], v[198:201], v[124:127]
	v_mfma_f32_16x16x32_bf16 v[120:123], v[138:141], v[198:201], v[120:123]
	v_mfma_f32_16x16x32_bf16 v[108:111], v[130:133], v[206:209], v[108:111]
	v_mfma_f32_16x16x32_bf16 v[100:103], v[138:141], v[206:209], v[100:103]
	v_mfma_f32_16x16x32_bf16 v[92:95], v[130:133], v[214:217], v[92:95]
	v_mfma_f32_16x16x32_bf16 v[84:87], v[138:141], v[214:217], v[84:87]
	v_mfma_f32_16x16x32_bf16 v[76:79], v[130:133], v[222:225], v[76:79]
	v_mfma_f32_16x16x32_bf16 v[68:71], v[138:141], v[222:225], v[68:71]
	v_mfma_f32_16x16x32_bf16 v[124:127], v[134:137], v[202:205], v[124:127]
	v_mfma_f32_16x16x32_bf16 v[120:123], v[142:145], v[202:205], v[120:123]
	v_mfma_f32_16x16x32_bf16 v[108:111], v[134:137], v[210:213], v[108:111]
	v_mfma_f32_16x16x32_bf16 v[100:103], v[142:145], v[210:213], v[100:103]
	v_mfma_f32_16x16x32_bf16 v[92:95], v[134:137], v[218:221], v[92:95]
	v_mfma_f32_16x16x32_bf16 v[84:87], v[142:145], v[218:221], v[84:87]
	v_mfma_f32_16x16x32_bf16 v[76:79], v[134:137], v[226:229], v[76:79]
	v_mfma_f32_16x16x32_bf16 v[68:71], v[142:145], v[226:229], v[68:71]
	s_setprio 0
	s_setprio 1
	v_mfma_f32_16x16x32_bf16 v[116:119], v[146:149], v[198:201], v[116:119]
	v_mfma_f32_16x16x32_bf16 v[112:115], v[190:193], v[198:201], v[112:115]
	v_mfma_f32_16x16x32_bf16 v[104:107], v[146:149], v[206:209], v[104:107]
	v_mfma_f32_16x16x32_bf16 v[96:99], v[190:193], v[206:209], v[96:99]
	v_mfma_f32_16x16x32_bf16 v[88:91], v[146:149], v[214:217], v[88:91]
	v_mfma_f32_16x16x32_bf16 v[80:83], v[190:193], v[214:217], v[80:83]
	v_mfma_f32_16x16x32_bf16 v[72:75], v[146:149], v[222:225], v[72:75]
	v_mfma_f32_16x16x32_bf16 v[64:67], v[190:193], v[222:225], v[64:67]
	v_mfma_f32_16x16x32_bf16 v[116:119], v[186:189], v[202:205], v[116:119]
	v_mfma_f32_16x16x32_bf16 v[112:115], v[194:197], v[202:205], v[112:115]
	v_mfma_f32_16x16x32_bf16 v[104:107], v[186:189], v[210:213], v[104:107]
	v_mfma_f32_16x16x32_bf16 v[96:99], v[194:197], v[210:213], v[96:99]
	s_barrier
	s_setprio 2
	v_mfma_f32_16x16x32_bf16 v[88:91], v[186:189], v[218:221], v[88:91]
	v_mfma_f32_16x16x32_bf16 v[80:83], v[194:197], v[218:221], v[80:83]
	v_mfma_f32_16x16x32_bf16 v[72:75], v[186:189], v[226:229], v[72:75]
	v_mfma_f32_16x16x32_bf16 v[64:67], v[194:197], v[226:229], v[64:67]
	s_setprio 0
	s_add_i32 s34, s73, s67
	s_mov_b32 m0, s34
	ds_read_b128 v[198:201], v181 offset:49152
	ds_read_b128 v[202:205], v181 offset:50176
	ds_read_b128 v[206:209], v181 offset:51200
	ds_read_b128 v[210:213], v181 offset:52224
	ds_read_b128 v[214:217], v181 offset:53248
	ds_read_b128 v[218:221], v181 offset:54272
	ds_read_b128 v[222:225], v181 offset:55296
	ds_read_b128 v[226:229], v181 offset:56320
	global_load_lds_dwordx4 v154, s[76:77]
	s_add_i32 m0, s34, 0x2000
	s_add_u32 s30, s30, 0x80080
	s_addc_u32 s31, s31, 0
	s_add_i32 s34, s74, s67
	global_load_lds_dwordx4 v158, s[76:77]
	s_mov_b32 m0, s34
	s_nop 0
	global_load_lds_dwordx4 v154, s[30:31]
	s_add_i32 m0, s34, 0x2000
	s_nop 0
	global_load_lds_dwordx4 v158, s[30:31]
	s_mov_b32 m0, s49
	s_nop 0
	global_load_lds_dwordx4 v152, s[78:79]
	s_mov_b32 m0, s50
	s_nop 0
	global_load_lds_dwordx4 v156, s[78:79]
	s_waitcnt vmcnt(8)
	s_waitcnt lgkmcnt(0)
	s_barrier
	s_setprio 1
	s_waitcnt lgkmcnt(0)
	v_mfma_f32_16x16x32_bf16 v[60:63], v[130:133], v[198:201], v[60:63]
	v_mfma_f32_16x16x32_bf16 v[52:55], v[138:141], v[198:201], v[52:55]
	v_mfma_f32_16x16x32_bf16 v[44:47], v[130:133], v[206:209], v[44:47]
	v_mfma_f32_16x16x32_bf16 v[36:39], v[138:141], v[206:209], v[36:39]
	v_mfma_f32_16x16x32_bf16 v[28:31], v[130:133], v[214:217], v[28:31]
	v_mfma_f32_16x16x32_bf16 v[20:23], v[138:141], v[214:217], v[20:23]
	v_mfma_f32_16x16x32_bf16 v[12:15], v[130:133], v[222:225], v[12:15]
	v_mfma_f32_16x16x32_bf16 v[4:7], v[138:141], v[222:225], v[4:7]
	v_mfma_f32_16x16x32_bf16 v[60:63], v[134:137], v[202:205], v[60:63]
	v_mfma_f32_16x16x32_bf16 v[52:55], v[142:145], v[202:205], v[52:55]
	v_mfma_f32_16x16x32_bf16 v[44:47], v[134:137], v[210:213], v[44:47]
	v_mfma_f32_16x16x32_bf16 v[36:39], v[142:145], v[210:213], v[36:39]
	v_mfma_f32_16x16x32_bf16 v[28:31], v[134:137], v[218:221], v[28:31]
	v_mfma_f32_16x16x32_bf16 v[20:23], v[142:145], v[218:221], v[20:23]
	v_mfma_f32_16x16x32_bf16 v[12:15], v[134:137], v[226:229], v[12:15]
	v_mfma_f32_16x16x32_bf16 v[4:7], v[142:145], v[226:229], v[4:7]
	s_setprio 0
	s_setprio 1
	v_mfma_f32_16x16x32_bf16 v[56:59], v[146:149], v[198:201], v[56:59]
	v_mfma_f32_16x16x32_bf16 v[48:51], v[190:193], v[198:201], v[48:51]
	v_mfma_f32_16x16x32_bf16 v[40:43], v[146:149], v[206:209], v[40:43]
	v_mfma_f32_16x16x32_bf16 v[32:35], v[190:193], v[206:209], v[32:35]
	v_mfma_f32_16x16x32_bf16 v[24:27], v[146:149], v[214:217], v[24:27]
	v_mfma_f32_16x16x32_bf16 v[16:19], v[190:193], v[214:217], v[16:19]
	v_mfma_f32_16x16x32_bf16 v[8:11], v[146:149], v[222:225], v[8:11]
	v_mfma_f32_16x16x32_bf16 v[0:3], v[190:193], v[222:225], v[0:3]
	v_mfma_f32_16x16x32_bf16 v[56:59], v[186:189], v[202:205], v[56:59]
	v_mfma_f32_16x16x32_bf16 v[48:51], v[194:197], v[202:205], v[48:51]
	v_mfma_f32_16x16x32_bf16 v[40:43], v[186:189], v[210:213], v[40:43]
	v_mfma_f32_16x16x32_bf16 v[32:35], v[194:197], v[210:213], v[32:35]
	s_barrier
	s_setprio 2
	v_mfma_f32_16x16x32_bf16 v[24:27], v[186:189], v[218:221], v[24:27]
	v_mfma_f32_16x16x32_bf16 v[16:19], v[194:197], v[218:221], v[16:19]
	v_mfma_f32_16x16x32_bf16 v[8:11], v[186:189], v[226:229], v[8:11]
	v_mfma_f32_16x16x32_bf16 v[0:3], v[194:197], v[226:229], v[0:3]
	s_setprio 0
	s_add_i32 s72, s72, 2
	s_add_u32 s70, s70, 0x100
	s_addc_u32 s71, s71, 0
	s_add_u32 s28, s28, 0x100
	s_addc_u32 s29, s29, 0
	s_cmp_gt_u32 s72, 29
	s_cbranch_scc0 .LBB0_3122
	s_and_b64 vcc, exec, s[14:15]
	s_cbranch_vccz .LBB0_3125
	s_barrier

.LBB0_3281:
	ds_read_b128 v[128:131], v231
	ds_read_b128 v[132:135], v231 offset:1024
	ds_read_b128 v[136:139], v231 offset:2048
	ds_read_b128 v[140:143], v231 offset:3072
	ds_read_b128 v[144:147], v232
	ds_read_b128 v[148:151], v232 offset:1024
	ds_read_b128 v[152:155], v232 offset:2048
	ds_read_b128 v[174:177], v232 offset:3072
	s_add_u32 s24, s22, 0xfff80080
	s_addc_u32 s25, s23, -1
	s_cmp_eq_u32 s30, 28
	s_cselect_b32 s27, s3, s25
	s_cselect_b32 s26, s15, s24
	s_cselect_b32 s25, s13, s29
	s_cselect_b32 s24, s21, s28
	s_add_i32 m0, s40, 0xc000
	ds_read_b128 v[178:181], v233
	ds_read_b128 v[182:185], v233 offset:1024
	ds_read_b128 v[186:189], v233 offset:2048
	ds_read_b128 v[190:193], v233 offset:3072
	ds_read_b128 v[194:197], v233 offset:4096
	ds_read_b128 v[198:201], v233 offset:5120
	ds_read_b128 v[202:205], v233 offset:6144
	ds_read_b128 v[206:209], v233 offset:7168
	global_load_lds_dwordx4 v168, s[22:23]
	s_add_i32 m0, s40, 0xe000
	s_nop 0
	global_load_lds_dwordx4 v166, s[22:23]
	s_waitcnt vmcnt(8)
	s_waitcnt lgkmcnt(0)
	s_barrier
	s_setprio 1
	s_waitcnt lgkmcnt(0)
	v_mfma_f32_16x16x32_bf16 v[124:127], v[128:131], v[178:181], v[124:127]
	v_mfma_f32_16x16x32_bf16 v[120:123], v[136:139], v[178:181], v[120:123]
	v_mfma_f32_16x16x32_bf16 v[116:119], v[128:131], v[186:189], v[116:119]
	v_mfma_f32_16x16x32_bf16 v[112:115], v[136:139], v[186:189], v[112:115]
	v_mfma_f32_16x16x32_bf16 v[108:111], v[128:131], v[194:197], v[108:111]
	v_mfma_f32_16x16x32_bf16 v[104:107], v[136:139], v[194:197], v[104:107]
	v_mfma_f32_16x16x32_bf16 v[100:103], v[128:131], v[202:205], v[100:103]
	v_mfma_f32_16x16x32_bf16 v[96:99], v[136:139], v[202:205], v[96:99]
	v_mfma_f32_16x16x32_bf16 v[124:127], v[132:135], v[182:185], v[124:127]
	v_mfma_f32_16x16x32_bf16 v[120:123], v[140:143], v[182:185], v[120:123]
	v_mfma_f32_16x16x32_bf16 v[116:119], v[132:135], v[190:193], v[116:119]
	v_mfma_f32_16x16x32_bf16 v[112:115], v[140:143], v[190:193], v[112:115]
	v_mfma_f32_16x16x32_bf16 v[108:111], v[132:135], v[198:201], v[108:111]
	v_mfma_f32_16x16x32_bf16 v[104:107], v[140:143], v[198:201], v[104:107]
	v_mfma_f32_16x16x32_bf16 v[100:103], v[132:135], v[206:209], v[100:103]
	v_mfma_f32_16x16x32_bf16 v[96:99], v[140:143], v[206:209], v[96:99]
	s_setprio 0
	s_setprio 1
	v_mfma_f32_16x16x32_bf16 v[60:63], v[144:147], v[178:181], v[60:63]
	v_mfma_f32_16x16x32_bf16 v[56:59], v[152:155], v[178:181], v[56:59]
	v_mfma_f32_16x16x32_bf16 v[52:55], v[144:147], v[186:189], v[52:55]
	v_mfma_f32_16x16x32_bf16 v[48:51], v[152:155], v[186:189], v[48:51]
	v_mfma_f32_16x16x32_bf16 v[44:47], v[144:147], v[194:197], v[44:47]
	v_mfma_f32_16x16x32_bf16 v[40:43], v[152:155], v[194:197], v[40:43]
	v_mfma_f32_16x16x32_bf16 v[36:39], v[144:147], v[202:205], v[36:39]
	v_mfma_f32_16x16x32_bf16 v[32:35], v[152:155], v[202:205], v[32:35]
	v_mfma_f32_16x16x32_bf16 v[60:63], v[148:151], v[182:185], v[60:63]
	v_mfma_f32_16x16x32_bf16 v[56:59], v[174:177], v[182:185], v[56:59]
	v_mfma_f32_16x16x32_bf16 v[52:55], v[148:151], v[190:193], v[52:55]
	v_mfma_f32_16x16x32_bf16 v[48:51], v[174:177], v[190:193], v[48:51]
	s_barrier
	s_setprio 2
	v_mfma_f32_16x16x32_bf16 v[44:47], v[148:151], v[198:201], v[44:47]
	v_mfma_f32_16x16x32_bf16 v[40:43], v[174:177], v[198:201], v[40:43]
	v_mfma_f32_16x16x32_bf16 v[36:39], v[148:151], v[206:209], v[36:39]
	v_mfma_f32_16x16x32_bf16 v[32:35], v[174:177], v[206:209], v[32:35]
	s_setprio 0
	s_add_i32 s31, s64, s67
	s_add_u32 s78, s24, s6
	s_addc_u32 s79, s25, s7
	s_mov_b32 m0, s31
	ds_read_b128 v[178:181], v233 offset:16384
	ds_read_b128 v[182:185], v233 offset:17408
	ds_read_b128 v[186:189], v233 offset:18432
	ds_read_b128 v[190:193], v233 offset:19456
	ds_read_b128 v[194:197], v233 offset:20480
	ds_read_b128 v[198:201], v233 offset:21504
	ds_read_b128 v[202:205], v233 offset:22528
	ds_read_b128 v[206:209], v233 offset:23552
	global_load_lds_dwordx4 v158, s[24:25]
	s_add_i32 m0, s31, 0x2000
	s_add_u32 s34, s24, 0x80000
	s_addc_u32 s35, s25, 0
	s_add_i32 s31, s65, s67
	global_load_lds_dwordx4 v162, s[24:25]
	s_mov_b32 m0, s31
	s_add_u32 s80, s26, s6
	s_addc_u32 s81, s27, s7
	global_load_lds_dwordx4 v158, s[34:35]
	s_add_i32 m0, s31, 0x2000
	s_nop 0
	global_load_lds_dwordx4 v162, s[34:35]
	s_mov_b32 m0, s40
	s_nop 0
	global_load_lds_dwordx4 v156, s[26:27]
	s_mov_b32 m0, s41
	s_nop 0
	global_load_lds_dwordx4 v160, s[26:27]
	s_waitcnt vmcnt(8)
	s_waitcnt lgkmcnt(0)
	s_barrier
	s_setprio 1
	s_waitcnt lgkmcnt(0)
	v_mfma_f32_16x16x32_bf16 v[92:95], v[128:131], v[178:181], v[92:95]
	v_mfma_f32_16x16x32_bf16 v[88:91], v[136:139], v[178:181], v[88:91]
	v_mfma_f32_16x16x32_bf16 v[84:87], v[128:131], v[186:189], v[84:87]
	v_mfma_f32_16x16x32_bf16 v[80:83], v[136:139], v[186:189], v[80:83]
	v_mfma_f32_16x16x32_bf16 v[76:79], v[128:131], v[194:197], v[76:79]
	v_mfma_f32_16x16x32_bf16 v[72:75], v[136:139], v[194:197], v[72:75]
	v_mfma_f32_16x16x32_bf16 v[68:71], v[128:131], v[202:205], v[68:71]
	v_mfma_f32_16x16x32_bf16 v[64:67], v[136:139], v[202:205], v[64:67]
	v_mfma_f32_16x16x32_bf16 v[92:95], v[132:135], v[182:185], v[92:95]
	v_mfma_f32_16x16x32_bf16 v[88:91], v[140:143], v[182:185], v[88:91]
	v_mfma_f32_16x16x32_bf16 v[84:87], v[132:135], v[190:193], v[84:87]
	v_mfma_f32_16x16x32_bf16 v[80:83], v[140:143], v[190:193], v[80:83]
	v_mfma_f32_16x16x32_bf16 v[76:79], v[132:135], v[198:201], v[76:79]
	v_mfma_f32_16x16x32_bf16 v[72:75], v[140:143], v[198:201], v[72:75]
	v_mfma_f32_16x16x32_bf16 v[68:71], v[132:135], v[206:209], v[68:71]
	v_mfma_f32_16x16x32_bf16 v[64:67], v[140:143], v[206:209], v[64:67]
	s_setprio 0
	s_setprio 1
	v_mfma_f32_16x16x32_bf16 v[28:31], v[144:147], v[178:181], v[28:31]
	v_mfma_f32_16x16x32_bf16 v[24:27], v[152:155], v[178:181], v[24:27]
	v_mfma_f32_16x16x32_bf16 v[20:23], v[144:147], v[186:189], v[20:23]
	v_mfma_f32_16x16x32_bf16 v[16:19], v[152:155], v[186:189], v[16:19]
	v_mfma_f32_16x16x32_bf16 v[12:15], v[144:147], v[194:197], v[12:15]
	v_mfma_f32_16x16x32_bf16 v[8:11], v[152:155], v[194:197], v[8:11]
	v_mfma_f32_16x16x32_bf16 v[4:7], v[144:147], v[202:205], v[4:7]
	v_mfma_f32_16x16x32_bf16 v[0:3], v[152:155], v[202:205], v[0:3]
	v_mfma_f32_16x16x32_bf16 v[28:31], v[148:151], v[182:185], v[28:31]
	v_mfma_f32_16x16x32_bf16 v[24:27], v[174:177], v[182:185], v[24:27]
	v_mfma_f32_16x16x32_bf16 v[20:23], v[148:151], v[190:193], v[20:23]
	v_mfma_f32_16x16x32_bf16 v[16:19], v[174:177], v[190:193], v[16:19]
	s_barrier
	s_setprio 2
	v_mfma_f32_16x16x32_bf16 v[12:15], v[148:151], v[198:201], v[12:15]
	v_mfma_f32_16x16x32_bf16 v[8:11], v[174:177], v[198:201], v[8:11]
	v_mfma_f32_16x16x32_bf16 v[4:7], v[148:151], v[206:209], v[4:7]
	v_mfma_f32_16x16x32_bf16 v[0:3], v[174:177], v[206:209], v[0:3]
	s_setprio 0
	s_add_i32 s31, 0, 0x18000
	s_add_i32 s34, 0, 0x1c000
	v_add_u32_e32 v140, s31, v230
	v_add_u32_e32 v164, s34, v230
	ds_read_b128 v[128:131], v140
	ds_read_b128 v[132:135], v140 offset:1024
	ds_read_b128 v[136:139], v140 offset:2048
	ds_read_b128 v[140:143], v140 offset:3072
	ds_read_b128 v[144:147], v164
	ds_read_b128 v[148:151], v164 offset:1024
	ds_read_b128 v[152:155], v164 offset:2048
	ds_read_b128 v[174:177], v164 offset:3072
	s_add_u32 s26, s26, 0x80000
	s_addc_u32 s27, s27, 0
	s_mov_b32 m0, s42
	ds_read_b128 v[178:181], v233 offset:32768
	ds_read_b128 v[182:185], v233 offset:33792
	ds_read_b128 v[186:189], v233 offset:34816
	ds_read_b128 v[190:193], v233 offset:35840
	ds_read_b128 v[194:197], v233 offset:36864
	ds_read_b128 v[198:201], v233 offset:37888
	ds_read_b128 v[202:205], v233 offset:38912
	ds_read_b128 v[206:209], v233 offset:39936
	global_load_lds_dwordx4 v156, s[26:27]
	s_mov_b32 m0, s43
	s_nop 0
	global_load_lds_dwordx4 v160, s[26:27]
	s_waitcnt vmcnt(8)
	s_waitcnt lgkmcnt(0)
	s_barrier
	s_setprio 1
	s_waitcnt lgkmcnt(0)
	v_mfma_f32_16x16x32_bf16 v[124:127], v[128:131], v[178:181], v[124:127]
	v_mfma_f32_16x16x32_bf16 v[120:123], v[136:139], v[178:181], v[120:123]
	v_mfma_f32_16x16x32_bf16 v[116:119], v[128:131], v[186:189], v[116:119]
	v_mfma_f32_16x16x32_bf16 v[112:115], v[136:139], v[186:189], v[112:115]
	v_mfma_f32_16x16x32_bf16 v[108:111], v[128:131], v[194:197], v[108:111]
	v_mfma_f32_16x16x32_bf16 v[104:107], v[136:139], v[194:197], v[104:107]
	v_mfma_f32_16x16x32_bf16 v[100:103], v[128:131], v[202:205], v[100:103]
	v_mfma_f32_16x16x32_bf16 v[96:99], v[136:139], v[202:205], v[96:99]
	v_mfma_f32_16x16x32_bf16 v[124:127], v[132:135], v[182:185], v[124:127]
	v_mfma_f32_16x16x32_bf16 v[120:123], v[140:143], v[182:185], v[120:123]
	v_mfma_f32_16x16x32_bf16 v[116:119], v[132:135], v[190:193], v[116:119]
	v_mfma_f32_16x16x32_bf16 v[112:115], v[140:143], v[190:193], v[112:115]
	v_mfma_f32_16x16x32_bf16 v[108:111], v[132:135], v[198:201], v[108:111]
	v_mfma_f32_16x16x32_bf16 v[104:107], v[140:143], v[198:201], v[104:107]
	v_mfma_f32_16x16x32_bf16 v[100:103], v[132:135], v[206:209], v[100:103]
	v_mfma_f32_16x16x32_bf16 v[96:99], v[140:143], v[206:209], v[96:99]
	s_setprio 0
	s_setprio 1
	v_mfma_f32_16x16x32_bf16 v[60:63], v[144:147], v[178:181], v[60:63]
	v_mfma_f32_16x16x32_bf16 v[56:59], v[152:155], v[178:181], v[56:59]
	v_mfma_f32_16x16x32_bf16 v[52:55], v[144:147], v[186:189], v[52:55]
	v_mfma_f32_16x16x32_bf16 v[48:51], v[152:155], v[186:189], v[48:51]
	v_mfma_f32_16x16x32_bf16 v[44:47], v[144:147], v[194:197], v[44:47]
	v_mfma_f32_16x16x32_bf16 v[40:43], v[152:155], v[194:197], v[40:43]
	v_mfma_f32_16x16x32_bf16 v[36:39], v[144:147], v[202:205], v[36:39]
	v_mfma_f32_16x16x32_bf16 v[32:35], v[152:155], v[202:205], v[32:35]
	v_mfma_f32_16x16x32_bf16 v[60:63], v[148:151], v[182:185], v[60:63]
	v_mfma_f32_16x16x32_bf16 v[56:59], v[174:177], v[182:185], v[56:59]
	v_mfma_f32_16x16x32_bf16 v[52:55], v[148:151], v[190:193], v[52:55]
	v_mfma_f32_16x16x32_bf16 v[48:51], v[174:177], v[190:193], v[48:51]
	s_barrier
	s_setprio 2
	v_mfma_f32_16x16x32_bf16 v[44:47], v[148:151], v[198:201], v[44:47]
	v_mfma_f32_16x16x32_bf16 v[40:43], v[174:177], v[198:201], v[40:43]
	v_mfma_f32_16x16x32_bf16 v[36:39], v[148:151], v[206:209], v[36:39]
	v_mfma_f32_16x16x32_bf16 v[32:35], v[174:177], v[206:209], v[32:35]
	s_setprio 0
	s_add_i32 s26, s31, s67
	s_mov_b32 m0, s26
	ds_read_b128 v[178:181], v233 offset:49152
	ds_read_b128 v[182:185], v233 offset:50176
	ds_read_b128 v[186:189], v233 offset:51200
	ds_read_b128 v[190:193], v233 offset:52224
	ds_read_b128 v[194:197], v233 offset:53248
	ds_read_b128 v[198:201], v233 offset:54272
	ds_read_b128 v[202:205], v233 offset:55296
	ds_read_b128 v[206:209], v233 offset:56320
	global_load_lds_dwordx4 v158, s[78:79]
	s_add_i32 m0, s26, 0x2000
	s_add_u32 s24, s24, 0x80080
	s_addc_u32 s25, s25, 0
	s_add_i32 s26, s34, s67
	global_load_lds_dwordx4 v162, s[78:79]
	s_mov_b32 m0, s26
	s_nop 0
	global_load_lds_dwordx4 v158, s[24:25]
	s_add_i32 m0, s26, 0x2000
	s_nop 0
	global_load_lds_dwordx4 v162, s[24:25]
	s_mov_b32 m0, s57
	s_nop 0
	global_load_lds_dwordx4 v156, s[80:81]
	s_mov_b32 m0, s58
	s_nop 0
	global_load_lds_dwordx4 v160, s[80:81]
	s_waitcnt vmcnt(8)
	s_waitcnt lgkmcnt(0)
	s_barrier
	s_setprio 1
	s_waitcnt lgkmcnt(0)
	v_mfma_f32_16x16x32_bf16 v[92:95], v[128:131], v[178:181], v[92:95]
	v_mfma_f32_16x16x32_bf16 v[88:91], v[136:139], v[178:181], v[88:91]
	v_mfma_f32_16x16x32_bf16 v[84:87], v[128:131], v[186:189], v[84:87]
	v_mfma_f32_16x16x32_bf16 v[80:83], v[136:139], v[186:189], v[80:83]
	v_mfma_f32_16x16x32_bf16 v[76:79], v[128:131], v[194:197], v[76:79]
	v_mfma_f32_16x16x32_bf16 v[72:75], v[136:139], v[194:197], v[72:75]
	v_mfma_f32_16x16x32_bf16 v[68:71], v[128:131], v[202:205], v[68:71]
	v_mfma_f32_16x16x32_bf16 v[64:67], v[136:139], v[202:205], v[64:67]
	v_mfma_f32_16x16x32_bf16 v[92:95], v[132:135], v[182:185], v[92:95]
	v_mfma_f32_16x16x32_bf16 v[88:91], v[140:143], v[182:185], v[88:91]
	v_mfma_f32_16x16x32_bf16 v[84:87], v[132:135], v[190:193], v[84:87]
	v_mfma_f32_16x16x32_bf16 v[80:83], v[140:143], v[190:193], v[80:83]
	v_mfma_f32_16x16x32_bf16 v[76:79], v[132:135], v[198:201], v[76:79]
	v_mfma_f32_16x16x32_bf16 v[72:75], v[140:143], v[198:201], v[72:75]
	v_mfma_f32_16x16x32_bf16 v[68:71], v[132:135], v[206:209], v[68:71]
	v_mfma_f32_16x16x32_bf16 v[64:67], v[140:143], v[206:209], v[64:67]
	s_setprio 0
	s_setprio 1
	v_mfma_f32_16x16x32_bf16 v[28:31], v[144:147], v[178:181], v[28:31]
	v_mfma_f32_16x16x32_bf16 v[24:27], v[152:155], v[178:181], v[24:27]
	v_mfma_f32_16x16x32_bf16 v[20:23], v[144:147], v[186:189], v[20:23]
	v_mfma_f32_16x16x32_bf16 v[16:19], v[152:155], v[186:189], v[16:19]
	v_mfma_f32_16x16x32_bf16 v[12:15], v[144:147], v[194:197], v[12:15]
	v_mfma_f32_16x16x32_bf16 v[8:11], v[152:155], v[194:197], v[8:11]
	v_mfma_f32_16x16x32_bf16 v[4:7], v[144:147], v[202:205], v[4:7]
	v_mfma_f32_16x16x32_bf16 v[0:3], v[152:155], v[202:205], v[0:3]
	v_mfma_f32_16x16x32_bf16 v[28:31], v[148:151], v[182:185], v[28:31]
	v_mfma_f32_16x16x32_bf16 v[24:27], v[174:177], v[182:185], v[24:27]
	v_mfma_f32_16x16x32_bf16 v[20:23], v[148:151], v[190:193], v[20:23]
	v_mfma_f32_16x16x32_bf16 v[16:19], v[174:177], v[190:193], v[16:19]
	s_barrier
	s_setprio 2
	v_mfma_f32_16x16x32_bf16 v[12:15], v[148:151], v[198:201], v[12:15]
	v_mfma_f32_16x16x32_bf16 v[8:11], v[174:177], v[198:201], v[8:11]
	v_mfma_f32_16x16x32_bf16 v[4:7], v[148:151], v[206:209], v[4:7]
	v_mfma_f32_16x16x32_bf16 v[0:3], v[174:177], v[206:209], v[0:3]
	s_setprio 0
	s_add_i32 s30, s30, 2
	s_add_u32 s28, s28, 0x100
	s_addc_u32 s29, s29, 0
	s_add_u32 s22, s22, 0x100
	s_addc_u32 s23, s23, 0
	s_cmp_gt_u32 s30, 29
	s_cbranch_scc0 .LBB0_3281
	s_and_b64 vcc, exec, s[8:9]
	s_cbranch_vccz .LBB0_3284
	s_barrier

.LBB0_3501:
	ds_read_b128 v[128:131], v201
	ds_read_b128 v[132:135], v201 offset:1024
	ds_read_b128 v[136:139], v201 offset:2048
	ds_read_b128 v[140:143], v201 offset:3072
	ds_read_b128 v[144:147], v202
	ds_read_b128 v[148:151], v202 offset:1024
	ds_read_b128 v[170:173], v202 offset:2048
	ds_read_b128 v[174:177], v202 offset:3072
	s_add_u32 s18, s16, 0x100
	s_addc_u32 s19, s17, 0
	s_cmpk_eq_i32 s68, 0x54
	s_cselect_b32 s23, s3, s19
	s_cselect_b32 s22, s2, s18
	s_cselect_b32 s21, s15, s25
	s_cselect_b32 s20, s14, s24
	v_lshl_add_u64 v[198:199], s[16:17], 0, v[164:165]
	s_add_i32 m0, s30, 0xc000
	ds_read_b128 v[178:181], v203
	ds_read_b128 v[182:185], v203 offset:1024
	ds_read_b128 v[186:189], v203 offset:2048
	ds_read_b128 v[190:193], v203 offset:3072
	ds_read_b128 v[194:197], v203 offset:4096
	ds_read_b128 v[206:209], v203 offset:5120
	ds_read_b128 v[210:213], v203 offset:6144
	ds_read_b128 v[214:217], v203 offset:7168
	global_load_lds_dwordx4 v[198:199], off
	v_lshl_add_u64 v[198:199], s[16:17], 0, v[162:163]
	s_add_i32 m0, s30, 0xe000
	s_nop 0
	global_load_lds_dwordx4 v[198:199], off
	s_waitcnt vmcnt(8)
	s_waitcnt lgkmcnt(0)
	s_barrier
	s_setprio 1
	s_waitcnt lgkmcnt(0)
	v_mfma_f32_16x16x32_bf16 v[124:127], v[128:131], v[178:181], v[124:127]
	v_mfma_f32_16x16x32_bf16 v[120:123], v[136:139], v[178:181], v[120:123]
	v_mfma_f32_16x16x32_bf16 v[116:119], v[128:131], v[186:189], v[116:119]
	v_mfma_f32_16x16x32_bf16 v[112:115], v[136:139], v[186:189], v[112:115]
	v_mfma_f32_16x16x32_bf16 v[108:111], v[128:131], v[194:197], v[108:111]
	v_mfma_f32_16x16x32_bf16 v[104:107], v[136:139], v[194:197], v[104:107]
	v_mfma_f32_16x16x32_bf16 v[100:103], v[128:131], v[210:213], v[100:103]
	v_mfma_f32_16x16x32_bf16 v[96:99], v[136:139], v[210:213], v[96:99]
	v_mfma_f32_16x16x32_bf16 v[124:127], v[132:135], v[182:185], v[124:127]
	v_mfma_f32_16x16x32_bf16 v[120:123], v[140:143], v[182:185], v[120:123]
	v_mfma_f32_16x16x32_bf16 v[116:119], v[132:135], v[190:193], v[116:119]
	v_mfma_f32_16x16x32_bf16 v[112:115], v[140:143], v[190:193], v[112:115]
	v_mfma_f32_16x16x32_bf16 v[108:111], v[132:135], v[206:209], v[108:111]
	v_mfma_f32_16x16x32_bf16 v[104:107], v[140:143], v[206:209], v[104:107]
	v_mfma_f32_16x16x32_bf16 v[100:103], v[132:135], v[214:217], v[100:103]
	v_mfma_f32_16x16x32_bf16 v[96:99], v[140:143], v[214:217], v[96:99]
	s_setprio 0
	s_setprio 1
	v_mfma_f32_16x16x32_bf16 v[60:63], v[144:147], v[178:181], v[60:63]
	v_mfma_f32_16x16x32_bf16 v[56:59], v[170:173], v[178:181], v[56:59]
	v_mfma_f32_16x16x32_bf16 v[52:55], v[144:147], v[186:189], v[52:55]
	v_mfma_f32_16x16x32_bf16 v[48:51], v[170:173], v[186:189], v[48:51]
	v_mfma_f32_16x16x32_bf16 v[44:47], v[144:147], v[194:197], v[44:47]
	v_mfma_f32_16x16x32_bf16 v[40:43], v[170:173], v[194:197], v[40:43]
	v_mfma_f32_16x16x32_bf16 v[36:39], v[144:147], v[210:213], v[36:39]
	v_mfma_f32_16x16x32_bf16 v[32:35], v[170:173], v[210:213], v[32:35]
	v_mfma_f32_16x16x32_bf16 v[60:63], v[148:151], v[182:185], v[60:63]
	v_mfma_f32_16x16x32_bf16 v[56:59], v[174:177], v[182:185], v[56:59]
	v_mfma_f32_16x16x32_bf16 v[52:55], v[148:151], v[190:193], v[52:55]
	v_mfma_f32_16x16x32_bf16 v[48:51], v[174:177], v[190:193], v[48:51]
	s_barrier
	s_setprio 2
	v_mfma_f32_16x16x32_bf16 v[44:47], v[148:151], v[206:209], v[44:47]
	v_mfma_f32_16x16x32_bf16 v[40:43], v[174:177], v[206:209], v[40:43]
	v_mfma_f32_16x16x32_bf16 v[36:39], v[148:151], v[214:217], v[36:39]
	v_mfma_f32_16x16x32_bf16 v[32:35], v[174:177], v[214:217], v[32:35]
	s_setprio 0
	s_add_i32 s16, s52, s67
	s_add_u32 s72, s20, s8
	s_addc_u32 s73, s21, s9
	s_mov_b32 m0, s16
	ds_read_b128 v[178:181], v203 offset:16384
	ds_read_b128 v[182:185], v203 offset:17408
	ds_read_b128 v[186:189], v203 offset:18432
	ds_read_b128 v[190:193], v203 offset:19456
	ds_read_b128 v[194:197], v203 offset:20480
	ds_read_b128 v[206:209], v203 offset:21504
	ds_read_b128 v[210:213], v203 offset:22528
	ds_read_b128 v[214:217], v203 offset:23552
	global_load_lds_dwordx4 v154, s[20:21]
	s_add_i32 m0, s16, 0x2000
	s_add_u32 s16, s20, 0x160000
	s_addc_u32 s17, s21, 0
	s_add_i32 s69, s53, s67
	global_load_lds_dwordx4 v158, s[20:21]
	s_mov_b32 m0, s69
	s_add_u32 s74, s22, s8
	s_addc_u32 s75, s23, s9
	global_load_lds_dwordx4 v154, s[16:17]
	s_add_i32 m0, s69, 0x2000
	s_nop 0
	global_load_lds_dwordx4 v158, s[16:17]
	s_mov_b32 m0, s30
	s_nop 0
	global_load_lds_dwordx4 v152, s[22:23]
	s_mov_b32 m0, s31
	s_nop 0
	global_load_lds_dwordx4 v156, s[22:23]
	s_waitcnt vmcnt(8)
	s_waitcnt lgkmcnt(0)
	s_barrier
	s_setprio 1
	s_waitcnt lgkmcnt(0)
	v_mfma_f32_16x16x32_bf16 v[92:95], v[128:131], v[178:181], v[92:95]
	v_mfma_f32_16x16x32_bf16 v[88:91], v[136:139], v[178:181], v[88:91]
	v_mfma_f32_16x16x32_bf16 v[84:87], v[128:131], v[186:189], v[84:87]
	v_mfma_f32_16x16x32_bf16 v[80:83], v[136:139], v[186:189], v[80:83]
	v_mfma_f32_16x16x32_bf16 v[76:79], v[128:131], v[194:197], v[76:79]
	v_mfma_f32_16x16x32_bf16 v[72:75], v[136:139], v[194:197], v[72:75]
	v_mfma_f32_16x16x32_bf16 v[68:71], v[128:131], v[210:213], v[68:71]
	v_mfma_f32_16x16x32_bf16 v[64:67], v[136:139], v[210:213], v[64:67]
	v_mfma_f32_16x16x32_bf16 v[92:95], v[132:135], v[182:185], v[92:95]
	v_mfma_f32_16x16x32_bf16 v[88:91], v[140:143], v[182:185], v[88:91]
	v_mfma_f32_16x16x32_bf16 v[84:87], v[132:135], v[190:193], v[84:87]
	v_mfma_f32_16x16x32_bf16 v[80:83], v[140:143], v[190:193], v[80:83]
	v_mfma_f32_16x16x32_bf16 v[76:79], v[132:135], v[206:209], v[76:79]
	v_mfma_f32_16x16x32_bf16 v[72:75], v[140:143], v[206:209], v[72:75]
	v_mfma_f32_16x16x32_bf16 v[68:71], v[132:135], v[214:217], v[68:71]
	v_mfma_f32_16x16x32_bf16 v[64:67], v[140:143], v[214:217], v[64:67]
	s_setprio 0
	s_setprio 1
	v_mfma_f32_16x16x32_bf16 v[28:31], v[144:147], v[178:181], v[28:31]
	v_mfma_f32_16x16x32_bf16 v[24:27], v[170:173], v[178:181], v[24:27]
	v_mfma_f32_16x16x32_bf16 v[20:23], v[144:147], v[186:189], v[20:23]
	v_mfma_f32_16x16x32_bf16 v[16:19], v[170:173], v[186:189], v[16:19]
	v_mfma_f32_16x16x32_bf16 v[12:15], v[144:147], v[194:197], v[12:15]
	v_mfma_f32_16x16x32_bf16 v[8:11], v[170:173], v[194:197], v[8:11]
	v_mfma_f32_16x16x32_bf16 v[4:7], v[144:147], v[210:213], v[4:7]
	v_mfma_f32_16x16x32_bf16 v[0:3], v[170:173], v[210:213], v[0:3]
	v_mfma_f32_16x16x32_bf16 v[28:31], v[148:151], v[182:185], v[28:31]
	v_mfma_f32_16x16x32_bf16 v[24:27], v[174:177], v[182:185], v[24:27]
	v_mfma_f32_16x16x32_bf16 v[20:23], v[148:151], v[190:193], v[20:23]
	v_mfma_f32_16x16x32_bf16 v[16:19], v[174:177], v[190:193], v[16:19]
	s_barrier
	s_setprio 2
	v_mfma_f32_16x16x32_bf16 v[12:15], v[148:151], v[206:209], v[12:15]
	v_mfma_f32_16x16x32_bf16 v[8:11], v[174:177], v[206:209], v[8:11]
	v_mfma_f32_16x16x32_bf16 v[4:7], v[148:151], v[214:217], v[4:7]
	v_mfma_f32_16x16x32_bf16 v[0:3], v[174:177], v[214:217], v[0:3]
	s_setprio 0
	s_add_i32 s69, 0, 0x18000
	s_add_i32 s70, 0, 0x1c000
	v_add_u32_e32 v140, s69, v200
	v_add_u32_e32 v160, s70, v200
	ds_read_b128 v[128:131], v140
	ds_read_b128 v[132:135], v140 offset:1024
	ds_read_b128 v[136:139], v140 offset:2048
	ds_read_b128 v[140:143], v140 offset:3072
	ds_read_b128 v[144:147], v160
	ds_read_b128 v[148:151], v160 offset:1024
	ds_read_b128 v[170:173], v160 offset:2048
	ds_read_b128 v[174:177], v160 offset:3072
	s_add_u32 s16, s22, 0x160000
	s_addc_u32 s17, s23, 0
	s_mov_b32 m0, s34
	ds_read_b128 v[178:181], v203 offset:32768
	ds_read_b128 v[182:185], v203 offset:33792
	ds_read_b128 v[186:189], v203 offset:34816
	ds_read_b128 v[190:193], v203 offset:35840
	ds_read_b128 v[194:197], v203 offset:36864
	ds_read_b128 v[206:209], v203 offset:37888
	ds_read_b128 v[210:213], v203 offset:38912
	ds_read_b128 v[214:217], v203 offset:39936
	global_load_lds_dwordx4 v152, s[16:17]
	s_mov_b32 m0, s35
	s_nop 0
	global_load_lds_dwordx4 v156, s[16:17]
	s_waitcnt vmcnt(8)
	s_waitcnt lgkmcnt(0)
	s_barrier
	s_setprio 1
	s_waitcnt lgkmcnt(0)
	v_mfma_f32_16x16x32_bf16 v[124:127], v[128:131], v[178:181], v[124:127]
	v_mfma_f32_16x16x32_bf16 v[120:123], v[136:139], v[178:181], v[120:123]
	v_mfma_f32_16x16x32_bf16 v[116:119], v[128:131], v[186:189], v[116:119]
	v_mfma_f32_16x16x32_bf16 v[112:115], v[136:139], v[186:189], v[112:115]
	v_mfma_f32_16x16x32_bf16 v[108:111], v[128:131], v[194:197], v[108:111]
	v_mfma_f32_16x16x32_bf16 v[104:107], v[136:139], v[194:197], v[104:107]
	v_mfma_f32_16x16x32_bf16 v[100:103], v[128:131], v[210:213], v[100:103]
	v_mfma_f32_16x16x32_bf16 v[96:99], v[136:139], v[210:213], v[96:99]
	v_mfma_f32_16x16x32_bf16 v[124:127], v[132:135], v[182:185], v[124:127]
	v_mfma_f32_16x16x32_bf16 v[120:123], v[140:143], v[182:185], v[120:123]
	v_mfma_f32_16x16x32_bf16 v[116:119], v[132:135], v[190:193], v[116:119]
	v_mfma_f32_16x16x32_bf16 v[112:115], v[140:143], v[190:193], v[112:115]
	v_mfma_f32_16x16x32_bf16 v[108:111], v[132:135], v[206:209], v[108:111]
	v_mfma_f32_16x16x32_bf16 v[104:107], v[140:143], v[206:209], v[104:107]
	v_mfma_f32_16x16x32_bf16 v[100:103], v[132:135], v[214:217], v[100:103]
	v_mfma_f32_16x16x32_bf16 v[96:99], v[140:143], v[214:217], v[96:99]
	s_setprio 0
	s_setprio 1
	v_mfma_f32_16x16x32_bf16 v[60:63], v[144:147], v[178:181], v[60:63]
	v_mfma_f32_16x16x32_bf16 v[56:59], v[170:173], v[178:181], v[56:59]
	v_mfma_f32_16x16x32_bf16 v[52:55], v[144:147], v[186:189], v[52:55]
	v_mfma_f32_16x16x32_bf16 v[48:51], v[170:173], v[186:189], v[48:51]
	v_mfma_f32_16x16x32_bf16 v[44:47], v[144:147], v[194:197], v[44:47]
	v_mfma_f32_16x16x32_bf16 v[40:43], v[170:173], v[194:197], v[40:43]
	v_mfma_f32_16x16x32_bf16 v[36:39], v[144:147], v[210:213], v[36:39]
	v_mfma_f32_16x16x32_bf16 v[32:35], v[170:173], v[210:213], v[32:35]
	v_mfma_f32_16x16x32_bf16 v[60:63], v[148:151], v[182:185], v[60:63]
	v_mfma_f32_16x16x32_bf16 v[56:59], v[174:177], v[182:185], v[56:59]
	v_mfma_f32_16x16x32_bf16 v[52:55], v[148:151], v[190:193], v[52:55]
	v_mfma_f32_16x16x32_bf16 v[48:51], v[174:177], v[190:193], v[48:51]
	s_barrier
	s_setprio 2
	v_mfma_f32_16x16x32_bf16 v[44:47], v[148:151], v[206:209], v[44:47]
	v_mfma_f32_16x16x32_bf16 v[40:43], v[174:177], v[206:209], v[40:43]
	v_mfma_f32_16x16x32_bf16 v[36:39], v[148:151], v[214:217], v[36:39]
	v_mfma_f32_16x16x32_bf16 v[32:35], v[174:177], v[214:217], v[32:35]
	s_setprio 0
	s_add_i32 s16, s69, s67
	s_mov_b32 m0, s16
	ds_read_b128 v[178:181], v203 offset:49152
	ds_read_b128 v[182:185], v203 offset:50176
	ds_read_b128 v[186:189], v203 offset:51200
	ds_read_b128 v[190:193], v203 offset:52224
	ds_read_b128 v[194:197], v203 offset:53248
	ds_read_b128 v[206:209], v203 offset:54272
	ds_read_b128 v[210:213], v203 offset:55296
	ds_read_b128 v[214:217], v203 offset:56320
	global_load_lds_dwordx4 v154, s[72:73]
	s_add_i32 m0, s16, 0x2000
	s_add_u32 s16, s20, 0x160080
	s_addc_u32 s17, s21, 0
	s_add_i32 s20, s70, s67
	global_load_lds_dwordx4 v158, s[72:73]
	s_mov_b32 m0, s20
	s_nop 0
	global_load_lds_dwordx4 v154, s[16:17]
	s_add_i32 m0, s20, 0x2000
	s_nop 0
	global_load_lds_dwordx4 v158, s[16:17]
	s_mov_b32 m0, s47
	s_nop 0
	global_load_lds_dwordx4 v152, s[74:75]
	s_mov_b32 m0, s48
	s_nop 0
	global_load_lds_dwordx4 v156, s[74:75]
	s_waitcnt vmcnt(8)
	s_waitcnt lgkmcnt(0)
	s_barrier
	s_setprio 1
	s_waitcnt lgkmcnt(0)
	v_mfma_f32_16x16x32_bf16 v[92:95], v[128:131], v[178:181], v[92:95]
	v_mfma_f32_16x16x32_bf16 v[88:91], v[136:139], v[178:181], v[88:91]
	v_mfma_f32_16x16x32_bf16 v[84:87], v[128:131], v[186:189], v[84:87]
	v_mfma_f32_16x16x32_bf16 v[80:83], v[136:139], v[186:189], v[80:83]
	v_mfma_f32_16x16x32_bf16 v[76:79], v[128:131], v[194:197], v[76:79]
	v_mfma_f32_16x16x32_bf16 v[72:75], v[136:139], v[194:197], v[72:75]
	v_mfma_f32_16x16x32_bf16 v[68:71], v[128:131], v[210:213], v[68:71]
	v_mfma_f32_16x16x32_bf16 v[64:67], v[136:139], v[210:213], v[64:67]
	v_mfma_f32_16x16x32_bf16 v[92:95], v[132:135], v[182:185], v[92:95]
	v_mfma_f32_16x16x32_bf16 v[88:91], v[140:143], v[182:185], v[88:91]
	v_mfma_f32_16x16x32_bf16 v[84:87], v[132:135], v[190:193], v[84:87]
	v_mfma_f32_16x16x32_bf16 v[80:83], v[140:143], v[190:193], v[80:83]
	v_mfma_f32_16x16x32_bf16 v[76:79], v[132:135], v[206:209], v[76:79]
	v_mfma_f32_16x16x32_bf16 v[72:75], v[140:143], v[206:209], v[72:75]
	v_mfma_f32_16x16x32_bf16 v[68:71], v[132:135], v[214:217], v[68:71]
	v_mfma_f32_16x16x32_bf16 v[64:67], v[140:143], v[214:217], v[64:67]
	s_setprio 0
	s_setprio 1
	v_mfma_f32_16x16x32_bf16 v[28:31], v[144:147], v[178:181], v[28:31]
	v_mfma_f32_16x16x32_bf16 v[24:27], v[170:173], v[178:181], v[24:27]
	v_mfma_f32_16x16x32_bf16 v[20:23], v[144:147], v[186:189], v[20:23]
	v_mfma_f32_16x16x32_bf16 v[16:19], v[170:173], v[186:189], v[16:19]
	v_mfma_f32_16x16x32_bf16 v[12:15], v[144:147], v[194:197], v[12:15]
	v_mfma_f32_16x16x32_bf16 v[8:11], v[170:173], v[194:197], v[8:11]
	v_mfma_f32_16x16x32_bf16 v[4:7], v[144:147], v[210:213], v[4:7]
	v_mfma_f32_16x16x32_bf16 v[0:3], v[170:173], v[210:213], v[0:3]
	v_mfma_f32_16x16x32_bf16 v[28:31], v[148:151], v[182:185], v[28:31]
	v_mfma_f32_16x16x32_bf16 v[24:27], v[174:177], v[182:185], v[24:27]
	v_mfma_f32_16x16x32_bf16 v[20:23], v[148:151], v[190:193], v[20:23]
	v_mfma_f32_16x16x32_bf16 v[16:19], v[174:177], v[190:193], v[16:19]
	s_barrier
	s_setprio 2
	v_mfma_f32_16x16x32_bf16 v[12:15], v[148:151], v[206:209], v[12:15]
	v_mfma_f32_16x16x32_bf16 v[8:11], v[174:177], v[206:209], v[8:11]
	v_mfma_f32_16x16x32_bf16 v[4:7], v[148:151], v[214:217], v[4:7]
	v_mfma_f32_16x16x32_bf16 v[0:3], v[174:177], v[214:217], v[0:3]
	s_setprio 0
	s_add_i32 s68, s68, 2
	s_add_u32 s24, s24, 0x100
	s_addc_u32 s25, s25, 0
	s_cmpk_gt_u32 s68, 0x55
	s_mov_b64 s[16:17], s[18:19]
	s_cbranch_scc0 .LBB0_3501
	s_and_b64 vcc, exec, s[10:11]
	s_cbranch_vccz .LBB0_3504
	s_barrier
